# instruction selection: packed f32 VALU ops (v_pk_add_f32 / v_pk_mul_f32) beside MFMAs split into their two single ops in the prompt attention unit and the HGRN output unit (219 sites, bit-identical)
# speedup vs baseline: 1.0023x; 1.0023x over previous
; #define NEG_INF (-__builtin_inff())
; template <bool LUTB, bool WINLO>
; DEV void mask_bias(f32x4 (&s)[4], const AttnCtx& C, int t, int p0, int pstep, bool colok) {
; #pragma unroll
;     for (int kt = 0; kt < 4; ++kt)
; #pragma unroll
;         for (int i = 0; i < 4; ++i) { const int rel = t - (p0 + pstep * (16 * kt + 4 * C.q4 + i));
;             bool ok = colok && rel >= 0; if (WINLO) ok = ok && rel < 512;
;             float v = s[kt][i]; if (LUTB) v += C.lut[C.h * 129 + (rel < 0 ? 0 : (rel < 128 ? rel : 128))];
;             s[kt][i] = ok ? v : NEG_INF; }
; }
; DEV void attn_unit_mfma(Frame& F, int qg, int kv) {
;     ...
;         for (int g = 0; g < 2; ++g) { if (near) mask_bias<true, false>(s[g], C, C.tq[g], 1024 * i + 31, 16, true);
;             ref_step(s[g], m[g], O[g], L[g], pf[g], true); }
.LBB0_929:
	s_andn2_b64 vcc, exec, s[14:15]
	v_add_u32_e32 v18, v105, v112
	s_cbranch_vccnz .LBB0_931
	v_add_u32_e32 v21, -4, v112
	v_add_u32_e32 v113, -4, v18
	v_add_u32_e32 v122, 0xffffffe0, v113
	v_add_u32_e32 v123, v21, v100
	v_subrev_u32_e32 v124, 52, v18
	v_add_u32_e32 v126, 0xfffffeec, v18
	v_add_u32_e32 v127, 0xfffffefc, v18
	v_add_u32_e32 v128, 0xfffffdec, v18
	v_add_u32_e32 v129, 0xfffffdfc, v18
	v_med3_i32 v114, v113, 0, v172
	v_med3_i32 v115, v123, 0, v172
	v_med3_i32 v116, v122, 0, v172
	v_med3_i32 v117, v124, 0, v172
	v_med3_i32 v118, v127, 0, v172
	v_med3_i32 v119, v126, 0, v172
	v_med3_i32 v120, v129, 0, v172
	v_med3_i32 v121, v128, 0, v172
	v_lshl_add_u32 v114, v114, 2, v174
	v_lshl_add_u32 v115, v115, 2, v174
	v_lshl_add_u32 v116, v116, 2, v174
	v_lshl_add_u32 v117, v117, 2, v174
	v_lshl_add_u32 v118, v118, 2, v174
	v_lshl_add_u32 v119, v119, 2, v174
	v_lshl_add_u32 v120, v120, 2, v174
	v_lshl_add_u32 v121, v121, 2, v174
	ds_read_b32 v125, v114
	ds_read_b32 v114, v115
	ds_read_b32 v115, v116
	ds_read_b32 v130, v117
	ds_read_b32 v116, v118
	ds_read_b32 v117, v119
	ds_read_b32 v118, v120
	ds_read_b32 v119, v121
	s_waitcnt lgkmcnt(0)
	v_add_f32_e32 v82, v82, v125
	v_cmp_lt_i32_e32 vcc, -1, v113
	v_mov_b32_e32 v120, v83
	v_mov_b32_e32 v121, v84
	v_cndmask_b32_e32 v82, v173, v82, vcc
	v_add_f32_e32 v114, v120, v114
	v_add_f32_e32 v115, v121, v115
	v_cmp_lt_i32_e32 vcc, -1, v123
	v_sub_u32_e32 v120, v21, v98
	v_sub_u32_e32 v21, v21, v1
	v_cndmask_b32_e32 v83, v173, v114, vcc
	v_cmp_lt_i32_e32 vcc, -1, v122
	v_add_f32_e32 v85, v85, v130
	v_add_u32_e32 v113, 0xfffffcec, v18
	v_add_u32_e32 v130, 0xfffffcfc, v18
	v_add_u32_e32 v131, 0xffffff00, v21
	v_add_u32_e32 v132, 0xffffff00, v120
	v_add_u32_e32 v133, 0xfffffe00, v21
	v_add_u32_e32 v134, 0xfffffe00, v120
	v_add_u32_e32 v135, 0xfffffd00, v120
	v_cndmask_b32_e32 v84, v173, v115, vcc
	v_cmp_lt_i32_e32 vcc, -1, v124
	v_med3_i32 v114, v130, 0, v172
	v_med3_i32 v115, v113, 0, v172
	v_med3_i32 v121, v132, 0, v172
	v_med3_i32 v122, v131, 0, v172
	v_med3_i32 v123, v134, 0, v172
	v_med3_i32 v124, v133, 0, v172
	v_add_u32_e32 v21, 0xfffffd00, v21
	v_med3_i32 v120, v135, 0, v172
	v_cndmask_b32_e32 v85, v173, v85, vcc
	v_lshl_add_u32 v114, v114, 2, v174
	v_lshl_add_u32 v115, v115, 2, v174
	v_lshl_add_u32 v121, v121, 2, v174
	v_lshl_add_u32 v122, v122, 2, v174
	v_lshl_add_u32 v123, v123, 2, v174
	v_lshl_add_u32 v124, v124, 2, v174
	v_lshl_add_u32 v125, v120, 2, v174
	v_med3_i32 v120, v21, 0, v172
	v_add_f32_e32 v86, v86, v116
	v_add_f32_e32 v87, v87, v117
	v_cmp_lt_i32_e32 vcc, -1, v126
	v_lshl_add_u32 v136, v120, 2, v174
	ds_read_b32 v114, v114
	ds_read_b32 v115, v115
	ds_read_b32 v120, v121
	ds_read_b32 v121, v122
	ds_read_b32 v122, v123
	ds_read_b32 v123, v124
	ds_read_b32 v124, v125
	ds_read_b32 v125, v136
	v_cndmask_b32_e32 v87, v173, v87, vcc
	v_cmp_lt_i32_e32 vcc, -1, v127
	s_waitcnt lgkmcnt(0)
	v_add_f32_e32 v88, v88, v120
	v_add_f32_e32 v89, v89, v121
	v_add_f32_e32 v94, v94, v118
	v_add_f32_e32 v95, v95, v119
	v_cndmask_b32_e32 v86, v173, v86, vcc
	v_cmp_lt_i32_e32 vcc, -1, v131
	v_add_f32_e32 v96, v96, v122
	v_add_f32_e32 v97, v97, v123
	v_add_f32_e32 v90, v90, v114
	v_add_f32_e32 v91, v91, v115
	v_cndmask_b32_e32 v89, v173, v89, vcc
	v_cmp_lt_i32_e32 vcc, -1, v132
	v_add_f32_e32 v92, v92, v124
	v_add_f32_e32 v93, v93, v125
	s_nop 0
	v_cndmask_b32_e32 v88, v173, v88, vcc
	v_cmp_lt_i32_e32 vcc, -1, v128
	s_nop 1
	v_cndmask_b32_e32 v95, v173, v95, vcc
	v_cmp_lt_i32_e32 vcc, -1, v129
	s_nop 1
	v_cndmask_b32_e32 v94, v173, v94, vcc
	v_cmp_lt_i32_e32 vcc, -1, v133
	s_nop 1
	v_cndmask_b32_e32 v97, v173, v97, vcc
	v_cmp_lt_i32_e32 vcc, -1, v134
	s_nop 1
	v_cndmask_b32_e32 v96, v173, v96, vcc
	v_cmp_lt_i32_e32 vcc, -1, v113
	s_nop 1
	v_cndmask_b32_e32 v91, v173, v91, vcc
	v_cmp_lt_i32_e32 vcc, -1, v130
	s_nop 1
	v_cndmask_b32_e32 v90, v173, v90, vcc
	v_cmp_lt_i32_e32 vcc, -1, v21
	s_nop 1
	v_cndmask_b32_e32 v93, v173, v93, vcc
	v_cmp_lt_i32_e32 vcc, -1, v135
	s_nop 1
	v_cndmask_b32_e32 v92, v173, v92, vcc

; #define NEG_INF (-__builtin_inff())
; template <bool LUTB, bool WINLO>
; DEV void mask_bias(f32x4 (&s)[4], const AttnCtx& C, int t, int p0, int pstep, bool colok) {
; #pragma unroll
;     for (int kt = 0; kt < 4; ++kt)
; #pragma unroll
;         for (int i = 0; i < 4; ++i) { const int rel = t - (p0 + pstep * (16 * kt + 4 * C.q4 + i));
;             bool ok = colok && rel >= 0; if (WINLO) ok = ok && rel < 512;
;             float v = s[kt][i]; if (LUTB) v += C.lut[C.h * 129 + (rel < 0 ? 0 : (rel < 128 ? rel : 128))];
;             s[kt][i] = ok ? v : NEG_INF; }
; }
; DEV void attn_unit_mfma(Frame& F, int qg, int kv) {
;     ...
;         for (int g = 0; g < 2; ++g) { if (near) mask_bias<true, false>(s[g], C, C.tq[g], 1024 * i + 31, 16, true);
;             ref_step(s[g], m[g], O[g], L[g], pf[g], true); }
.LBB0_935:
	s_andn2_b64 vcc, exec, s[10:11]
	s_cbranch_vccnz .LBB0_937
	v_add_u32_e32 v113, 0xffffffe0, v18
	v_add_u32_e32 v122, v112, v100
	v_subrev_u32_e32 v123, 48, v18
	v_add_u32_e32 v126, 0xfffffef0, v18
	v_add_u32_e32 v127, 0xffffff00, v18
	v_add_u32_e32 v129, 0xfffffe00, v18
	v_med3_i32 v21, v18, 0, v172
	v_med3_i32 v114, v122, 0, v172
	v_med3_i32 v115, v113, 0, v172
	v_med3_i32 v116, v123, 0, v172
	v_med3_i32 v117, v127, 0, v172
	v_med3_i32 v118, v126, 0, v172
	v_add_u32_e32 v128, 0xfffffdf0, v18
	v_med3_i32 v119, v129, 0, v172
	v_lshl_add_u32 v21, v21, 2, v174
	v_lshl_add_u32 v114, v114, 2, v174
	v_lshl_add_u32 v115, v115, 2, v174
	v_lshl_add_u32 v116, v116, 2, v174
	v_lshl_add_u32 v117, v117, 2, v174
	v_lshl_add_u32 v118, v118, 2, v174
	v_lshl_add_u32 v119, v119, 2, v174
	v_med3_i32 v120, v128, 0, v172
	v_lshl_add_u32 v120, v120, 2, v174
	ds_read_b32 v21, v21
	ds_read_b32 v114, v114
	ds_read_b32 v115, v115
	ds_read_b32 v124, v116
	ds_read_b32 v116, v117
	ds_read_b32 v117, v118
	ds_read_b32 v118, v119
	ds_read_b32 v119, v120
	s_waitcnt lgkmcnt(0)
	v_add_f32_e32 v21, v70, v21
	v_cmp_lt_i32_e32 vcc, -1, v18
	v_mov_b32_e32 v120, v71
	v_mov_b32_e32 v121, v72
	v_cndmask_b32_e32 v70, v173, v21, vcc
	v_add_f32_e32 v114, v120, v114
	v_add_f32_e32 v115, v121, v115
	v_cmp_lt_i32_e32 vcc, -1, v122
	v_add_f32_e32 v21, v73, v124
	v_sub_u32_e32 v120, v112, v1
	v_cndmask_b32_e32 v71, v173, v114, vcc
	v_cmp_lt_i32_e32 vcc, -1, v113
	v_add_u32_e32 v130, 0xffffff00, v120
	v_add_u32_e32 v132, 0xfffffe00, v120
	v_cndmask_b32_e32 v72, v173, v115, vcc
	v_cmp_lt_i32_e32 vcc, -1, v123
	v_med3_i32 v122, v130, 0, v172
	v_med3_i32 v124, v132, 0, v172
	v_cndmask_b32_e32 v73, v173, v21, vcc
	v_add_u32_e32 v21, 0xfffffcf0, v18
	v_med3_i32 v114, v21, 0, v172
	v_lshl_add_u32 v115, v114, 2, v174
	v_sub_u32_e32 v114, v112, v98
	v_add_u32_e32 v18, 0xfffffd00, v18
	v_add_u32_e32 v131, 0xffffff00, v114
	v_add_u32_e32 v133, 0xfffffe00, v114
	v_add_u32_e32 v135, 0xfffffd00, v114
	v_med3_i32 v113, v18, 0, v172
	v_med3_i32 v121, v131, 0, v172
	v_med3_i32 v123, v133, 0, v172
	v_add_u32_e32 v134, 0xfffffd00, v120
	v_med3_i32 v114, v135, 0, v172
	v_lshl_add_u32 v113, v113, 2, v174
	v_lshl_add_u32 v121, v121, 2, v174
	v_lshl_add_u32 v122, v122, 2, v174
	v_lshl_add_u32 v123, v123, 2, v174
	v_lshl_add_u32 v124, v124, 2, v174
	v_lshl_add_u32 v125, v114, 2, v174
	v_med3_i32 v114, v134, 0, v172
	v_add_f32_e32 v74, v74, v116
	v_add_f32_e32 v75, v75, v117
	v_cmp_lt_i32_e32 vcc, -1, v126
	v_lshl_add_u32 v136, v114, 2, v174
	ds_read_b32 v114, v113
	ds_read_b32 v115, v115
	ds_read_b32 v120, v121
	ds_read_b32 v121, v122
	ds_read_b32 v122, v123
	ds_read_b32 v123, v124
	ds_read_b32 v124, v125
	ds_read_b32 v125, v136
	v_cndmask_b32_e32 v75, v173, v75, vcc
	v_cmp_lt_i32_e32 vcc, -1, v127
	s_waitcnt lgkmcnt(0)
	v_add_f32_e32 v76, v76, v120
	v_add_f32_e32 v77, v77, v121
	v_add_f32_e32 v78, v78, v118
	v_add_f32_e32 v79, v79, v119
	v_cndmask_b32_e32 v74, v173, v74, vcc
	v_cmp_lt_i32_e32 vcc, -1, v130
	v_add_f32_e32 v80, v80, v122
	v_add_f32_e32 v81, v81, v123
	v_add_f32_e32 v66, v66, v114
	v_add_f32_e32 v67, v67, v115
	v_cndmask_b32_e32 v77, v173, v77, vcc
	v_cmp_lt_i32_e32 vcc, -1, v131
	v_add_f32_e32 v68, v68, v124
	v_add_f32_e32 v69, v69, v125
	s_nop 0
	v_cndmask_b32_e32 v76, v173, v76, vcc
	v_cmp_lt_i32_e32 vcc, -1, v128
	s_nop 1
	v_cndmask_b32_e32 v79, v173, v79, vcc
	v_cmp_lt_i32_e32 vcc, -1, v129
	s_nop 1
	v_cndmask_b32_e32 v78, v173, v78, vcc
	v_cmp_lt_i32_e32 vcc, -1, v132
	s_nop 1
	v_cndmask_b32_e32 v81, v173, v81, vcc
	v_cmp_lt_i32_e32 vcc, -1, v133
	s_nop 1
	v_cndmask_b32_e32 v80, v173, v80, vcc
	v_cmp_lt_i32_e32 vcc, -1, v21
	s_nop 1
	v_cndmask_b32_e32 v67, v173, v67, vcc
	v_cmp_lt_i32_e32 vcc, -1, v18
	s_nop 1
	v_cndmask_b32_e32 v66, v173, v66, vcc
	v_cmp_lt_i32_e32 vcc, -1, v134
	s_nop 1
	v_cndmask_b32_e32 v69, v173, v69, vcc
	v_cmp_lt_i32_e32 vcc, -1, v135
	s_nop 1
	v_cndmask_b32_e32 v68, v173, v68, vcc

; #define LAS __attribute__((address_space(3)))
; DEV void qk64(const LAS unsigned char* Kb, const AttnCtx& C, const ab8 (&qf)[2][2], f32x4 (&s)[2][4], float init0, float init1, bool a0, bool a1) {
;     ab8 k0[4], k1[4];
; #pragma unroll
;     for (int kt = 0; kt < 4; ++kt) { k0[kt] = *(const LAS ab8*)(Kb + swz(16 * kt + C.n, C.q4)); k1[kt] = *(const LAS ab8*)(Kb + swz(16 * kt + C.n, 4 + C.q4)); }
;     __builtin_amdgcn_sched_barrier(0);
; #pragma unroll
;     for (int kt = 0; kt < 4; ++kt) {
;         if (a0) { f32x4 c = {init0, init0, init0, init0}; c = __builtin_amdgcn_mfma_f32_16x16x32_bf16(k0[kt], qf[0][0], c, 0, 0, 0); s[0][kt] = __builtin_amdgcn_mfma_f32_16x16x32_bf16(k1[kt], qf[0][1], c, 0, 0, 0); }
;         if (a1) { f32x4 c = {init1, init1, init1, init1}; c = __builtin_amdgcn_mfma_f32_16x16x32_bf16(k0[kt], qf[1][0], c, 0, 0, 0); s[1][kt] = __builtin_amdgcn_mfma_f32_16x16x32_bf16(k1[kt], qf[1][1], c, 0, 0, 0); }
;     }
; }
; DEV void attn_unit_mfma(Frame& F, int qg, int kv) {
;     ...
;         const bool near = t0 - (1024 * i + 1039) < 128; const float bi = near ? 0.f : C.b31;
;         f32x4 s[2][4]; qk64(Kb, C, qf, s, cinit(bi, m[0], true), cinit(bi, m[1], true), true, true);
;         ab8 pf[2][2];
; #pragma unroll
;         for (int g = 0; g < 2; ++g) { if (near) mask_bias<true, false>(s[g], C, C.tq[g], 1024 * i + 31, 16, true);
.LBB0_949:
	s_mul_hi_u32 s10, s12, 0xaaaaaaab
	s_lshr_b32 s24, s10, 1
	s_mul_i32 s24, s24, 0xc000
	s_cmp_gt_i32 s22, s19
	v_subrev_u32_e32 v59, s24, v177
	s_cselect_b64 s[10:11], -1, 0
	s_add_i32 s12, s14, 0
	v_subrev_u32_e32 v58, s24, v176
	v_add_u32_e32 v70, s12, v59
	v_add_u32_e32 v71, s12, v58
	ds_read_b128 v[58:61], v70
	ds_read_b128 v[62:65], v70 offset:2048
	ds_read_b128 v[66:69], v71
	ds_read_b128 v[74:77], v71 offset:2048
	ds_read_b128 v[106:109], v70 offset:4096
	ds_read_b128 v[110:113], v70 offset:6144
	ds_read_b128 v[114:117], v71 offset:4096
	ds_read_b128 v[118:121], v71 offset:6144
	v_cndmask_b32_e64 v70, v175, 0, s[10:11]
	s_cmp_le_i32 s22, s19
	v_sub_f32_e32 v122, v70, v21
	v_sub_f32_e32 v126, v70, v95
	v_mov_b32_e32 v123, v122
	v_mov_b32_e32 v124, v122
	v_mov_b32_e32 v125, v122
	v_mov_b32_e32 v127, v126
	v_mov_b32_e32 v128, v126
	v_mov_b32_e32 v129, v126
	s_waitcnt lgkmcnt(0)
	v_mfma_f32_16x16x32_bf16 v[70:73], v[58:61], v[2:5], v[122:125]
	v_add_u32_e32 v102, v105, v104
	v_mfma_f32_16x16x32_bf16 v[58:61], v[58:61], v[10:13], v[126:129]
	v_mfma_f32_16x16x32_bf16 v[86:89], v[66:69], v[6:9], v[70:73]
	v_mfma_f32_16x16x32_bf16 v[70:73], v[66:69], v[14:17], v[58:61]
	v_mfma_f32_16x16x32_bf16 v[58:61], v[62:65], v[2:5], v[122:125]
	v_mfma_f32_16x16x32_bf16 v[82:85], v[74:77], v[6:9], v[58:61]
	v_mfma_f32_16x16x32_bf16 v[58:61], v[62:65], v[10:13], v[126:129]
	v_mfma_f32_16x16x32_bf16 v[66:69], v[74:77], v[14:17], v[58:61]
	v_mfma_f32_16x16x32_bf16 v[58:61], v[106:109], v[2:5], v[122:125]
	v_mfma_f32_16x16x32_bf16 v[78:81], v[114:117], v[6:9], v[58:61]
	v_mfma_f32_16x16x32_bf16 v[58:61], v[106:109], v[10:13], v[126:129]
	v_mfma_f32_16x16x32_bf16 v[62:65], v[114:117], v[14:17], v[58:61]
	v_mfma_f32_16x16x32_bf16 v[58:61], v[110:113], v[2:5], v[122:125]
	v_mfma_f32_16x16x32_bf16 v[74:77], v[118:121], v[6:9], v[58:61]
	v_mfma_f32_16x16x32_bf16 v[58:61], v[110:113], v[10:13], v[126:129]
	v_mfma_f32_16x16x32_bf16 v[58:61], v[118:121], v[14:17], v[58:61]
	s_cbranch_scc1 .LBB0_951
	v_add_u32_e32 v97, -4, v104
	v_add_u32_e32 v103, -4, v102
	v_add_u32_e32 v114, 0xffffffe0, v103
	v_add_u32_e32 v115, v97, v100
	v_subrev_u32_e32 v116, 52, v102
	v_add_u32_e32 v118, 0xfffffeec, v102
	v_add_u32_e32 v119, 0xfffffefc, v102
	v_add_u32_e32 v120, 0xfffffdec, v102
	v_add_u32_e32 v121, 0xfffffdfc, v102
	v_med3_i32 v106, v103, 0, v172
	v_med3_i32 v107, v115, 0, v172
	v_med3_i32 v108, v114, 0, v172
	v_med3_i32 v109, v116, 0, v172
	v_med3_i32 v110, v119, 0, v172
	v_med3_i32 v111, v118, 0, v172
	v_med3_i32 v112, v121, 0, v172
	v_med3_i32 v113, v120, 0, v172
	v_lshl_add_u32 v106, v106, 2, v174
	v_lshl_add_u32 v107, v107, 2, v174
	v_lshl_add_u32 v108, v108, 2, v174
	v_lshl_add_u32 v109, v109, 2, v174
	v_lshl_add_u32 v110, v110, 2, v174
	v_lshl_add_u32 v111, v111, 2, v174
	v_lshl_add_u32 v112, v112, 2, v174
	v_lshl_add_u32 v113, v113, 2, v174
	ds_read_b32 v117, v106
	ds_read_b32 v106, v107
	ds_read_b32 v107, v108
	ds_read_b32 v122, v109
	ds_read_b32 v108, v110
	ds_read_b32 v109, v111
	ds_read_b32 v110, v112
	ds_read_b32 v111, v113
	s_waitcnt lgkmcnt(0)
	v_add_f32_e32 v86, v86, v117
	v_cmp_lt_i32_e32 vcc, -1, v103
	v_mov_b32_e32 v112, v87
	v_mov_b32_e32 v113, v88
	v_cndmask_b32_e32 v86, v173, v86, vcc
	v_add_f32_e32 v106, v112, v106
	v_add_f32_e32 v107, v113, v107
	v_cmp_lt_i32_e32 vcc, -1, v115
	v_sub_u32_e32 v112, v97, v98
	v_sub_u32_e32 v97, v97, v1
	v_cndmask_b32_e32 v87, v173, v106, vcc
	v_cmp_lt_i32_e32 vcc, -1, v114
	v_add_f32_e32 v89, v89, v122
	v_add_u32_e32 v103, 0xfffffcec, v102
	v_add_u32_e32 v122, 0xfffffcfc, v102
	v_add_u32_e32 v123, 0xffffff00, v97
	v_add_u32_e32 v124, 0xffffff00, v112
	v_add_u32_e32 v125, 0xfffffe00, v97
	v_add_u32_e32 v126, 0xfffffe00, v112
	v_add_u32_e32 v127, 0xfffffd00, v112
	v_cndmask_b32_e32 v88, v173, v107, vcc
	v_cmp_lt_i32_e32 vcc, -1, v116
	v_med3_i32 v106, v122, 0, v172
	v_med3_i32 v107, v103, 0, v172
	v_med3_i32 v113, v124, 0, v172
	v_med3_i32 v114, v123, 0, v172
	v_med3_i32 v115, v126, 0, v172
	v_med3_i32 v116, v125, 0, v172
	v_add_u32_e32 v97, 0xfffffd00, v97
	v_med3_i32 v112, v127, 0, v172
	v_cndmask_b32_e32 v89, v173, v89, vcc
	v_lshl_add_u32 v106, v106, 2, v174
	v_lshl_add_u32 v107, v107, 2, v174
	v_lshl_add_u32 v113, v113, 2, v174
	v_lshl_add_u32 v114, v114, 2, v174
	v_lshl_add_u32 v115, v115, 2, v174
	v_lshl_add_u32 v116, v116, 2, v174
	v_lshl_add_u32 v117, v112, 2, v174
	v_med3_i32 v112, v97, 0, v172
	v_add_f32_e32 v82, v82, v108
	v_add_f32_e32 v83, v83, v109
	v_cmp_lt_i32_e32 vcc, -1, v118
	v_lshl_add_u32 v128, v112, 2, v174
	ds_read_b32 v106, v106
	ds_read_b32 v107, v107
	ds_read_b32 v112, v113
	ds_read_b32 v113, v114
	ds_read_b32 v114, v115
	ds_read_b32 v115, v116
	ds_read_b32 v116, v117
	ds_read_b32 v117, v128
	v_cndmask_b32_e32 v83, v173, v83, vcc
	v_cmp_lt_i32_e32 vcc, -1, v119
	s_waitcnt lgkmcnt(0)
	v_add_f32_e32 v84, v84, v112
	v_add_f32_e32 v85, v85, v113
	v_add_f32_e32 v78, v78, v110
	v_add_f32_e32 v79, v79, v111
	v_cndmask_b32_e32 v82, v173, v82, vcc
	v_cmp_lt_i32_e32 vcc, -1, v123
	v_add_f32_e32 v80, v80, v114
	v_add_f32_e32 v81, v81, v115
	v_add_f32_e32 v74, v74, v106
	v_add_f32_e32 v75, v75, v107
	v_cndmask_b32_e32 v85, v173, v85, vcc
	v_cmp_lt_i32_e32 vcc, -1, v124
	v_add_f32_e32 v76, v76, v116
	v_add_f32_e32 v77, v77, v117
	s_nop 0
	v_cndmask_b32_e32 v84, v173, v84, vcc
	v_cmp_lt_i32_e32 vcc, -1, v120
	s_nop 1
	v_cndmask_b32_e32 v79, v173, v79, vcc
	v_cmp_lt_i32_e32 vcc, -1, v121
	s_nop 1
	v_cndmask_b32_e32 v78, v173, v78, vcc
	v_cmp_lt_i32_e32 vcc, -1, v125
	s_nop 1
	v_cndmask_b32_e32 v81, v173, v81, vcc
	v_cmp_lt_i32_e32 vcc, -1, v126
	s_nop 1
	v_cndmask_b32_e32 v80, v173, v80, vcc
	v_cmp_lt_i32_e32 vcc, -1, v103
	s_nop 1
	v_cndmask_b32_e32 v75, v173, v75, vcc
	v_cmp_lt_i32_e32 vcc, -1, v122
	s_nop 1
	v_cndmask_b32_e32 v74, v173, v74, vcc
	v_cmp_lt_i32_e32 vcc, -1, v97
	s_nop 1
	v_cndmask_b32_e32 v77, v173, v77, vcc
	v_cmp_lt_i32_e32 vcc, -1, v127
	s_nop 1
	v_cndmask_b32_e32 v76, v173, v76, vcc
; #define LAS __attribute__((address_space(3)))
; DEV float dpp_xor1(float v) { return __builtin_bit_cast(float, __builtin_amdgcn_update_dpp(0, __builtin_bit_cast(int, v), 0xB1, 0xF, 0xF, true)); }
; DEV float dpp_xor2(float v) { return __builtin_bit_cast(float, __builtin_amdgcn_update_dpp(0, __builtin_bit_cast(int, v), 0x4E, 0xF, 0xF, true)); }
; DEV void attn_unit_mfma(Frame& F, int qg, int kv) {
;     ...
; #pragma unroll
;             for (int kt = 0; kt < 4; ++kt) {
; #pragma unroll
;                 for (int ii = 0; ii < 4; ++ii) s[g][kt][ii] = __builtin_amdgcn_exp2f(s[g][kt][ii]) * invl[g];
;                 float i0 = s[g][kt][0], i1 = s[g][kt][1], i2 = s[g][kt][2], i3 = s[g][kt][3];
;                 i0 += dpp_xor1(i0); i0 += dpp_xor2(i0); i1 += dpp_xor1(i1); i1 += dpp_xor2(i1); i2 += dpp_xor1(i2); i2 += dpp_xor2(i2); i3 += dpp_xor1(i3); i3 += dpp_xor2(i3);
;                 if (C.h == 0) { const int J = 16 * i + 4 * kt + C.q4; LAS float* sr = score + (8 * w + 4 * g + (C.n >> 2)) * SCS + J;
;                     __hip_atomic_fetch_add(sr, 2.f * (i0 + i1 + i2) + i3, __ATOMIC_RELAXED, __HIP_MEMORY_SCOPE_WORKGROUP); __hip_atomic_fetch_add(sr + 1, i3, __ATOMIC_RELAXED, __HIP_MEMORY_SCOPE_WORKGROUP); } }
.LBB0_951:
	v_exp_f32_e32 v86, v86
	v_exp_f32_e32 v87, v87
	v_exp_f32_e32 v88, v88
	v_exp_f32_e32 v89, v89
	v_add_u32_e32 v97, 0, v96
	v_mul_f32_e32 v86, v90, v86
	v_mul_f32_e32 v87, v91, v87
	v_mul_f32_e32 v88, v90, v88
	v_mul_f32_e32 v89, v91, v89
	s_nop 0
	v_add_f32_dpp v103, v86, v86 quad_perm:[1,0,3,2] row_mask:0xf bank_mask:0xf bound_ctrl:1
	v_add_f32_dpp v107, v87, v87 quad_perm:[1,0,3,2] row_mask:0xf bank_mask:0xf bound_ctrl:1
	v_add_f32_dpp v109, v88, v88 quad_perm:[1,0,3,2] row_mask:0xf bank_mask:0xf bound_ctrl:1
	v_add_f32_dpp v111, v89, v89 quad_perm:[1,0,3,2] row_mask:0xf bank_mask:0xf bound_ctrl:1
	v_mov_b32_dpp v106, v103 quad_perm:[2,3,0,1] row_mask:0xf bank_mask:0xf bound_ctrl:1
	v_mov_b32_dpp v108, v107 quad_perm:[2,3,0,1] row_mask:0xf bank_mask:0xf bound_ctrl:1
	v_mov_b32_dpp v110, v109 quad_perm:[2,3,0,1] row_mask:0xf bank_mask:0xf bound_ctrl:1
	v_mov_b32_dpp v112, v111 quad_perm:[2,3,0,1] row_mask:0xf bank_mask:0xf bound_ctrl:1
	s_and_saveexec_b64 s[12:13], s[8:9]
	s_cbranch_execz .LBB0_953
	v_add_f32_e32 v107, v107, v108
	v_add_f32_e32 v103, v103, v106
	v_add_f32_e32 v109, v109, v110
	v_add_f32_e32 v103, v103, v107
	v_add_f32_e32 v111, v111, v112
	v_add_f32_e32 v103, v103, v109
	v_fma_f32 v103, 2.0, v103, v111
	ds_add_f32 v97, v103
	ds_add_f32 v97, v111 offset:4
.LBB0_953:
	s_or_b64 exec, exec, s[12:13]
	v_exp_f32_e32 v82, v82
	v_exp_f32_e32 v83, v83
	v_exp_f32_e32 v84, v84
	v_exp_f32_e32 v85, v85
	v_mul_f32_e32 v82, v90, v82
	v_mul_f32_e32 v83, v91, v83
	v_mul_f32_e32 v84, v90, v84
	v_mul_f32_e32 v85, v91, v85
	s_nop 0
	v_add_f32_dpp v103, v82, v82 quad_perm:[1,0,3,2] row_mask:0xf bank_mask:0xf bound_ctrl:1
	v_add_f32_dpp v107, v83, v83 quad_perm:[1,0,3,2] row_mask:0xf bank_mask:0xf bound_ctrl:1
	v_add_f32_dpp v109, v84, v84 quad_perm:[1,0,3,2] row_mask:0xf bank_mask:0xf bound_ctrl:1
	v_add_f32_dpp v111, v85, v85 quad_perm:[1,0,3,2] row_mask:0xf bank_mask:0xf bound_ctrl:1
	v_mov_b32_dpp v106, v103 quad_perm:[2,3,0,1] row_mask:0xf bank_mask:0xf bound_ctrl:1
	v_mov_b32_dpp v108, v107 quad_perm:[2,3,0,1] row_mask:0xf bank_mask:0xf bound_ctrl:1
	v_mov_b32_dpp v110, v109 quad_perm:[2,3,0,1] row_mask:0xf bank_mask:0xf bound_ctrl:1
	v_mov_b32_dpp v112, v111 quad_perm:[2,3,0,1] row_mask:0xf bank_mask:0xf bound_ctrl:1
	s_and_saveexec_b64 s[12:13], s[8:9]
	s_cbranch_execz .LBB0_955
	v_add_f32_e32 v107, v107, v108
	v_add_f32_e32 v103, v103, v106
	v_add_f32_e32 v109, v109, v110
	v_add_f32_e32 v103, v103, v107
	v_add_f32_e32 v111, v111, v112
	v_add_f32_e32 v103, v103, v109
	v_fma_f32 v103, 2.0, v103, v111
	ds_add_f32 v97, v103 offset:16
	ds_add_f32 v97, v111 offset:20
.LBB0_955:
	s_or_b64 exec, exec, s[12:13]
	v_exp_f32_e32 v78, v78
	v_exp_f32_e32 v79, v79
	v_exp_f32_e32 v80, v80
	v_exp_f32_e32 v81, v81
	v_mul_f32_e32 v78, v90, v78
	v_mul_f32_e32 v79, v91, v79
	v_mul_f32_e32 v80, v90, v80
	v_mul_f32_e32 v81, v91, v81
	s_nop 0
	v_add_f32_dpp v103, v78, v78 quad_perm:[1,0,3,2] row_mask:0xf bank_mask:0xf bound_ctrl:1
	v_add_f32_dpp v107, v79, v79 quad_perm:[1,0,3,2] row_mask:0xf bank_mask:0xf bound_ctrl:1
	v_add_f32_dpp v109, v80, v80 quad_perm:[1,0,3,2] row_mask:0xf bank_mask:0xf bound_ctrl:1
	v_add_f32_dpp v111, v81, v81 quad_perm:[1,0,3,2] row_mask:0xf bank_mask:0xf bound_ctrl:1
	v_mov_b32_dpp v106, v103 quad_perm:[2,3,0,1] row_mask:0xf bank_mask:0xf bound_ctrl:1
	v_mov_b32_dpp v108, v107 quad_perm:[2,3,0,1] row_mask:0xf bank_mask:0xf bound_ctrl:1
	v_mov_b32_dpp v110, v109 quad_perm:[2,3,0,1] row_mask:0xf bank_mask:0xf bound_ctrl:1
	v_mov_b32_dpp v112, v111 quad_perm:[2,3,0,1] row_mask:0xf bank_mask:0xf bound_ctrl:1
	s_and_saveexec_b64 s[12:13], s[8:9]
	s_cbranch_execz .LBB0_957
	v_add_f32_e32 v107, v107, v108
	v_add_f32_e32 v103, v103, v106
	v_add_f32_e32 v109, v109, v110
	v_add_f32_e32 v103, v103, v107
	v_add_f32_e32 v111, v111, v112
	v_add_f32_e32 v103, v103, v109
	v_fma_f32 v103, 2.0, v103, v111
	ds_add_f32 v97, v103 offset:32
	ds_add_f32 v97, v111 offset:36
.LBB0_957:
	s_or_b64 exec, exec, s[12:13]
	v_exp_f32_e32 v74, v74
	v_exp_f32_e32 v75, v75
	v_exp_f32_e32 v76, v76
	v_exp_f32_e32 v77, v77
	v_mul_f32_e32 v74, v90, v74
	v_mul_f32_e32 v75, v91, v75
	v_mul_f32_e32 v76, v90, v76
	v_mul_f32_e32 v77, v91, v77
	s_nop 0
	v_add_f32_dpp v103, v74, v74 quad_perm:[1,0,3,2] row_mask:0xf bank_mask:0xf bound_ctrl:1
	v_add_f32_dpp v107, v75, v75 quad_perm:[1,0,3,2] row_mask:0xf bank_mask:0xf bound_ctrl:1
	v_add_f32_dpp v109, v76, v76 quad_perm:[1,0,3,2] row_mask:0xf bank_mask:0xf bound_ctrl:1
	v_add_f32_dpp v111, v77, v77 quad_perm:[1,0,3,2] row_mask:0xf bank_mask:0xf bound_ctrl:1
	v_mov_b32_dpp v106, v103 quad_perm:[2,3,0,1] row_mask:0xf bank_mask:0xf bound_ctrl:1
	v_mov_b32_dpp v108, v107 quad_perm:[2,3,0,1] row_mask:0xf bank_mask:0xf bound_ctrl:1
	v_mov_b32_dpp v110, v109 quad_perm:[2,3,0,1] row_mask:0xf bank_mask:0xf bound_ctrl:1
	v_mov_b32_dpp v112, v111 quad_perm:[2,3,0,1] row_mask:0xf bank_mask:0xf bound_ctrl:1
	s_and_saveexec_b64 s[12:13], s[8:9]
	s_cbranch_execz .LBB0_959
	v_add_f32_e32 v107, v107, v108
	v_add_f32_e32 v103, v103, v106
	v_add_f32_e32 v109, v109, v110
	v_add_f32_e32 v103, v103, v107
	v_add_f32_e32 v111, v111, v112
	v_add_f32_e32 v103, v103, v109
	v_fma_f32 v103, 2.0, v103, v111
	ds_add_f32 v97, v103 offset:48
	ds_add_f32 v97, v111 offset:52
; #define LAS __attribute__((address_space(3)))
; #define NEG_INF (-__builtin_inff())
; DEV float dpp_xor1(float v) { return __builtin_bit_cast(float, __builtin_amdgcn_update_dpp(0, __builtin_bit_cast(int, v), 0xB1, 0xF, 0xF, true)); }
; DEV float dpp_xor2(float v) { return __builtin_bit_cast(float, __builtin_amdgcn_update_dpp(0, __builtin_bit_cast(int, v), 0x4E, 0xF, 0xF, true)); }
; template <bool LUTB, bool WINLO>
; DEV void mask_bias(f32x4 (&s)[4], const AttnCtx& C, int t, int p0, int pstep, bool colok) {
; #pragma unroll
;     for (int kt = 0; kt < 4; ++kt)
; #pragma unroll
;         for (int i = 0; i < 4; ++i) { const int rel = t - (p0 + pstep * (16 * kt + 4 * C.q4 + i));
;             bool ok = colok && rel >= 0; if (WINLO) ok = ok && rel < 512;
;             float v = s[kt][i]; if (LUTB) v += C.lut[C.h * 129 + (rel < 0 ? 0 : (rel < 128 ? rel : 128))];
;             s[kt][i] = ok ? v : NEG_INF; }
; }
; DEV void attn_unit_mfma(Frame& F, int qg, int kv) {
;     ...
;         for (int g = 0; g < 2; ++g) { if (near) mask_bias<true, false>(s[g], C, C.tq[g], 1024 * i + 31, 16, true);
; #pragma unroll
;             for (int kt = 0; kt < 4; ++kt) {
; #pragma unroll
;                 for (int ii = 0; ii < 4; ++ii) s[g][kt][ii] = __builtin_amdgcn_exp2f(s[g][kt][ii]) * invl[g];
;                 float i0 = s[g][kt][0], i1 = s[g][kt][1], i2 = s[g][kt][2], i3 = s[g][kt][3];
;                 i0 += dpp_xor1(i0); i0 += dpp_xor2(i0); i1 += dpp_xor1(i1); i1 += dpp_xor2(i1); i2 += dpp_xor1(i2); i2 += dpp_xor2(i2); i3 += dpp_xor1(i3); i3 += dpp_xor2(i3);
;                 if (C.h == 0) { const int J = 16 * i + 4 * kt + C.q4; LAS float* sr = score + (8 * w + 4 * g + (C.n >> 2)) * SCS + J;
;                     __hip_atomic_fetch_add(sr, 2.f * (i0 + i1 + i2) + i3, __ATOMIC_RELAXED, __HIP_MEMORY_SCOPE_WORKGROUP); __hip_atomic_fetch_add(sr + 1, i3, __ATOMIC_RELAXED, __HIP_MEMORY_SCOPE_WORKGROUP); } }
.LBB0_959:
	s_or_b64 exec, exec, s[12:13]
	s_andn2_b64 vcc, exec, s[10:11]
	s_cbranch_vccnz .LBB0_961
	v_add_u32_e32 v114, 0xffffffe0, v102
	v_add_u32_e32 v115, v104, v100
	v_subrev_u32_e32 v116, 48, v102
	v_add_u32_e32 v117, 0xfffffef0, v102
	v_add_u32_e32 v118, 0xffffff00, v102
	v_add_u32_e32 v119, 0xfffffdf0, v102
	v_add_u32_e32 v120, 0xfffffe00, v102
	v_med3_i32 v103, v102, 0, v172
	v_med3_i32 v106, v115, 0, v172
	v_med3_i32 v107, v114, 0, v172
	v_med3_i32 v108, v116, 0, v172
	v_med3_i32 v109, v118, 0, v172
	v_med3_i32 v110, v117, 0, v172
	v_med3_i32 v111, v120, 0, v172
	v_med3_i32 v112, v119, 0, v172
	v_lshl_add_u32 v103, v103, 2, v174
	v_lshl_add_u32 v106, v106, 2, v174
	v_lshl_add_u32 v107, v107, 2, v174
	v_lshl_add_u32 v108, v108, 2, v174
	v_lshl_add_u32 v109, v109, 2, v174
	v_lshl_add_u32 v110, v110, 2, v174
	v_lshl_add_u32 v111, v111, 2, v174
	v_lshl_add_u32 v112, v112, 2, v174
	ds_read_b32 v103, v103
	ds_read_b32 v106, v106
	ds_read_b32 v107, v107
	ds_read_b32 v121, v108
	ds_read_b32 v108, v109
	ds_read_b32 v109, v110
	ds_read_b32 v110, v111
	ds_read_b32 v111, v112
	s_waitcnt lgkmcnt(0)
	v_add_f32_e32 v70, v70, v103
	v_cmp_lt_i32_e32 vcc, -1, v102
	v_mov_b32_e32 v112, v71
	v_mov_b32_e32 v113, v72
	v_cndmask_b32_e32 v70, v173, v70, vcc
	v_add_f32_e32 v106, v112, v106
	v_add_f32_e32 v107, v113, v107
	v_cmp_lt_i32_e32 vcc, -1, v115
	v_add_f32_e32 v73, v73, v121
	v_add_u32_e32 v121, 0xfffffd00, v102
	v_cndmask_b32_e32 v71, v173, v106, vcc
	v_cmp_lt_i32_e32 vcc, -1, v114
	v_sub_u32_e32 v106, v104, v98
	v_add_u32_e32 v123, 0xffffff00, v106
	v_cndmask_b32_e32 v72, v173, v107, vcc
	v_sub_u32_e32 v107, v104, v1
	v_cmp_lt_i32_e32 vcc, -1, v116
	v_add_u32_e32 v116, 0xfffffcf0, v102
	v_add_u32_e32 v122, 0xffffff00, v107
	v_add_u32_e32 v124, 0xfffffe00, v107
	v_add_u32_e32 v125, 0xfffffe00, v106
	v_add_u32_e32 v127, 0xfffffd00, v106
	v_med3_i32 v102, v121, 0, v172
	v_med3_i32 v103, v116, 0, v172
	v_med3_i32 v112, v123, 0, v172
	v_med3_i32 v113, v122, 0, v172
	v_med3_i32 v114, v125, 0, v172
	v_med3_i32 v115, v124, 0, v172
	v_add_u32_e32 v126, 0xfffffd00, v107
	v_med3_i32 v106, v127, 0, v172
	v_cndmask_b32_e32 v73, v173, v73, vcc
	v_lshl_add_u32 v102, v102, 2, v174
	v_lshl_add_u32 v103, v103, 2, v174
	v_lshl_add_u32 v112, v112, 2, v174
	v_lshl_add_u32 v113, v113, 2, v174
	v_lshl_add_u32 v114, v114, 2, v174
	v_lshl_add_u32 v115, v115, 2, v174
	v_lshl_add_u32 v128, v106, 2, v174
	v_med3_i32 v106, v126, 0, v172
	v_add_f32_e32 v66, v66, v108
	v_add_f32_e32 v67, v67, v109
	v_cmp_lt_i32_e32 vcc, -1, v117
	v_lshl_add_u32 v129, v106, 2, v174
	ds_read_b32 v102, v102
	ds_read_b32 v103, v103
	ds_read_b32 v106, v112
	ds_read_b32 v107, v113
	ds_read_b32 v112, v114
	ds_read_b32 v113, v115
	ds_read_b32 v114, v128
	ds_read_b32 v115, v129
	v_cndmask_b32_e32 v67, v173, v67, vcc
	v_cmp_lt_i32_e32 vcc, -1, v118
	s_waitcnt lgkmcnt(0)
	v_add_f32_e32 v68, v68, v106
	v_add_f32_e32 v69, v69, v107
	v_add_f32_e32 v62, v62, v110
	v_add_f32_e32 v63, v63, v111
	v_cndmask_b32_e32 v66, v173, v66, vcc
	v_cmp_lt_i32_e32 vcc, -1, v122
	v_add_f32_e32 v64, v64, v112
	v_add_f32_e32 v65, v65, v113
	v_add_f32_e32 v58, v58, v102
	v_add_f32_e32 v59, v59, v103
	v_cndmask_b32_e32 v69, v173, v69, vcc
	v_cmp_lt_i32_e32 vcc, -1, v123
	v_add_f32_e32 v60, v60, v114
	v_add_f32_e32 v61, v61, v115
	s_nop 0
	v_cndmask_b32_e32 v68, v173, v68, vcc
	v_cmp_lt_i32_e32 vcc, -1, v119
	s_nop 1
	v_cndmask_b32_e32 v63, v173, v63, vcc
	v_cmp_lt_i32_e32 vcc, -1, v120
	s_nop 1
	v_cndmask_b32_e32 v62, v173, v62, vcc
	v_cmp_lt_i32_e32 vcc, -1, v124
	s_nop 1
	v_cndmask_b32_e32 v65, v173, v65, vcc
	v_cmp_lt_i32_e32 vcc, -1, v125
	s_nop 1
	v_cndmask_b32_e32 v64, v173, v64, vcc
	v_cmp_lt_i32_e32 vcc, -1, v116
	s_nop 1
	v_cndmask_b32_e32 v59, v173, v59, vcc
	v_cmp_lt_i32_e32 vcc, -1, v121
	s_nop 1
	v_cndmask_b32_e32 v58, v173, v58, vcc
	v_cmp_lt_i32_e32 vcc, -1, v126
	s_nop 1
	v_cndmask_b32_e32 v61, v173, v61, vcc
	v_cmp_lt_i32_e32 vcc, -1, v127
	s_nop 1
	v_cndmask_b32_e32 v60, v173, v60, vcc
.LBB0_961:
	v_exp_f32_e32 v70, v70
	v_exp_f32_e32 v71, v71
	v_exp_f32_e32 v72, v72
	v_exp_f32_e32 v73, v73
	v_mul_f32_e32 v70, v92, v70
	v_mul_f32_e32 v71, v93, v71
	v_mul_f32_e32 v72, v92, v72
	v_mul_f32_e32 v73, v93, v73
	s_nop 0
	v_add_f32_dpp v102, v70, v70 quad_perm:[1,0,3,2] row_mask:0xf bank_mask:0xf bound_ctrl:1
	v_add_f32_dpp v106, v71, v71 quad_perm:[1,0,3,2] row_mask:0xf bank_mask:0xf bound_ctrl:1
	v_add_f32_dpp v108, v72, v72 quad_perm:[1,0,3,2] row_mask:0xf bank_mask:0xf bound_ctrl:1
	v_add_f32_dpp v110, v73, v73 quad_perm:[1,0,3,2] row_mask:0xf bank_mask:0xf bound_ctrl:1
	v_mov_b32_dpp v103, v102 quad_perm:[2,3,0,1] row_mask:0xf bank_mask:0xf bound_ctrl:1
	v_mov_b32_dpp v107, v106 quad_perm:[2,3,0,1] row_mask:0xf bank_mask:0xf bound_ctrl:1
	v_mov_b32_dpp v109, v108 quad_perm:[2,3,0,1] row_mask:0xf bank_mask:0xf bound_ctrl:1
	v_mov_b32_dpp v111, v110 quad_perm:[2,3,0,1] row_mask:0xf bank_mask:0xf bound_ctrl:1
	s_and_saveexec_b64 s[10:11], s[8:9]
	s_cbranch_execz .LBB0_963
	v_add_f32_e32 v106, v106, v107
	v_add_f32_e32 v102, v102, v103
	v_add_f32_e32 v108, v108, v109
	v_add_f32_e32 v102, v102, v106
	v_add_f32_e32 v110, v110, v111
	v_add_f32_e32 v102, v102, v108
	v_fma_f32 v102, 2.0, v102, v110
	ds_add_f32 v97, v102 offset:4160
	ds_add_f32 v97, v110 offset:4164
; #define LAS __attribute__((address_space(3)))
; DEV float dpp_xor1(float v) { return __builtin_bit_cast(float, __builtin_amdgcn_update_dpp(0, __builtin_bit_cast(int, v), 0xB1, 0xF, 0xF, true)); }
; DEV float dpp_xor2(float v) { return __builtin_bit_cast(float, __builtin_amdgcn_update_dpp(0, __builtin_bit_cast(int, v), 0x4E, 0xF, 0xF, true)); }
; DEV void attn_unit_mfma(Frame& F, int qg, int kv) {
;     ...
; #pragma unroll
;             for (int kt = 0; kt < 4; ++kt) {
; #pragma unroll
;                 for (int ii = 0; ii < 4; ++ii) s[g][kt][ii] = __builtin_amdgcn_exp2f(s[g][kt][ii]) * invl[g];
;                 float i0 = s[g][kt][0], i1 = s[g][kt][1], i2 = s[g][kt][2], i3 = s[g][kt][3];
;                 i0 += dpp_xor1(i0); i0 += dpp_xor2(i0); i1 += dpp_xor1(i1); i1 += dpp_xor2(i1); i2 += dpp_xor1(i2); i2 += dpp_xor2(i2); i3 += dpp_xor1(i3); i3 += dpp_xor2(i3);
;                 if (C.h == 0) { const int J = 16 * i + 4 * kt + C.q4; LAS float* sr = score + (8 * w + 4 * g + (C.n >> 2)) * SCS + J;
;                     __hip_atomic_fetch_add(sr, 2.f * (i0 + i1 + i2) + i3, __ATOMIC_RELAXED, __HIP_MEMORY_SCOPE_WORKGROUP); __hip_atomic_fetch_add(sr + 1, i3, __ATOMIC_RELAXED, __HIP_MEMORY_SCOPE_WORKGROUP); } }
.LBB0_963:
	s_or_b64 exec, exec, s[10:11]
	v_exp_f32_e32 v66, v66
	v_exp_f32_e32 v67, v67
	v_exp_f32_e32 v68, v68
	v_exp_f32_e32 v69, v69
	v_mul_f32_e32 v66, v92, v66
	v_mul_f32_e32 v67, v93, v67
	v_mul_f32_e32 v68, v92, v68
	v_mul_f32_e32 v69, v93, v69
	s_nop 0
	v_add_f32_dpp v102, v66, v66 quad_perm:[1,0,3,2] row_mask:0xf bank_mask:0xf bound_ctrl:1
	v_add_f32_dpp v106, v67, v67 quad_perm:[1,0,3,2] row_mask:0xf bank_mask:0xf bound_ctrl:1
	v_add_f32_dpp v108, v68, v68 quad_perm:[1,0,3,2] row_mask:0xf bank_mask:0xf bound_ctrl:1
	v_add_f32_dpp v110, v69, v69 quad_perm:[1,0,3,2] row_mask:0xf bank_mask:0xf bound_ctrl:1
	v_mov_b32_dpp v103, v102 quad_perm:[2,3,0,1] row_mask:0xf bank_mask:0xf bound_ctrl:1
	v_mov_b32_dpp v107, v106 quad_perm:[2,3,0,1] row_mask:0xf bank_mask:0xf bound_ctrl:1
	v_mov_b32_dpp v109, v108 quad_perm:[2,3,0,1] row_mask:0xf bank_mask:0xf bound_ctrl:1
	v_mov_b32_dpp v111, v110 quad_perm:[2,3,0,1] row_mask:0xf bank_mask:0xf bound_ctrl:1
	s_and_saveexec_b64 s[10:11], s[8:9]
	s_cbranch_execz .LBB0_965
	v_add_f32_e32 v106, v106, v107
	v_add_f32_e32 v102, v102, v103
	v_add_f32_e32 v108, v108, v109
	v_add_f32_e32 v102, v102, v106
	v_add_f32_e32 v110, v110, v111
	v_add_f32_e32 v102, v102, v108
	v_fma_f32 v102, 2.0, v102, v110
	ds_add_f32 v97, v102 offset:4176
	ds_add_f32 v97, v110 offset:4180
.LBB0_965:
	s_or_b64 exec, exec, s[10:11]
	v_exp_f32_e32 v62, v62
	v_exp_f32_e32 v63, v63
	v_exp_f32_e32 v64, v64
	v_exp_f32_e32 v65, v65
	v_mul_f32_e32 v62, v92, v62
	v_mul_f32_e32 v63, v93, v63
	v_mul_f32_e32 v64, v92, v64
	v_mul_f32_e32 v65, v93, v65
	s_nop 0
	v_add_f32_dpp v102, v62, v62 quad_perm:[1,0,3,2] row_mask:0xf bank_mask:0xf bound_ctrl:1
	v_add_f32_dpp v106, v63, v63 quad_perm:[1,0,3,2] row_mask:0xf bank_mask:0xf bound_ctrl:1
	v_add_f32_dpp v108, v64, v64 quad_perm:[1,0,3,2] row_mask:0xf bank_mask:0xf bound_ctrl:1
	v_add_f32_dpp v110, v65, v65 quad_perm:[1,0,3,2] row_mask:0xf bank_mask:0xf bound_ctrl:1
	v_mov_b32_dpp v103, v102 quad_perm:[2,3,0,1] row_mask:0xf bank_mask:0xf bound_ctrl:1
	v_mov_b32_dpp v107, v106 quad_perm:[2,3,0,1] row_mask:0xf bank_mask:0xf bound_ctrl:1
	v_mov_b32_dpp v109, v108 quad_perm:[2,3,0,1] row_mask:0xf bank_mask:0xf bound_ctrl:1
	v_mov_b32_dpp v111, v110 quad_perm:[2,3,0,1] row_mask:0xf bank_mask:0xf bound_ctrl:1
	s_and_saveexec_b64 s[10:11], s[8:9]
	s_cbranch_execz .LBB0_967
	v_add_f32_e32 v106, v106, v107
	v_add_f32_e32 v102, v102, v103
	v_add_f32_e32 v108, v108, v109
	v_add_f32_e32 v102, v102, v106
	v_add_f32_e32 v110, v110, v111
	v_add_f32_e32 v102, v102, v108
	v_fma_f32 v102, 2.0, v102, v110
	ds_add_f32 v97, v102 offset:4192
	ds_add_f32 v97, v110 offset:4196
.LBB0_967:
	s_or_b64 exec, exec, s[10:11]
	v_exp_f32_e32 v58, v58
	v_exp_f32_e32 v59, v59
	v_exp_f32_e32 v60, v60
	v_exp_f32_e32 v61, v61
	v_mul_f32_e32 v58, v92, v58
	v_mul_f32_e32 v59, v93, v59
	v_mul_f32_e32 v60, v92, v60
	v_mul_f32_e32 v61, v93, v61
	s_nop 0
	v_add_f32_dpp v102, v58, v58 quad_perm:[1,0,3,2] row_mask:0xf bank_mask:0xf bound_ctrl:1
	v_add_f32_dpp v106, v59, v59 quad_perm:[1,0,3,2] row_mask:0xf bank_mask:0xf bound_ctrl:1
	v_add_f32_dpp v108, v60, v60 quad_perm:[1,0,3,2] row_mask:0xf bank_mask:0xf bound_ctrl:1
	v_add_f32_dpp v110, v61, v61 quad_perm:[1,0,3,2] row_mask:0xf bank_mask:0xf bound_ctrl:1
	v_mov_b32_dpp v103, v102 quad_perm:[2,3,0,1] row_mask:0xf bank_mask:0xf bound_ctrl:1
	v_mov_b32_dpp v107, v106 quad_perm:[2,3,0,1] row_mask:0xf bank_mask:0xf bound_ctrl:1
	v_mov_b32_dpp v109, v108 quad_perm:[2,3,0,1] row_mask:0xf bank_mask:0xf bound_ctrl:1
	v_mov_b32_dpp v111, v110 quad_perm:[2,3,0,1] row_mask:0xf bank_mask:0xf bound_ctrl:1
	s_and_saveexec_b64 s[10:11], s[8:9]
	s_cbranch_execz .LBB0_942
	v_add_f32_e32 v106, v106, v107
	v_add_f32_e32 v102, v102, v103
	v_add_f32_e32 v108, v108, v109
	v_add_f32_e32 v102, v102, v106
	v_add_f32_e32 v110, v110, v111
	v_add_f32_e32 v102, v102, v108
	v_fma_f32 v102, 2.0, v102, v110
	ds_add_f32 v97, v102 offset:4208
	ds_add_f32 v97, v110 offset:4212
	s_branch .LBB0_942

; #define NEG_INF (-__builtin_inff())
; template <bool LUTB, bool WINLO>
; DEV void mask_bias(f32x4 (&s)[4], const AttnCtx& C, int t, int p0, int pstep, bool colok) {
; #pragma unroll
;     for (int kt = 0; kt < 4; ++kt)
; #pragma unroll
;         for (int i = 0; i < 4; ++i) { const int rel = t - (p0 + pstep * (16 * kt + 4 * C.q4 + i));
;             bool ok = colok && rel >= 0; if (WINLO) ok = ok && rel < 512;
;             float v = s[kt][i]; if (LUTB) v += C.lut[C.h * 129 + (rel < 0 ? 0 : (rel < 128 ? rel : 128))];
;             s[kt][i] = ok ? v : NEG_INF; }
; }
; DEV void attn_unit_mfma(Frame& F, int qg, int kv) {
;     ...
;         const int j = lst[1 + i]; const unsigned byte = (msk[2 * j + (w >> 2)] >> (8 * (w & 3))) & 0xffu;
;         const bool a0 = (byte & 0xfu) != 0u, a1 = (byte & 0xf0u) != 0u;
;         if (a0 || a1) {
;             const bool near = j >= cur - 2; const float bi = near ? 0.f : C.b31;
;             const bool c0 = ((byte >> (C.n >> 2)) & 1u) != 0u, c1 = ((byte >> (4 + (C.n >> 2))) & 1u) != 0u;
;     ...
;             if (a0 && a1) SEL_BODY(true, true); else if (a0) SEL_BODY(true, false); else SEL_BODY(false, true);
.Lmy_orig_0:
	s_and_b32 s9, s8, 15
	s_cmp_eq_u32 s9, 0
	s_cselect_b64 s[14:15], -1, 0
	s_and_b32 s9, s8, 0xf0
	s_cmp_eq_u32 s9, 0
	s_cselect_b64 s[12:13], -1, 0
	s_cmp_ge_i32 s29, s22
	s_cselect_b64 s[18:19], -1, 0
	s_cmp_lt_i32 s29, s22
	v_and_b32_e32 v66, s8, v206
	s_cselect_b64 vcc, -1, 0
	v_cmp_ne_u32_e64 s[10:11], 0, v66
	v_and_b32_e32 v66, s8, v207
	s_or_b64 s[16:17], s[14:15], s[12:13]
	v_cndmask_b32_e32 v214, 0, v175, vcc
	v_cmp_ne_u32_e64 s[8:9], 0, v66
	s_mov_b64 s[12:13], -1
	s_and_b64 vcc, exec, s[16:17]
	s_cbranch_vccz .LBB0_1186
	v_add3_u32 v66, s27, v199, v198
	v_add3_u32 v67, s27, v197, v198
	ds_read_b128 v[70:73], v66
	ds_read_b128 v[74:77], v66 offset:2048
	ds_read_b128 v[90:93], v67
	ds_read_b128 v[78:81], v67 offset:2048
	ds_read_b128 v[82:85], v66 offset:4096
	ds_read_b128 v[86:89], v66 offset:6144
	ds_read_b128 v[94:97], v67 offset:4096
	ds_read_b128 v[66:69], v67 offset:6144
	s_and_b64 vcc, exec, s[14:15]
	s_cbranch_vccz .LBB0_1180
	v_cmp_eq_f32_e64 s[12:13], s3, v212
	s_nop 1
	v_cndmask_b32_e64 v98, v212, 0, s[12:13]
	v_sub_f32_e32 v98, v214, v98
	v_cndmask_b32_e64 v102, v173, v98, s[8:9]
	v_mov_b32_e32 v103, v102
	v_mov_b32_e32 v104, v102
	v_mov_b32_e32 v105, v102
	s_andn2_b64 vcc, exec, s[18:19]
	s_waitcnt lgkmcnt(0)
	v_mfma_f32_16x16x32_bf16 v[98:101], v[70:73], v[10:13], v[102:105]
	v_mfma_f32_16x16x32_bf16 v[110:113], v[90:93], v[14:17], v[98:101]
	v_mfma_f32_16x16x32_bf16 v[98:101], v[74:77], v[10:13], v[102:105]
	v_mfma_f32_16x16x32_bf16 v[106:109], v[78:81], v[14:17], v[98:101]
	v_mfma_f32_16x16x32_bf16 v[98:101], v[82:85], v[10:13], v[102:105]
	v_mfma_f32_16x16x32_bf16 v[102:105], v[86:89], v[10:13], v[102:105]
	v_mfma_f32_16x16x32_bf16 v[98:101], v[94:97], v[14:17], v[98:101]
	v_mfma_f32_16x16x32_bf16 v[102:105], v[66:69], v[14:17], v[102:105]
	s_cbranch_vccnz .LBB0_1177
	s_lshl_b32 s14, s29, 6
	v_subrev_u32_e32 v122, s14, v144
	v_sub_u32_e32 v123, v122, v20
	v_add_u32_e32 v124, v122, v208
	v_add_u32_e32 v125, -3, v123
	v_add_u32_e32 v126, -2, v123
	v_subrev_u32_e32 v127, 17, v123
	v_add_u32_e32 v128, -16, v123
	v_subrev_u32_e32 v129, 33, v123
	v_subrev_u32_e32 v130, 32, v123
	v_med3_i32 v114, v123, 0, v172
	v_med3_i32 v115, v124, 0, v172
	v_med3_i32 v116, v126, 0, v172
	v_med3_i32 v117, v125, 0, v172
	v_med3_i32 v118, v128, 0, v172
	v_med3_i32 v119, v127, 0, v172
	v_med3_i32 v120, v130, 0, v172
	v_med3_i32 v121, v129, 0, v172
	v_lshl_add_u32 v114, v114, 2, v174
	v_lshl_add_u32 v115, v115, 2, v174
	v_lshl_add_u32 v116, v116, 2, v174
	v_lshl_add_u32 v117, v117, 2, v174
	v_lshl_add_u32 v118, v118, 2, v174
	v_lshl_add_u32 v119, v119, 2, v174
	v_lshl_add_u32 v120, v120, 2, v174
	v_lshl_add_u32 v121, v121, 2, v174
	ds_read_b32 v114, v114
	ds_read_b32 v115, v115
	ds_read_b32 v116, v116
	ds_read_b32 v117, v117
	ds_read_b32 v118, v118
	ds_read_b32 v119, v119
	ds_read_b32 v120, v120
	ds_read_b32 v121, v121
	s_waitcnt lgkmcnt(0)
	v_add_f32_e32 v110, v110, v114
	v_add_f32_e32 v111, v111, v115
	v_cmp_lt_i32_e32 vcc, -1, v124
	v_add_f32_e32 v112, v112, v116
	v_add_f32_e32 v113, v113, v117
	v_sub_u32_e32 v116, v122, v158
	v_cndmask_b32_e32 v111, v173, v111, vcc
	v_cmp_lt_i32_e32 vcc, -1, v123
	v_sub_u32_e32 v117, v122, v1
	v_subrev_u32_e32 v124, 49, v123
	v_cndmask_b32_e32 v110, v173, v110, vcc
	v_cmp_lt_i32_e32 vcc, -1, v125
	v_subrev_u32_e32 v125, 48, v123
	v_add_u32_e32 v131, -16, v116
	v_cndmask_b32_e32 v113, v173, v113, vcc
	v_cmp_lt_i32_e32 vcc, -1, v126
	v_add_u32_e32 v126, -16, v117
	v_subrev_u32_e32 v132, 32, v117
	v_subrev_u32_e32 v133, 32, v116
	v_subrev_u32_e32 v135, 48, v116
	v_med3_i32 v114, v125, 0, v172
	v_med3_i32 v115, v124, 0, v172
	v_med3_i32 v122, v131, 0, v172
	v_med3_i32 v123, v126, 0, v172
	v_add_f32_e32 v106, v106, v118
	v_add_f32_e32 v107, v107, v119
	v_med3_i32 v118, v133, 0, v172
	v_med3_i32 v119, v132, 0, v172
	v_subrev_u32_e32 v134, 48, v117
	v_med3_i32 v116, v135, 0, v172
	v_lshl_add_u32 v114, v114, 2, v174
	v_lshl_add_u32 v115, v115, 2, v174
	v_lshl_add_u32 v122, v122, 2, v174
	v_lshl_add_u32 v123, v123, 2, v174
	v_lshl_add_u32 v118, v118, 2, v174
	v_lshl_add_u32 v119, v119, 2, v174
	v_lshl_add_u32 v136, v116, 2, v174
	v_med3_i32 v116, v134, 0, v172
	v_lshl_add_u32 v137, v116, 2, v174
	ds_read_b32 v114, v114
	ds_read_b32 v115, v115
	ds_read_b32 v116, v122
	ds_read_b32 v117, v123
	ds_read_b32 v118, v118
	ds_read_b32 v119, v119
	ds_read_b32 v122, v136
	ds_read_b32 v123, v137
	v_cndmask_b32_e32 v112, v173, v112, vcc
	s_waitcnt lgkmcnt(0)
	v_add_f32_e32 v108, v108, v116
	v_add_f32_e32 v109, v109, v117
	v_cmp_lt_i32_e32 vcc, -1, v126
	v_add_f32_e32 v100, v100, v118
	v_add_f32_e32 v101, v101, v119
	v_add_f32_e32 v98, v98, v120
	v_add_f32_e32 v99, v99, v121
	v_cndmask_b32_e32 v109, v173, v109, vcc
	v_cmp_lt_i32_e32 vcc, -1, v131
	v_add_f32_e32 v104, v104, v122
	v_add_f32_e32 v105, v105, v123
	v_add_f32_e32 v102, v102, v114
	v_add_f32_e32 v103, v103, v115
	v_cndmask_b32_e32 v108, v173, v108, vcc
	v_cmp_lt_i32_e32 vcc, -1, v127
	s_nop 1
	v_cndmask_b32_e32 v107, v173, v107, vcc
	v_cmp_lt_i32_e32 vcc, -1, v128
	s_nop 1
	v_cndmask_b32_e32 v106, v173, v106, vcc
	v_cmp_lt_i32_e32 vcc, -1, v132
	s_nop 1
	v_cndmask_b32_e32 v101, v173, v101, vcc
	v_cmp_lt_i32_e32 vcc, -1, v133
	s_nop 1
	v_cndmask_b32_e32 v100, v173, v100, vcc
	v_cmp_lt_i32_e32 vcc, -1, v129
	s_nop 1
	v_cndmask_b32_e32 v99, v173, v99, vcc
	v_cmp_lt_i32_e32 vcc, -1, v130
	s_nop 1
	v_cndmask_b32_e32 v98, v173, v98, vcc
	v_cmp_lt_i32_e32 vcc, -1, v134
	s_nop 1
	v_cndmask_b32_e32 v105, v173, v105, vcc
	v_cmp_lt_i32_e32 vcc, -1, v135
	s_nop 1
	v_cndmask_b32_e32 v104, v173, v104, vcc
	v_cmp_lt_i32_e32 vcc, -1, v124
	s_nop 1
	v_cndmask_b32_e32 v103, v173, v103, vcc
	v_cmp_lt_i32_e32 vcc, -1, v125
	s_nop 1
	v_cndmask_b32_e32 v102, v173, v102, vcc

; #define NEG_INF (-__builtin_inff())
; template <bool LUTB, bool WINLO>
; DEV void mask_bias(f32x4 (&s)[4], const AttnCtx& C, int t, int p0, int pstep, bool colok) {
; #pragma unroll
;     for (int kt = 0; kt < 4; ++kt)
; #pragma unroll
;         for (int i = 0; i < 4; ++i) { const int rel = t - (p0 + pstep * (16 * kt + 4 * C.q4 + i));
;             bool ok = colok && rel >= 0; if (WINLO) ok = ok && rel < 512;
;             float v = s[kt][i]; if (LUTB) v += C.lut[C.h * 129 + (rel < 0 ? 0 : (rel < 128 ? rel : 128))];
;             s[kt][i] = ok ? v : NEG_INF; }
; }
; DEV void attn_unit_mfma(Frame& F, int qg, int kv) {
;     ...
;             if (a0 && a1) SEL_BODY(true, true); else if (a0) SEL_BODY(true, false); else SEL_BODY(false, true);
.LBB0_1180:
	v_mov_b64_e32 v[136:137], v[60:61]
	s_nop 0
	v_mov_b64_e32 v[116:117], v[64:65]
	v_mov_b64_e32 v[124:125], v[56:57]
	v_mov_b64_e32 v[128:129], v[52:53]
	v_mov_b64_e32 v[132:133], v[48:49]
	s_and_b64 vcc, exec, s[12:13]
	v_mov_b32_e32 v215, v213
	v_mov_b64_e32 v[134:135], v[58:59]
	v_mov_b64_e32 v[114:115], v[62:63]
	v_mov_b64_e32 v[122:123], v[54:55]
	v_mov_b64_e32 v[126:127], v[50:51]
	v_mov_b64_e32 v[130:131], v[46:47]
	s_cbranch_vccz .LBB0_1252
	v_cmp_eq_f32_e64 s[12:13], s3, v213
	s_nop 1
	v_cndmask_b32_e64 v98, v213, 0, s[12:13]
	v_sub_f32_e32 v98, v214, v98
	v_cndmask_b32_e64 v98, v173, v98, s[10:11]
	v_mov_b32_e32 v99, v98
	v_mov_b32_e32 v100, v98
	v_mov_b32_e32 v101, v98
	s_andn2_b64 vcc, exec, s[18:19]
	s_waitcnt lgkmcnt(0)
	v_mfma_f32_16x16x32_bf16 v[70:73], v[70:73], v[2:5], v[98:101]
	v_mfma_f32_16x16x32_bf16 v[90:93], v[90:93], v[6:9], v[70:73]
	v_mfma_f32_16x16x32_bf16 v[70:73], v[74:77], v[2:5], v[98:101]
	v_mfma_f32_16x16x32_bf16 v[74:77], v[78:81], v[6:9], v[70:73]
	v_mfma_f32_16x16x32_bf16 v[70:73], v[82:85], v[2:5], v[98:101]
	v_mfma_f32_16x16x32_bf16 v[78:81], v[86:89], v[2:5], v[98:101]
	v_mfma_f32_16x16x32_bf16 v[70:73], v[94:97], v[6:9], v[70:73]
	v_mfma_f32_16x16x32_bf16 v[66:69], v[66:69], v[6:9], v[78:81]
	s_cbranch_vccnz .LBB0_1183
	s_lshl_b32 s14, s29, 6
	v_subrev_u32_e32 v86, s14, v146
	v_sub_u32_e32 v87, v86, v20
	v_add_u32_e32 v88, v86, v208
	v_add_u32_e32 v89, -3, v87
	v_add_u32_e32 v94, -2, v87
	v_subrev_u32_e32 v95, 17, v87
	v_add_u32_e32 v96, -16, v87
	v_subrev_u32_e32 v97, 33, v87
	v_subrev_u32_e32 v98, 32, v87
	v_med3_i32 v78, v87, 0, v172
	v_med3_i32 v79, v88, 0, v172
	v_med3_i32 v80, v94, 0, v172
	v_med3_i32 v81, v89, 0, v172
	v_med3_i32 v82, v96, 0, v172
	v_med3_i32 v83, v95, 0, v172
	v_med3_i32 v84, v98, 0, v172
	v_med3_i32 v85, v97, 0, v172
	v_lshl_add_u32 v78, v78, 2, v174
	v_lshl_add_u32 v79, v79, 2, v174
	v_lshl_add_u32 v80, v80, 2, v174
	v_lshl_add_u32 v81, v81, 2, v174
	v_lshl_add_u32 v82, v82, 2, v174
	v_lshl_add_u32 v83, v83, 2, v174
	v_lshl_add_u32 v84, v84, 2, v174
	v_lshl_add_u32 v85, v85, 2, v174
	ds_read_b32 v78, v78
	ds_read_b32 v79, v79
	ds_read_b32 v80, v80
	ds_read_b32 v81, v81
	ds_read_b32 v82, v82
	ds_read_b32 v83, v83
	ds_read_b32 v84, v84
	ds_read_b32 v85, v85
	s_waitcnt lgkmcnt(0)
	v_add_f32_e32 v78, v90, v78
	v_add_f32_e32 v79, v91, v79
	v_cmp_lt_i32_e32 vcc, -1, v88
	v_add_f32_e32 v80, v92, v80
	v_add_f32_e32 v81, v93, v81
	v_subrev_u32_e32 v88, 49, v87
	v_cndmask_b32_e32 v91, v173, v79, vcc
	v_cmp_lt_i32_e32 vcc, -1, v87
	v_med3_i32 v79, v88, 0, v172
	v_add_f32_e32 v74, v74, v82
	v_add_f32_e32 v75, v75, v83
	v_cndmask_b32_e32 v90, v173, v78, vcc
	v_cmp_lt_i32_e32 vcc, -1, v89
	v_subrev_u32_e32 v89, 48, v87
	v_med3_i32 v78, v89, 0, v172
	v_cndmask_b32_e32 v93, v173, v81, vcc
	v_cmp_lt_i32_e32 vcc, -1, v94
	v_sub_u32_e32 v81, v86, v1
	v_add_u32_e32 v94, -16, v81
	v_cndmask_b32_e32 v92, v173, v80, vcc
	v_sub_u32_e32 v80, v86, v158
	v_add_u32_e32 v99, -16, v80
	v_subrev_u32_e32 v100, 32, v81
	v_subrev_u32_e32 v101, 32, v80
	v_subrev_u32_e32 v103, 48, v80
	v_med3_i32 v86, v99, 0, v172
	v_med3_i32 v87, v94, 0, v172
	v_med3_i32 v82, v101, 0, v172
	v_med3_i32 v83, v100, 0, v172
	v_subrev_u32_e32 v102, 48, v81
	v_med3_i32 v80, v103, 0, v172
	v_lshl_add_u32 v78, v78, 2, v174
	v_lshl_add_u32 v79, v79, 2, v174
	v_lshl_add_u32 v86, v86, 2, v174
	v_lshl_add_u32 v87, v87, 2, v174
	v_lshl_add_u32 v82, v82, 2, v174
	v_lshl_add_u32 v83, v83, 2, v174
	v_lshl_add_u32 v104, v80, 2, v174
	v_med3_i32 v80, v102, 0, v172
	v_lshl_add_u32 v105, v80, 2, v174
	ds_read_b32 v78, v78
	ds_read_b32 v79, v79
	ds_read_b32 v80, v86
	ds_read_b32 v81, v87
	ds_read_b32 v82, v82
	ds_read_b32 v83, v83
	ds_read_b32 v86, v104
	ds_read_b32 v87, v105
	s_waitcnt lgkmcnt(0)
	v_add_f32_e32 v76, v76, v80
	v_add_f32_e32 v77, v77, v81
	v_cmp_lt_i32_e32 vcc, -1, v94
	v_add_f32_e32 v72, v72, v82
	v_add_f32_e32 v73, v73, v83
	v_add_f32_e32 v70, v70, v84
	v_add_f32_e32 v71, v71, v85
	v_cndmask_b32_e32 v77, v173, v77, vcc
	v_cmp_lt_i32_e32 vcc, -1, v99
	v_add_f32_e32 v68, v68, v86
	v_add_f32_e32 v69, v69, v87
	v_add_f32_e32 v66, v66, v78
	v_add_f32_e32 v67, v67, v79
	v_cndmask_b32_e32 v76, v173, v76, vcc
	v_cmp_lt_i32_e32 vcc, -1, v95
	s_nop 1
	v_cndmask_b32_e32 v75, v173, v75, vcc
	v_cmp_lt_i32_e32 vcc, -1, v96
	s_nop 1
	v_cndmask_b32_e32 v74, v173, v74, vcc
	v_cmp_lt_i32_e32 vcc, -1, v100
	s_nop 1
	v_cndmask_b32_e32 v73, v173, v73, vcc
	v_cmp_lt_i32_e32 vcc, -1, v101
	s_nop 1
	v_cndmask_b32_e32 v72, v173, v72, vcc
	v_cmp_lt_i32_e32 vcc, -1, v97
	s_nop 1
	v_cndmask_b32_e32 v71, v173, v71, vcc
	v_cmp_lt_i32_e32 vcc, -1, v98
	s_nop 1
	v_cndmask_b32_e32 v70, v173, v70, vcc
	v_cmp_lt_i32_e32 vcc, -1, v102
	s_nop 1
	v_cndmask_b32_e32 v69, v173, v69, vcc
	v_cmp_lt_i32_e32 vcc, -1, v103
	s_nop 1
	v_cndmask_b32_e32 v68, v173, v68, vcc
	v_cmp_lt_i32_e32 vcc, -1, v88
	s_nop 1
	v_cndmask_b32_e32 v67, v173, v67, vcc
	v_cmp_lt_i32_e32 vcc, -1, v89
	s_nop 1
	v_cndmask_b32_e32 v66, v173, v66, vcc

; #define NEG_INF (-__builtin_inff())
; template <bool LUTB, bool WINLO>
; DEV void mask_bias(f32x4 (&s)[4], const AttnCtx& C, int t, int p0, int pstep, bool colok) {
; #pragma unroll
;     for (int kt = 0; kt < 4; ++kt)
; #pragma unroll
;         for (int i = 0; i < 4; ++i) { const int rel = t - (p0 + pstep * (16 * kt + 4 * C.q4 + i));
;             bool ok = colok && rel >= 0; if (WINLO) ok = ok && rel < 512;
;             float v = s[kt][i]; if (LUTB) v += C.lut[C.h * 129 + (rel < 0 ? 0 : (rel < 128 ? rel : 128))];
;             s[kt][i] = ok ? v : NEG_INF; }
; }
; DEV void attn_unit_mfma(Frame& F, int qg, int kv) {
;     ...
;             if (a0 && a1) SEL_BODY(true, true); else if (a0) SEL_BODY(true, false); else SEL_BODY(false, true);
.LBB0_1187:
	v_cmp_eq_f32_e64 s[14:15], s3, v213
	v_cmp_eq_f32_e64 s[12:13], s3, v212
	s_waitcnt lgkmcnt(0)
	v_add3_u32 v79, s27, v199, v198
	v_cndmask_b32_e64 v66, v213, 0, s[14:15]
	v_sub_f32_e32 v66, v214, v66
	v_cndmask_b32_e64 v78, v173, v66, s[10:11]
	v_cndmask_b32_e64 v66, v212, 0, s[12:13]
	v_sub_f32_e32 v66, v214, v66
	v_add3_u32 v80, s27, v197, v198
	v_cndmask_b32_e64 v98, v173, v66, s[8:9]
	ds_read_b128 v[66:69], v79
	ds_read_b128 v[70:73], v80
	ds_read_b128 v[74:77], v79 offset:2048
	ds_read_b128 v[90:93], v80 offset:2048
	ds_read_b128 v[94:97], v79 offset:4096
	ds_read_b128 v[102:105], v80 offset:4096
	ds_read_b128 v[106:109], v79 offset:6144
	ds_read_b128 v[110:113], v80 offset:6144
	v_mov_b32_e32 v79, v78
	v_mov_b32_e32 v80, v78
	v_mov_b32_e32 v81, v78
	v_mov_b32_e32 v99, v98
	v_mov_b32_e32 v100, v98
	v_mov_b32_e32 v101, v98
	s_waitcnt lgkmcnt(0)
	v_mfma_f32_16x16x32_bf16 v[82:85], v[66:69], v[2:5], v[78:81]
	s_andn2_b64 vcc, exec, s[18:19]
	v_mfma_f32_16x16x32_bf16 v[66:69], v[66:69], v[10:13], v[98:101]
	v_mfma_f32_16x16x32_bf16 v[82:85], v[70:73], v[6:9], v[82:85]
	v_mfma_f32_16x16x32_bf16 v[66:69], v[70:73], v[14:17], v[66:69]
	v_mfma_f32_16x16x32_bf16 v[70:73], v[74:77], v[2:5], v[78:81]
	v_mfma_f32_16x16x32_bf16 v[86:89], v[90:93], v[6:9], v[70:73]
	v_mfma_f32_16x16x32_bf16 v[70:73], v[74:77], v[10:13], v[98:101]
	v_mfma_f32_16x16x32_bf16 v[74:77], v[94:97], v[2:5], v[78:81]
	v_mfma_f32_16x16x32_bf16 v[78:81], v[106:109], v[2:5], v[78:81]
	v_mfma_f32_16x16x32_bf16 v[70:73], v[90:93], v[14:17], v[70:73]
	v_mfma_f32_16x16x32_bf16 v[90:93], v[102:105], v[6:9], v[74:77]
	v_mfma_f32_16x16x32_bf16 v[74:77], v[94:97], v[10:13], v[98:101]
	v_mfma_f32_16x16x32_bf16 v[94:97], v[110:113], v[6:9], v[78:81]
	v_mfma_f32_16x16x32_bf16 v[78:81], v[106:109], v[10:13], v[98:101]
	v_mfma_f32_16x16x32_bf16 v[74:77], v[102:105], v[14:17], v[74:77]
	s_nop 1
	v_cndmask_b32_e64 v98, 0, 1, s[18:19]
	v_cmp_ne_u32_e64 s[16:17], 1, v98
	v_mfma_f32_16x16x32_bf16 v[78:81], v[110:113], v[14:17], v[78:81]
	s_cbranch_vccnz .LBB0_1189
	s_lshl_b32 s18, s29, 6
	v_subrev_u32_e32 v106, s18, v146
	v_sub_u32_e32 v107, v106, v20
	v_add_u32_e32 v108, v106, v208
	v_add_u32_e32 v109, -3, v107
	v_add_u32_e32 v110, -2, v107
	v_subrev_u32_e32 v111, 17, v107
	v_add_u32_e32 v112, -16, v107
	v_subrev_u32_e32 v113, 33, v107
	v_subrev_u32_e32 v114, 32, v107
	v_med3_i32 v98, v107, 0, v172
	v_med3_i32 v99, v108, 0, v172
	v_med3_i32 v100, v110, 0, v172
	v_med3_i32 v101, v109, 0, v172
	v_med3_i32 v102, v112, 0, v172
	v_med3_i32 v103, v111, 0, v172
	v_med3_i32 v104, v114, 0, v172
	v_med3_i32 v105, v113, 0, v172
	v_lshl_add_u32 v98, v98, 2, v174
	v_lshl_add_u32 v99, v99, 2, v174
	v_lshl_add_u32 v100, v100, 2, v174
	v_lshl_add_u32 v101, v101, 2, v174
	v_lshl_add_u32 v102, v102, 2, v174
	v_lshl_add_u32 v103, v103, 2, v174
	v_lshl_add_u32 v104, v104, 2, v174
	v_lshl_add_u32 v105, v105, 2, v174
	ds_read_b32 v98, v98
	ds_read_b32 v99, v99
	ds_read_b32 v100, v100
	ds_read_b32 v101, v101
	ds_read_b32 v102, v102
	ds_read_b32 v103, v103
	ds_read_b32 v104, v104
	ds_read_b32 v105, v105
	s_waitcnt lgkmcnt(0)
	v_add_f32_e32 v82, v82, v98
	v_add_f32_e32 v83, v83, v99
	v_cmp_lt_i32_e32 vcc, -1, v108
	v_add_f32_e32 v84, v84, v100
	v_add_f32_e32 v85, v85, v101
	v_sub_u32_e32 v100, v106, v158
	v_cndmask_b32_e32 v83, v173, v83, vcc
	v_cmp_lt_i32_e32 vcc, -1, v107
	v_sub_u32_e32 v101, v106, v1
	v_subrev_u32_e32 v108, 49, v107
	v_cndmask_b32_e32 v82, v173, v82, vcc
	v_cmp_lt_i32_e32 vcc, -1, v109
	v_subrev_u32_e32 v109, 48, v107
	v_add_u32_e32 v115, -16, v100
	v_cndmask_b32_e32 v85, v173, v85, vcc
	v_cmp_lt_i32_e32 vcc, -1, v110
	v_add_u32_e32 v110, -16, v101
	v_subrev_u32_e32 v116, 32, v101
	v_subrev_u32_e32 v117, 32, v100
	v_subrev_u32_e32 v119, 48, v100
	v_med3_i32 v98, v109, 0, v172
	v_med3_i32 v99, v108, 0, v172
	v_med3_i32 v106, v115, 0, v172
	v_med3_i32 v107, v110, 0, v172
	v_add_f32_e32 v86, v86, v102
	v_add_f32_e32 v87, v87, v103
	v_med3_i32 v102, v117, 0, v172
	v_med3_i32 v103, v116, 0, v172
	v_subrev_u32_e32 v118, 48, v101
	v_med3_i32 v100, v119, 0, v172
	v_lshl_add_u32 v98, v98, 2, v174
	v_lshl_add_u32 v99, v99, 2, v174
	v_lshl_add_u32 v106, v106, 2, v174
	v_lshl_add_u32 v107, v107, 2, v174
	v_lshl_add_u32 v102, v102, 2, v174
	v_lshl_add_u32 v103, v103, 2, v174
	v_lshl_add_u32 v120, v100, 2, v174
	v_med3_i32 v100, v118, 0, v172
	v_lshl_add_u32 v121, v100, 2, v174
	ds_read_b32 v98, v98
	ds_read_b32 v99, v99
	ds_read_b32 v100, v106
	ds_read_b32 v101, v107
	ds_read_b32 v102, v102
	ds_read_b32 v103, v103
	ds_read_b32 v106, v120
	ds_read_b32 v107, v121
	v_cndmask_b32_e32 v84, v173, v84, vcc
	s_waitcnt lgkmcnt(0)
	v_add_f32_e32 v88, v88, v100
	v_add_f32_e32 v89, v89, v101
	v_cmp_lt_i32_e32 vcc, -1, v110
	v_add_f32_e32 v92, v92, v102
	v_add_f32_e32 v93, v93, v103
	v_add_f32_e32 v90, v90, v104
	v_add_f32_e32 v91, v91, v105
	v_cndmask_b32_e32 v89, v173, v89, vcc
	v_cmp_lt_i32_e32 vcc, -1, v115
	v_add_f32_e32 v96, v96, v106
	v_add_f32_e32 v97, v97, v107
	v_add_f32_e32 v94, v94, v98
	v_add_f32_e32 v95, v95, v99
	v_cndmask_b32_e32 v88, v173, v88, vcc
	v_cmp_lt_i32_e32 vcc, -1, v111
	s_nop 1
	v_cndmask_b32_e32 v87, v173, v87, vcc
	v_cmp_lt_i32_e32 vcc, -1, v112
	s_nop 1
	v_cndmask_b32_e32 v86, v173, v86, vcc
	v_cmp_lt_i32_e32 vcc, -1, v116
	s_nop 1
	v_cndmask_b32_e32 v93, v173, v93, vcc
	v_cmp_lt_i32_e32 vcc, -1, v117
	s_nop 1
	v_cndmask_b32_e32 v92, v173, v92, vcc
	v_cmp_lt_i32_e32 vcc, -1, v113
	s_nop 1
	v_cndmask_b32_e32 v91, v173, v91, vcc
	v_cmp_lt_i32_e32 vcc, -1, v114
	s_nop 1
	v_cndmask_b32_e32 v90, v173, v90, vcc
	v_cmp_lt_i32_e32 vcc, -1, v118
	s_nop 1
	v_cndmask_b32_e32 v97, v173, v97, vcc
	v_cmp_lt_i32_e32 vcc, -1, v119
	s_nop 1
	v_cndmask_b32_e32 v96, v173, v96, vcc
	v_cmp_lt_i32_e32 vcc, -1, v108
	s_nop 1
	v_cndmask_b32_e32 v95, v173, v95, vcc
	v_cmp_lt_i32_e32 vcc, -1, v109
	s_nop 1
	v_cndmask_b32_e32 v94, v173, v94, vcc

; #define NEG_INF (-__builtin_inff())
; template <bool LUTB, bool WINLO>
; DEV void mask_bias(f32x4 (&s)[4], const AttnCtx& C, int t, int p0, int pstep, bool colok) {
; #pragma unroll
;     for (int kt = 0; kt < 4; ++kt)
; #pragma unroll
;         for (int i = 0; i < 4; ++i) { const int rel = t - (p0 + pstep * (16 * kt + 4 * C.q4 + i));
;             bool ok = colok && rel >= 0; if (WINLO) ok = ok && rel < 512;
;             float v = s[kt][i]; if (LUTB) v += C.lut[C.h * 129 + (rel < 0 ? 0 : (rel < 128 ? rel : 128))];
;             s[kt][i] = ok ? v : NEG_INF; }
; }
.LBB0_1191:
	s_lshl_b32 s10, s29, 6
	v_subrev_u32_e32 v106, s10, v144
	v_sub_u32_e32 v107, v106, v20
	v_add_u32_e32 v108, v106, v208
	v_add_u32_e32 v109, -3, v107
	v_add_u32_e32 v110, -2, v107
	v_subrev_u32_e32 v111, 17, v107
	v_add_u32_e32 v112, -16, v107
	v_subrev_u32_e32 v113, 33, v107
	v_subrev_u32_e32 v114, 32, v107
	v_med3_i32 v98, v107, 0, v172
	v_med3_i32 v99, v108, 0, v172
	v_med3_i32 v100, v110, 0, v172
	v_med3_i32 v101, v109, 0, v172
	v_med3_i32 v102, v112, 0, v172
	v_med3_i32 v103, v111, 0, v172
	v_med3_i32 v104, v114, 0, v172
	v_med3_i32 v105, v113, 0, v172
	v_lshl_add_u32 v98, v98, 2, v174
	v_lshl_add_u32 v99, v99, 2, v174
	v_lshl_add_u32 v100, v100, 2, v174
	v_lshl_add_u32 v101, v101, 2, v174
	v_lshl_add_u32 v102, v102, 2, v174
	v_lshl_add_u32 v103, v103, 2, v174
	v_lshl_add_u32 v104, v104, 2, v174
	v_lshl_add_u32 v105, v105, 2, v174
	ds_read_b32 v98, v98
	ds_read_b32 v99, v99
	ds_read_b32 v100, v100
	ds_read_b32 v101, v101
	ds_read_b32 v102, v102
	ds_read_b32 v103, v103
	ds_read_b32 v104, v104
	ds_read_b32 v105, v105
	s_waitcnt lgkmcnt(0)
	v_add_f32_e32 v66, v66, v98
	v_add_f32_e32 v67, v67, v99
	v_cmp_lt_i32_e32 vcc, -1, v108
	v_add_f32_e32 v68, v68, v100
	v_add_f32_e32 v69, v69, v101
	v_sub_u32_e32 v100, v106, v158
	v_cndmask_b32_e32 v67, v173, v67, vcc
	v_cmp_lt_i32_e32 vcc, -1, v107
	v_sub_u32_e32 v101, v106, v1
	v_subrev_u32_e32 v108, 49, v107
	v_cndmask_b32_e32 v66, v173, v66, vcc
	v_cmp_lt_i32_e32 vcc, -1, v109
	v_subrev_u32_e32 v109, 48, v107
	v_add_u32_e32 v115, -16, v100
	v_cndmask_b32_e32 v69, v173, v69, vcc
	v_cmp_lt_i32_e32 vcc, -1, v110
	v_add_u32_e32 v110, -16, v101
	v_subrev_u32_e32 v116, 32, v101
	v_subrev_u32_e32 v117, 32, v100
	v_subrev_u32_e32 v119, 48, v100
	v_med3_i32 v98, v109, 0, v172
	v_med3_i32 v99, v108, 0, v172
	v_med3_i32 v106, v115, 0, v172
	v_med3_i32 v107, v110, 0, v172
	v_add_f32_e32 v70, v70, v102
	v_add_f32_e32 v71, v71, v103
	v_med3_i32 v102, v117, 0, v172
	v_med3_i32 v103, v116, 0, v172
	v_subrev_u32_e32 v118, 48, v101
	v_med3_i32 v100, v119, 0, v172
	v_lshl_add_u32 v98, v98, 2, v174
	v_lshl_add_u32 v99, v99, 2, v174
	v_lshl_add_u32 v106, v106, 2, v174
	v_lshl_add_u32 v107, v107, 2, v174
	v_lshl_add_u32 v102, v102, 2, v174
	v_lshl_add_u32 v103, v103, 2, v174
	v_lshl_add_u32 v120, v100, 2, v174
	v_med3_i32 v100, v118, 0, v172
	v_lshl_add_u32 v121, v100, 2, v174
	ds_read_b32 v98, v98
	ds_read_b32 v99, v99
	ds_read_b32 v100, v106
	ds_read_b32 v101, v107
	ds_read_b32 v102, v102
	ds_read_b32 v103, v103
	ds_read_b32 v106, v120
	ds_read_b32 v107, v121
	v_cndmask_b32_e32 v68, v173, v68, vcc
	s_waitcnt lgkmcnt(0)
	v_add_f32_e32 v72, v72, v100
	v_add_f32_e32 v73, v73, v101
	v_cmp_lt_i32_e32 vcc, -1, v110
	v_add_f32_e32 v76, v76, v102
	v_add_f32_e32 v77, v77, v103
	v_add_f32_e32 v74, v74, v104
	v_add_f32_e32 v75, v75, v105
	v_cndmask_b32_e32 v73, v173, v73, vcc
	v_cmp_lt_i32_e32 vcc, -1, v115
	v_add_f32_e32 v80, v80, v106
	v_add_f32_e32 v81, v81, v107
	v_add_f32_e32 v78, v78, v98
	v_add_f32_e32 v79, v79, v99
	v_cndmask_b32_e32 v72, v173, v72, vcc
	v_cmp_lt_i32_e32 vcc, -1, v111
	s_nop 1
	v_cndmask_b32_e32 v71, v173, v71, vcc
	v_cmp_lt_i32_e32 vcc, -1, v112
	s_nop 1
	v_cndmask_b32_e32 v70, v173, v70, vcc
	v_cmp_lt_i32_e32 vcc, -1, v116
	s_nop 1
	v_cndmask_b32_e32 v77, v173, v77, vcc
	v_cmp_lt_i32_e32 vcc, -1, v117
	s_nop 1
	v_cndmask_b32_e32 v76, v173, v76, vcc
	v_cmp_lt_i32_e32 vcc, -1, v113
	s_nop 1
	v_cndmask_b32_e32 v75, v173, v75, vcc
	v_cmp_lt_i32_e32 vcc, -1, v114
	s_nop 1
	v_cndmask_b32_e32 v74, v173, v74, vcc
	v_cmp_lt_i32_e32 vcc, -1, v118
	s_nop 1
	v_cndmask_b32_e32 v81, v173, v81, vcc
	v_cmp_lt_i32_e32 vcc, -1, v119
	s_nop 1
	v_cndmask_b32_e32 v80, v173, v80, vcc
	v_cmp_lt_i32_e32 vcc, -1, v108
	s_nop 1
	v_cndmask_b32_e32 v79, v173, v79, vcc
	v_cmp_lt_i32_e32 vcc, -1, v109
	s_nop 1
	v_cndmask_b32_e32 v78, v173, v78, vcc

; #define NEG_INF (-__builtin_inff())
; template <bool LUTB, bool WINLO>
; DEV void mask_bias(f32x4 (&s)[4], const AttnCtx& C, int t, int p0, int pstep, bool colok) {
; #pragma unroll
;     for (int kt = 0; kt < 4; ++kt)
; #pragma unroll
;         for (int i = 0; i < 4; ++i) { const int rel = t - (p0 + pstep * (16 * kt + 4 * C.q4 + i));
;             bool ok = colok && rel >= 0; if (WINLO) ok = ok && rel < 512;
;             float v = s[kt][i]; if (LUTB) v += C.lut[C.h * 129 + (rel < 0 ? 0 : (rel < 128 ? rel : 128))];
;             s[kt][i] = ok ? v : NEG_INF; }
; }
; DEV void attn_unit_mfma(Frame& F, int qg, int kv) {
;     ...
;         const int j = lst[1 + i]; const unsigned byte = (msk[2 * j + (w >> 2)] >> (8 * (w & 3))) & 0xffu;
;         const bool a0 = (byte & 0xfu) != 0u, a1 = (byte & 0xf0u) != 0u;
;         if (a0 || a1) {
;             const bool near = j >= cur - 2; const float bi = near ? 0.f : C.b31;
;             const bool c0 = ((byte >> (C.n >> 2)) & 1u) != 0u, c1 = ((byte >> (4 + (C.n >> 2))) & 1u) != 0u;
;     ...
;             if (a0 && a1) SEL_BODY(true, true); else if (a0) SEL_BODY(true, false); else SEL_BODY(false, true);
.Lmy_orig_1:
	s_and_b32 s9, s8, 15
	s_cmp_eq_u32 s9, 0
	s_cselect_b64 s[12:13], -1, 0
	s_cmp_lg_u32 s9, 0
	s_cselect_b64 s[14:15], -1, 0
	s_and_b32 s9, s8, 0xf0
	s_cmp_lg_u32 s9, 0
	s_cselect_b64 s[16:17], -1, 0
	s_cmp_ge_i32 s29, s22
	s_cselect_b64 s[18:19], -1, 0
	s_cmp_lt_i32 s29, s22
	v_and_b32_e32 v66, s8, v206
	s_cselect_b64 vcc, -1, 0
	v_cmp_ne_u32_e64 s[10:11], 0, v66
	v_and_b32_e32 v66, s8, v207
	s_and_b64 s[16:17], s[14:15], s[16:17]
	v_cndmask_b32_e32 v214, 0, v175, vcc
	v_cmp_ne_u32_e64 s[8:9], 0, v66
	s_mov_b64 s[14:15], -1
	s_and_b64 vcc, exec, s[16:17]
	s_cbranch_vccnz .LBB0_1212
	v_add3_u32 v66, s27, v199, v198
	v_add3_u32 v67, s27, v197, v198
	ds_read_b128 v[70:73], v66 offset:16384
	ds_read_b128 v[74:77], v66 offset:18432
	ds_read_b128 v[90:93], v67 offset:16384
	ds_read_b128 v[78:81], v67 offset:18432
	ds_read_b128 v[82:85], v66 offset:20480
	ds_read_b128 v[86:89], v66 offset:22528
	ds_read_b128 v[94:97], v67 offset:20480
	ds_read_b128 v[66:69], v67 offset:22528
	s_andn2_b64 vcc, exec, s[12:13]
	s_mov_b64 s[12:13], -1
	s_cbranch_vccnz .LBB0_1205
	v_cmp_eq_f32_e64 s[12:13], s3, v212
	s_nop 1
	v_cndmask_b32_e64 v98, v212, 0, s[12:13]
	v_sub_f32_e32 v98, v214, v98
	v_cndmask_b32_e64 v102, v173, v98, s[8:9]
	v_mov_b32_e32 v103, v102
	v_mov_b32_e32 v104, v102
	v_mov_b32_e32 v105, v102
	s_andn2_b64 vcc, exec, s[18:19]
	s_waitcnt lgkmcnt(0)
	v_mfma_f32_16x16x32_bf16 v[98:101], v[70:73], v[10:13], v[102:105]
	v_mfma_f32_16x16x32_bf16 v[110:113], v[90:93], v[14:17], v[98:101]
	v_mfma_f32_16x16x32_bf16 v[98:101], v[74:77], v[10:13], v[102:105]
	v_mfma_f32_16x16x32_bf16 v[106:109], v[78:81], v[14:17], v[98:101]
	v_mfma_f32_16x16x32_bf16 v[98:101], v[82:85], v[10:13], v[102:105]
	v_mfma_f32_16x16x32_bf16 v[102:105], v[86:89], v[10:13], v[102:105]
	v_mfma_f32_16x16x32_bf16 v[98:101], v[94:97], v[14:17], v[98:101]
	v_mfma_f32_16x16x32_bf16 v[102:105], v[66:69], v[14:17], v[102:105]
	s_cbranch_vccnz .LBB0_1202
	s_lshl_b32 s14, s29, 6
	v_subrev_u32_e32 v122, s14, v144
	v_sub_u32_e32 v123, v122, v20
	v_add_u32_e32 v124, v122, v208
	v_add_u32_e32 v125, -3, v123
	v_add_u32_e32 v126, -2, v123
	v_subrev_u32_e32 v127, 17, v123
	v_add_u32_e32 v128, -16, v123
	v_subrev_u32_e32 v129, 33, v123
	v_subrev_u32_e32 v130, 32, v123
	v_med3_i32 v114, v123, 0, v172
	v_med3_i32 v115, v124, 0, v172
	v_med3_i32 v116, v126, 0, v172
	v_med3_i32 v117, v125, 0, v172
	v_med3_i32 v118, v128, 0, v172
	v_med3_i32 v119, v127, 0, v172
	v_med3_i32 v120, v130, 0, v172
	v_med3_i32 v121, v129, 0, v172
	v_lshl_add_u32 v114, v114, 2, v174
	v_lshl_add_u32 v115, v115, 2, v174
	v_lshl_add_u32 v116, v116, 2, v174
	v_lshl_add_u32 v117, v117, 2, v174
	v_lshl_add_u32 v118, v118, 2, v174
	v_lshl_add_u32 v119, v119, 2, v174
	v_lshl_add_u32 v120, v120, 2, v174
	v_lshl_add_u32 v121, v121, 2, v174
	ds_read_b32 v114, v114
	ds_read_b32 v115, v115
	ds_read_b32 v116, v116
	ds_read_b32 v117, v117
	ds_read_b32 v118, v118
	ds_read_b32 v119, v119
	ds_read_b32 v120, v120
	ds_read_b32 v121, v121
	s_waitcnt lgkmcnt(0)
	v_add_f32_e32 v110, v110, v114
	v_add_f32_e32 v111, v111, v115
	v_cmp_lt_i32_e32 vcc, -1, v124
	v_add_f32_e32 v112, v112, v116
	v_add_f32_e32 v113, v113, v117
	v_sub_u32_e32 v116, v122, v158
	v_cndmask_b32_e32 v111, v173, v111, vcc
	v_cmp_lt_i32_e32 vcc, -1, v123
	v_sub_u32_e32 v117, v122, v1
	v_subrev_u32_e32 v124, 49, v123
	v_cndmask_b32_e32 v110, v173, v110, vcc
	v_cmp_lt_i32_e32 vcc, -1, v125
	v_subrev_u32_e32 v125, 48, v123
	v_add_u32_e32 v131, -16, v116
	v_cndmask_b32_e32 v113, v173, v113, vcc
	v_cmp_lt_i32_e32 vcc, -1, v126
	v_add_u32_e32 v126, -16, v117
	v_subrev_u32_e32 v132, 32, v117
	v_subrev_u32_e32 v133, 32, v116
	v_subrev_u32_e32 v135, 48, v116
	v_med3_i32 v114, v125, 0, v172
	v_med3_i32 v115, v124, 0, v172
	v_med3_i32 v122, v131, 0, v172
	v_med3_i32 v123, v126, 0, v172
	v_add_f32_e32 v106, v106, v118
	v_add_f32_e32 v107, v107, v119
	v_med3_i32 v118, v133, 0, v172
	v_med3_i32 v119, v132, 0, v172
	v_subrev_u32_e32 v134, 48, v117
	v_med3_i32 v116, v135, 0, v172
	v_lshl_add_u32 v114, v114, 2, v174
	v_lshl_add_u32 v115, v115, 2, v174
	v_lshl_add_u32 v122, v122, 2, v174
	v_lshl_add_u32 v123, v123, 2, v174
	v_lshl_add_u32 v118, v118, 2, v174
	v_lshl_add_u32 v119, v119, 2, v174
	v_lshl_add_u32 v136, v116, 2, v174
	v_med3_i32 v116, v134, 0, v172
	v_lshl_add_u32 v137, v116, 2, v174
	ds_read_b32 v114, v114
	ds_read_b32 v115, v115
	ds_read_b32 v116, v122
	ds_read_b32 v117, v123
	ds_read_b32 v118, v118
	ds_read_b32 v119, v119
	ds_read_b32 v122, v136
	ds_read_b32 v123, v137
	v_cndmask_b32_e32 v112, v173, v112, vcc
	s_waitcnt lgkmcnt(0)
	v_add_f32_e32 v108, v108, v116
	v_add_f32_e32 v109, v109, v117
	v_cmp_lt_i32_e32 vcc, -1, v126
	v_add_f32_e32 v100, v100, v118
	v_add_f32_e32 v101, v101, v119
	v_add_f32_e32 v98, v98, v120
	v_add_f32_e32 v99, v99, v121
	v_cndmask_b32_e32 v109, v173, v109, vcc
	v_cmp_lt_i32_e32 vcc, -1, v131
	v_add_f32_e32 v104, v104, v122
	v_add_f32_e32 v105, v105, v123
	v_add_f32_e32 v102, v102, v114
	v_add_f32_e32 v103, v103, v115
	v_cndmask_b32_e32 v108, v173, v108, vcc
	v_cmp_lt_i32_e32 vcc, -1, v127
	s_nop 1
	v_cndmask_b32_e32 v107, v173, v107, vcc
	v_cmp_lt_i32_e32 vcc, -1, v128
	s_nop 1
	v_cndmask_b32_e32 v106, v173, v106, vcc
	v_cmp_lt_i32_e32 vcc, -1, v132
	s_nop 1
	v_cndmask_b32_e32 v101, v173, v101, vcc
	v_cmp_lt_i32_e32 vcc, -1, v133
	s_nop 1
	v_cndmask_b32_e32 v100, v173, v100, vcc
	v_cmp_lt_i32_e32 vcc, -1, v129
	s_nop 1
	v_cndmask_b32_e32 v99, v173, v99, vcc
	v_cmp_lt_i32_e32 vcc, -1, v130
	s_nop 1
	v_cndmask_b32_e32 v98, v173, v98, vcc
	v_cmp_lt_i32_e32 vcc, -1, v134
	s_nop 1
	v_cndmask_b32_e32 v105, v173, v105, vcc
	v_cmp_lt_i32_e32 vcc, -1, v135
	s_nop 1
	v_cndmask_b32_e32 v104, v173, v104, vcc
	v_cmp_lt_i32_e32 vcc, -1, v124
	s_nop 1
	v_cndmask_b32_e32 v103, v173, v103, vcc
	v_cmp_lt_i32_e32 vcc, -1, v125
	s_nop 1
	v_cndmask_b32_e32 v102, v173, v102, vcc

; #define NEG_INF (-__builtin_inff())
; template <bool LUTB, bool WINLO>
; DEV void mask_bias(f32x4 (&s)[4], const AttnCtx& C, int t, int p0, int pstep, bool colok) {
; #pragma unroll
;     for (int kt = 0; kt < 4; ++kt)
; #pragma unroll
;         for (int i = 0; i < 4; ++i) { const int rel = t - (p0 + pstep * (16 * kt + 4 * C.q4 + i));
;             bool ok = colok && rel >= 0; if (WINLO) ok = ok && rel < 512;
;             float v = s[kt][i]; if (LUTB) v += C.lut[C.h * 129 + (rel < 0 ? 0 : (rel < 128 ? rel : 128))];
;             s[kt][i] = ok ? v : NEG_INF; }
; }
; DEV void attn_unit_mfma(Frame& F, int qg, int kv) {
;     ...
;             if (a0 && a1) SEL_BODY(true, true); else if (a0) SEL_BODY(true, false); else SEL_BODY(false, true);
.LBB0_1205:
	v_mov_b64_e32 v[136:137], v[60:61]
	s_nop 1
	v_mov_b64_e32 v[112:113], v[64:65]
	v_mov_b64_e32 v[124:125], v[56:57]
	v_mov_b64_e32 v[128:129], v[52:53]
	v_mov_b64_e32 v[132:133], v[48:49]
	s_and_b64 vcc, exec, s[12:13]
	v_mov_b32_e32 v215, v213
	v_mov_b64_e32 v[134:135], v[58:59]
	v_mov_b64_e32 v[110:111], v[62:63]
	v_mov_b64_e32 v[122:123], v[54:55]
	v_mov_b64_e32 v[126:127], v[50:51]
	v_mov_b64_e32 v[130:131], v[46:47]
	s_cbranch_vccz .LBB0_1211
	v_cmp_eq_f32_e64 s[12:13], s3, v213
	s_nop 1
	v_cndmask_b32_e64 v98, v213, 0, s[12:13]
	v_sub_f32_e32 v98, v214, v98
	v_cndmask_b32_e64 v98, v173, v98, s[10:11]
	v_mov_b32_e32 v99, v98
	v_mov_b32_e32 v100, v98
	v_mov_b32_e32 v101, v98
	s_andn2_b64 vcc, exec, s[18:19]
	s_waitcnt lgkmcnt(0)
	v_mfma_f32_16x16x32_bf16 v[70:73], v[70:73], v[2:5], v[98:101]
	v_mfma_f32_16x16x32_bf16 v[90:93], v[90:93], v[6:9], v[70:73]
	v_mfma_f32_16x16x32_bf16 v[70:73], v[74:77], v[2:5], v[98:101]
	v_mfma_f32_16x16x32_bf16 v[74:77], v[78:81], v[6:9], v[70:73]
	v_mfma_f32_16x16x32_bf16 v[70:73], v[82:85], v[2:5], v[98:101]
	v_mfma_f32_16x16x32_bf16 v[78:81], v[86:89], v[2:5], v[98:101]
	v_mfma_f32_16x16x32_bf16 v[70:73], v[94:97], v[6:9], v[70:73]
	v_mfma_f32_16x16x32_bf16 v[66:69], v[66:69], v[6:9], v[78:81]
	s_cbranch_vccnz .LBB0_1208
	s_lshl_b32 s14, s29, 6
	v_subrev_u32_e32 v86, s14, v146
	v_sub_u32_e32 v87, v86, v20
	v_add_u32_e32 v88, v86, v208
	v_add_u32_e32 v89, -3, v87
	v_add_u32_e32 v94, -2, v87
	v_subrev_u32_e32 v95, 17, v87
	v_add_u32_e32 v96, -16, v87
	v_subrev_u32_e32 v97, 33, v87
	v_subrev_u32_e32 v98, 32, v87
	v_med3_i32 v78, v87, 0, v172
	v_med3_i32 v79, v88, 0, v172
	v_med3_i32 v80, v94, 0, v172
	v_med3_i32 v81, v89, 0, v172
	v_med3_i32 v82, v96, 0, v172
	v_med3_i32 v83, v95, 0, v172
	v_med3_i32 v84, v98, 0, v172
	v_med3_i32 v85, v97, 0, v172
	v_lshl_add_u32 v78, v78, 2, v174
	v_lshl_add_u32 v79, v79, 2, v174
	v_lshl_add_u32 v80, v80, 2, v174
	v_lshl_add_u32 v81, v81, 2, v174
	v_lshl_add_u32 v82, v82, 2, v174
	v_lshl_add_u32 v83, v83, 2, v174
	v_lshl_add_u32 v84, v84, 2, v174
	v_lshl_add_u32 v85, v85, 2, v174
	ds_read_b32 v78, v78
	ds_read_b32 v79, v79
	ds_read_b32 v80, v80
	ds_read_b32 v81, v81
	ds_read_b32 v82, v82
	ds_read_b32 v83, v83
	ds_read_b32 v84, v84
	ds_read_b32 v85, v85
	s_waitcnt lgkmcnt(0)
	v_add_f32_e32 v78, v90, v78
	v_add_f32_e32 v79, v91, v79
	v_cmp_lt_i32_e32 vcc, -1, v88
	v_add_f32_e32 v80, v92, v80
	v_add_f32_e32 v81, v93, v81
	v_subrev_u32_e32 v88, 49, v87
	v_cndmask_b32_e32 v91, v173, v79, vcc
	v_cmp_lt_i32_e32 vcc, -1, v87
	v_med3_i32 v79, v88, 0, v172
	v_add_f32_e32 v74, v74, v82
	v_add_f32_e32 v75, v75, v83
	v_cndmask_b32_e32 v90, v173, v78, vcc
	v_cmp_lt_i32_e32 vcc, -1, v89
	v_subrev_u32_e32 v89, 48, v87
	v_med3_i32 v78, v89, 0, v172
	v_cndmask_b32_e32 v93, v173, v81, vcc
	v_cmp_lt_i32_e32 vcc, -1, v94
	v_sub_u32_e32 v81, v86, v1
	v_add_u32_e32 v94, -16, v81
	v_cndmask_b32_e32 v92, v173, v80, vcc
	v_sub_u32_e32 v80, v86, v158
	v_add_u32_e32 v99, -16, v80
	v_subrev_u32_e32 v100, 32, v81
	v_subrev_u32_e32 v101, 32, v80
	v_subrev_u32_e32 v103, 48, v80
	v_med3_i32 v86, v99, 0, v172
	v_med3_i32 v87, v94, 0, v172
	v_med3_i32 v82, v101, 0, v172
	v_med3_i32 v83, v100, 0, v172
	v_subrev_u32_e32 v102, 48, v81
	v_med3_i32 v80, v103, 0, v172
	v_lshl_add_u32 v78, v78, 2, v174
	v_lshl_add_u32 v79, v79, 2, v174
	v_lshl_add_u32 v86, v86, 2, v174
	v_lshl_add_u32 v87, v87, 2, v174
	v_lshl_add_u32 v82, v82, 2, v174
	v_lshl_add_u32 v83, v83, 2, v174
	v_lshl_add_u32 v104, v80, 2, v174
	v_med3_i32 v80, v102, 0, v172
	v_lshl_add_u32 v105, v80, 2, v174
	ds_read_b32 v78, v78
	ds_read_b32 v79, v79
	ds_read_b32 v80, v86
	ds_read_b32 v81, v87
	ds_read_b32 v82, v82
	ds_read_b32 v83, v83
	ds_read_b32 v86, v104
	ds_read_b32 v87, v105
	s_waitcnt lgkmcnt(0)
	v_add_f32_e32 v76, v76, v80
	v_add_f32_e32 v77, v77, v81
	v_cmp_lt_i32_e32 vcc, -1, v94
	v_add_f32_e32 v72, v72, v82
	v_add_f32_e32 v73, v73, v83
	v_add_f32_e32 v70, v70, v84
	v_add_f32_e32 v71, v71, v85
	v_cndmask_b32_e32 v77, v173, v77, vcc
	v_cmp_lt_i32_e32 vcc, -1, v99
	v_add_f32_e32 v68, v68, v86
	v_add_f32_e32 v69, v69, v87
	v_add_f32_e32 v66, v66, v78
	v_add_f32_e32 v67, v67, v79
	v_cndmask_b32_e32 v76, v173, v76, vcc
	v_cmp_lt_i32_e32 vcc, -1, v95
	s_nop 1
	v_cndmask_b32_e32 v75, v173, v75, vcc
	v_cmp_lt_i32_e32 vcc, -1, v96
	s_nop 1
	v_cndmask_b32_e32 v74, v173, v74, vcc
	v_cmp_lt_i32_e32 vcc, -1, v100
	s_nop 1
	v_cndmask_b32_e32 v73, v173, v73, vcc
	v_cmp_lt_i32_e32 vcc, -1, v101
	s_nop 1
	v_cndmask_b32_e32 v72, v173, v72, vcc
	v_cmp_lt_i32_e32 vcc, -1, v97
	s_nop 1
	v_cndmask_b32_e32 v71, v173, v71, vcc
	v_cmp_lt_i32_e32 vcc, -1, v98
	s_nop 1
	v_cndmask_b32_e32 v70, v173, v70, vcc
	v_cmp_lt_i32_e32 vcc, -1, v102
	s_nop 1
	v_cndmask_b32_e32 v69, v173, v69, vcc
	v_cmp_lt_i32_e32 vcc, -1, v103
	s_nop 1
	v_cndmask_b32_e32 v68, v173, v68, vcc
	v_cmp_lt_i32_e32 vcc, -1, v88
	s_nop 1
	v_cndmask_b32_e32 v67, v173, v67, vcc
	v_cmp_lt_i32_e32 vcc, -1, v89
	s_nop 1
	v_cndmask_b32_e32 v66, v173, v66, vcc

; #define NEG_INF (-__builtin_inff())
; template <bool LUTB, bool WINLO>
; DEV void mask_bias(f32x4 (&s)[4], const AttnCtx& C, int t, int p0, int pstep, bool colok) {
; #pragma unroll
;     for (int kt = 0; kt < 4; ++kt)
; #pragma unroll
;         for (int i = 0; i < 4; ++i) { const int rel = t - (p0 + pstep * (16 * kt + 4 * C.q4 + i));
;             bool ok = colok && rel >= 0; if (WINLO) ok = ok && rel < 512;
;             float v = s[kt][i]; if (LUTB) v += C.lut[C.h * 129 + (rel < 0 ? 0 : (rel < 128 ? rel : 128))];
;             s[kt][i] = ok ? v : NEG_INF; }
; }
; DEV void attn_unit_mfma(Frame& F, int qg, int kv) {
;     ...
;             if (a0 && a1) SEL_BODY(true, true); else if (a0) SEL_BODY(true, false); else SEL_BODY(false, true);
.LBB0_1212:
	s_andn2_b64 vcc, exec, s[14:15]
	s_cbranch_vccnz .LBB0_1221
	v_cmp_eq_f32_e64 s[14:15], s3, v213
	v_cmp_eq_f32_e64 s[12:13], s3, v212
	s_waitcnt lgkmcnt(0)
	v_add3_u32 v79, s27, v199, v198
	v_cndmask_b32_e64 v66, v213, 0, s[14:15]
	v_sub_f32_e32 v66, v214, v66
	v_cndmask_b32_e64 v78, v173, v66, s[10:11]
	v_cndmask_b32_e64 v66, v212, 0, s[12:13]
	v_sub_f32_e32 v66, v214, v66
	v_add3_u32 v80, s27, v197, v198
	v_cndmask_b32_e64 v98, v173, v66, s[8:9]
	ds_read_b128 v[66:69], v79 offset:16384
	ds_read_b128 v[70:73], v80 offset:16384
	ds_read_b128 v[74:77], v79 offset:18432
	ds_read_b128 v[90:93], v80 offset:18432
	ds_read_b128 v[94:97], v79 offset:20480
	ds_read_b128 v[102:105], v80 offset:20480
	ds_read_b128 v[106:109], v79 offset:22528
	ds_read_b128 v[110:113], v80 offset:22528
	v_mov_b32_e32 v79, v78
	v_mov_b32_e32 v80, v78
	v_mov_b32_e32 v81, v78
	v_mov_b32_e32 v99, v98
	v_mov_b32_e32 v100, v98
	v_mov_b32_e32 v101, v98
	s_waitcnt lgkmcnt(0)
	v_mfma_f32_16x16x32_bf16 v[82:85], v[66:69], v[2:5], v[78:81]
	s_andn2_b64 vcc, exec, s[18:19]
	v_mfma_f32_16x16x32_bf16 v[66:69], v[66:69], v[10:13], v[98:101]
	v_mfma_f32_16x16x32_bf16 v[82:85], v[70:73], v[6:9], v[82:85]
	v_mfma_f32_16x16x32_bf16 v[66:69], v[70:73], v[14:17], v[66:69]
	v_mfma_f32_16x16x32_bf16 v[70:73], v[74:77], v[2:5], v[78:81]
	v_mfma_f32_16x16x32_bf16 v[86:89], v[90:93], v[6:9], v[70:73]
	v_mfma_f32_16x16x32_bf16 v[70:73], v[74:77], v[10:13], v[98:101]
	v_mfma_f32_16x16x32_bf16 v[74:77], v[94:97], v[2:5], v[78:81]
	v_mfma_f32_16x16x32_bf16 v[78:81], v[106:109], v[2:5], v[78:81]
	v_mfma_f32_16x16x32_bf16 v[70:73], v[90:93], v[14:17], v[70:73]
	v_mfma_f32_16x16x32_bf16 v[90:93], v[102:105], v[6:9], v[74:77]
	v_mfma_f32_16x16x32_bf16 v[74:77], v[94:97], v[10:13], v[98:101]
	v_mfma_f32_16x16x32_bf16 v[94:97], v[110:113], v[6:9], v[78:81]
	v_mfma_f32_16x16x32_bf16 v[78:81], v[106:109], v[10:13], v[98:101]
	v_mfma_f32_16x16x32_bf16 v[74:77], v[102:105], v[14:17], v[74:77]
	s_nop 1
	v_cndmask_b32_e64 v98, 0, 1, s[18:19]
	v_cmp_ne_u32_e64 s[16:17], 1, v98
	v_mfma_f32_16x16x32_bf16 v[78:81], v[110:113], v[14:17], v[78:81]
	s_cbranch_vccnz .LBB0_1215
	s_lshl_b32 s18, s29, 6
	v_subrev_u32_e32 v106, s18, v146
	v_sub_u32_e32 v107, v106, v20
	v_add_u32_e32 v108, v106, v208
	v_add_u32_e32 v109, -3, v107
	v_add_u32_e32 v110, -2, v107
	v_subrev_u32_e32 v111, 17, v107
	v_add_u32_e32 v112, -16, v107
	v_subrev_u32_e32 v113, 33, v107
	v_subrev_u32_e32 v114, 32, v107
	v_med3_i32 v98, v107, 0, v172
	v_med3_i32 v99, v108, 0, v172
	v_med3_i32 v100, v110, 0, v172
	v_med3_i32 v101, v109, 0, v172
	v_med3_i32 v102, v112, 0, v172
	v_med3_i32 v103, v111, 0, v172
	v_med3_i32 v104, v114, 0, v172
	v_med3_i32 v105, v113, 0, v172
	v_lshl_add_u32 v98, v98, 2, v174
	v_lshl_add_u32 v99, v99, 2, v174
	v_lshl_add_u32 v100, v100, 2, v174
	v_lshl_add_u32 v101, v101, 2, v174
	v_lshl_add_u32 v102, v102, 2, v174
	v_lshl_add_u32 v103, v103, 2, v174
	v_lshl_add_u32 v104, v104, 2, v174
	v_lshl_add_u32 v105, v105, 2, v174
	ds_read_b32 v98, v98
	ds_read_b32 v99, v99
	ds_read_b32 v100, v100
	ds_read_b32 v101, v101
	ds_read_b32 v102, v102
	ds_read_b32 v103, v103
	ds_read_b32 v104, v104
	ds_read_b32 v105, v105
	s_waitcnt lgkmcnt(0)
	v_add_f32_e32 v82, v82, v98
	v_add_f32_e32 v83, v83, v99
	v_cmp_lt_i32_e32 vcc, -1, v108
	v_add_f32_e32 v84, v84, v100
	v_add_f32_e32 v85, v85, v101
	v_sub_u32_e32 v100, v106, v158
	v_cndmask_b32_e32 v83, v173, v83, vcc
	v_cmp_lt_i32_e32 vcc, -1, v107
	v_sub_u32_e32 v101, v106, v1
	v_subrev_u32_e32 v108, 49, v107
	v_cndmask_b32_e32 v82, v173, v82, vcc
	v_cmp_lt_i32_e32 vcc, -1, v109
	v_subrev_u32_e32 v109, 48, v107
	v_add_u32_e32 v115, -16, v100
	v_cndmask_b32_e32 v85, v173, v85, vcc
	v_cmp_lt_i32_e32 vcc, -1, v110
	v_add_u32_e32 v110, -16, v101
	v_subrev_u32_e32 v116, 32, v101
	v_subrev_u32_e32 v117, 32, v100
	v_subrev_u32_e32 v119, 48, v100
	v_med3_i32 v98, v109, 0, v172
	v_med3_i32 v99, v108, 0, v172
	v_med3_i32 v106, v115, 0, v172
	v_med3_i32 v107, v110, 0, v172
	v_add_f32_e32 v86, v86, v102
	v_add_f32_e32 v87, v87, v103
	v_med3_i32 v102, v117, 0, v172
	v_med3_i32 v103, v116, 0, v172
	v_subrev_u32_e32 v118, 48, v101
	v_med3_i32 v100, v119, 0, v172
	v_lshl_add_u32 v98, v98, 2, v174
	v_lshl_add_u32 v99, v99, 2, v174
	v_lshl_add_u32 v106, v106, 2, v174
	v_lshl_add_u32 v107, v107, 2, v174
	v_lshl_add_u32 v102, v102, 2, v174
	v_lshl_add_u32 v103, v103, 2, v174
	v_lshl_add_u32 v120, v100, 2, v174
	v_med3_i32 v100, v118, 0, v172
	v_lshl_add_u32 v121, v100, 2, v174
	ds_read_b32 v98, v98
	ds_read_b32 v99, v99
	ds_read_b32 v100, v106
	ds_read_b32 v101, v107
	ds_read_b32 v102, v102
	ds_read_b32 v103, v103
	ds_read_b32 v106, v120
	ds_read_b32 v107, v121
	v_cndmask_b32_e32 v84, v173, v84, vcc
	s_waitcnt lgkmcnt(0)
	v_add_f32_e32 v88, v88, v100
	v_add_f32_e32 v89, v89, v101
	v_cmp_lt_i32_e32 vcc, -1, v110
	v_add_f32_e32 v92, v92, v102
	v_add_f32_e32 v93, v93, v103
	v_add_f32_e32 v90, v90, v104
	v_add_f32_e32 v91, v91, v105
	v_cndmask_b32_e32 v89, v173, v89, vcc
	v_cmp_lt_i32_e32 vcc, -1, v115
	v_add_f32_e32 v96, v96, v106
	v_add_f32_e32 v97, v97, v107
	v_add_f32_e32 v94, v94, v98
	v_add_f32_e32 v95, v95, v99
	v_cndmask_b32_e32 v88, v173, v88, vcc
	v_cmp_lt_i32_e32 vcc, -1, v111
	s_nop 1
	v_cndmask_b32_e32 v87, v173, v87, vcc
	v_cmp_lt_i32_e32 vcc, -1, v112
	s_nop 1
	v_cndmask_b32_e32 v86, v173, v86, vcc
	v_cmp_lt_i32_e32 vcc, -1, v116
	s_nop 1
	v_cndmask_b32_e32 v93, v173, v93, vcc
	v_cmp_lt_i32_e32 vcc, -1, v117
	s_nop 1
	v_cndmask_b32_e32 v92, v173, v92, vcc
	v_cmp_lt_i32_e32 vcc, -1, v113
	s_nop 1
	v_cndmask_b32_e32 v91, v173, v91, vcc
	v_cmp_lt_i32_e32 vcc, -1, v114
	s_nop 1
	v_cndmask_b32_e32 v90, v173, v90, vcc
	v_cmp_lt_i32_e32 vcc, -1, v118
	s_nop 1
	v_cndmask_b32_e32 v97, v173, v97, vcc
	v_cmp_lt_i32_e32 vcc, -1, v119
	s_nop 1
	v_cndmask_b32_e32 v96, v173, v96, vcc
	v_cmp_lt_i32_e32 vcc, -1, v108
	s_nop 1
	v_cndmask_b32_e32 v95, v173, v95, vcc
	v_cmp_lt_i32_e32 vcc, -1, v109
	s_nop 1
	v_cndmask_b32_e32 v94, v173, v94, vcc

; #define NEG_INF (-__builtin_inff())
; template <bool LUTB, bool WINLO>
; DEV void mask_bias(f32x4 (&s)[4], const AttnCtx& C, int t, int p0, int pstep, bool colok) {
; #pragma unroll
;     for (int kt = 0; kt < 4; ++kt)
; #pragma unroll
;         for (int i = 0; i < 4; ++i) { const int rel = t - (p0 + pstep * (16 * kt + 4 * C.q4 + i));
;             bool ok = colok && rel >= 0; if (WINLO) ok = ok && rel < 512;
;             float v = s[kt][i]; if (LUTB) v += C.lut[C.h * 129 + (rel < 0 ? 0 : (rel < 128 ? rel : 128))];
;             s[kt][i] = ok ? v : NEG_INF; }
; }
; DEV void attn_unit_mfma(Frame& F, int qg, int kv) {
;     ...
;         const int j = lst[1 + i]; const unsigned byte = (msk[2 * j + (w >> 2)] >> (8 * (w & 3))) & 0xffu;
;         const bool a0 = (byte & 0xfu) != 0u, a1 = (byte & 0xf0u) != 0u;
;         if (a0 || a1) {
;             const bool near = j >= cur - 2; const float bi = near ? 0.f : C.b31;
;             const bool c0 = ((byte >> (C.n >> 2)) & 1u) != 0u, c1 = ((byte >> (4 + (C.n >> 2))) & 1u) != 0u;
;     ...
;             if (a0 && a1) SEL_BODY(true, true); else if (a0) SEL_BODY(true, false); else SEL_BODY(false, true);
.Lmy_orig_2:
	s_and_b32 s9, s8, 15
	s_cmp_eq_u32 s9, 0
	s_cselect_b64 s[14:15], -1, 0
	s_cmp_lg_u32 s9, 0
	s_cselect_b64 s[12:13], -1, 0
	s_and_b32 s9, s8, 0xf0
	s_cmp_lg_u32 s9, 0
	s_cselect_b64 s[16:17], -1, 0
	s_cmp_ge_i32 s28, s22
	s_cselect_b64 s[18:19], -1, 0
	s_cmp_lt_i32 s28, s22
	v_and_b32_e32 v66, s8, v206
	s_cselect_b64 vcc, -1, 0
	v_cmp_ne_u32_e64 s[10:11], 0, v66
	v_and_b32_e32 v66, s8, v207
	s_and_b64 s[16:17], s[12:13], s[16:17]
	v_cndmask_b32_e32 v216, 0, v175, vcc
	v_cmp_ne_u32_e64 s[8:9], 0, v66
	s_mov_b64 s[12:13], -1
	s_and_b64 vcc, exec, s[16:17]
	v_add3_u32 v215, s27, v199, v198
	v_add3_u32 v214, s27, v197, v198
	s_cbranch_vccnz .LBB0_1238
	ds_read_b128 v[70:73], v215 offset:32768
	ds_read_b128 v[74:77], v215 offset:34816
	ds_read_b128 v[90:93], v214 offset:32768
	ds_read_b128 v[78:81], v214 offset:34816
	ds_read_b128 v[82:85], v215 offset:36864
	ds_read_b128 v[86:89], v215 offset:38912
	ds_read_b128 v[94:97], v214 offset:36864
	ds_read_b128 v[66:69], v214 offset:38912
	s_andn2_b64 vcc, exec, s[14:15]
	s_cbranch_vccnz .LBB0_1231
	v_cmp_eq_f32_e64 s[12:13], s3, v212
	s_nop 1
	v_cndmask_b32_e64 v98, v212, 0, s[12:13]
	v_sub_f32_e32 v98, v216, v98
	v_cndmask_b32_e64 v102, v173, v98, s[8:9]
	v_mov_b32_e32 v103, v102
	v_mov_b32_e32 v104, v102
	v_mov_b32_e32 v105, v102
	s_andn2_b64 vcc, exec, s[18:19]
	s_waitcnt lgkmcnt(0)
	v_mfma_f32_16x16x32_bf16 v[98:101], v[70:73], v[10:13], v[102:105]
	v_mfma_f32_16x16x32_bf16 v[110:113], v[90:93], v[14:17], v[98:101]
	v_mfma_f32_16x16x32_bf16 v[98:101], v[74:77], v[10:13], v[102:105]
	v_mfma_f32_16x16x32_bf16 v[106:109], v[78:81], v[14:17], v[98:101]
	v_mfma_f32_16x16x32_bf16 v[98:101], v[82:85], v[10:13], v[102:105]
	v_mfma_f32_16x16x32_bf16 v[102:105], v[86:89], v[10:13], v[102:105]
	v_mfma_f32_16x16x32_bf16 v[98:101], v[94:97], v[14:17], v[98:101]
	v_mfma_f32_16x16x32_bf16 v[102:105], v[66:69], v[14:17], v[102:105]
	s_cbranch_vccnz .LBB0_1228
	s_lshl_b32 s14, s28, 6
	v_subrev_u32_e32 v122, s14, v144
	v_sub_u32_e32 v123, v122, v20
	v_add_u32_e32 v124, v122, v208
	v_add_u32_e32 v125, -3, v123
	v_add_u32_e32 v126, -2, v123
	v_subrev_u32_e32 v127, 17, v123
	v_add_u32_e32 v128, -16, v123
	v_subrev_u32_e32 v129, 33, v123
	v_subrev_u32_e32 v130, 32, v123
	v_med3_i32 v114, v123, 0, v172
	v_med3_i32 v115, v124, 0, v172
	v_med3_i32 v116, v126, 0, v172
	v_med3_i32 v117, v125, 0, v172
	v_med3_i32 v118, v128, 0, v172
	v_med3_i32 v119, v127, 0, v172
	v_med3_i32 v120, v130, 0, v172
	v_med3_i32 v121, v129, 0, v172
	v_lshl_add_u32 v114, v114, 2, v174
	v_lshl_add_u32 v115, v115, 2, v174
	v_lshl_add_u32 v116, v116, 2, v174
	v_lshl_add_u32 v117, v117, 2, v174
	v_lshl_add_u32 v118, v118, 2, v174
	v_lshl_add_u32 v119, v119, 2, v174
	v_lshl_add_u32 v120, v120, 2, v174
	v_lshl_add_u32 v121, v121, 2, v174
	ds_read_b32 v114, v114
	ds_read_b32 v115, v115
	ds_read_b32 v116, v116
	ds_read_b32 v117, v117
	ds_read_b32 v118, v118
	ds_read_b32 v119, v119
	ds_read_b32 v120, v120
	ds_read_b32 v121, v121
	s_waitcnt lgkmcnt(0)
	v_add_f32_e32 v110, v110, v114
	v_add_f32_e32 v111, v111, v115
	v_cmp_lt_i32_e32 vcc, -1, v124
	v_add_f32_e32 v112, v112, v116
	v_add_f32_e32 v113, v113, v117
	v_sub_u32_e32 v116, v122, v158
	v_cndmask_b32_e32 v111, v173, v111, vcc
	v_cmp_lt_i32_e32 vcc, -1, v123
	v_sub_u32_e32 v117, v122, v1
	v_subrev_u32_e32 v124, 49, v123
	v_cndmask_b32_e32 v110, v173, v110, vcc
	v_cmp_lt_i32_e32 vcc, -1, v125
	v_subrev_u32_e32 v125, 48, v123
	v_add_u32_e32 v131, -16, v116
	v_cndmask_b32_e32 v113, v173, v113, vcc
	v_cmp_lt_i32_e32 vcc, -1, v126
	v_add_u32_e32 v126, -16, v117
	v_subrev_u32_e32 v132, 32, v117
	v_subrev_u32_e32 v133, 32, v116
	v_subrev_u32_e32 v135, 48, v116
	v_med3_i32 v114, v125, 0, v172
	v_med3_i32 v115, v124, 0, v172
	v_med3_i32 v122, v131, 0, v172
	v_med3_i32 v123, v126, 0, v172
	v_add_f32_e32 v106, v106, v118
	v_add_f32_e32 v107, v107, v119
	v_med3_i32 v118, v133, 0, v172
	v_med3_i32 v119, v132, 0, v172
	v_subrev_u32_e32 v134, 48, v117
	v_med3_i32 v116, v135, 0, v172
	v_lshl_add_u32 v114, v114, 2, v174
	v_lshl_add_u32 v115, v115, 2, v174
	v_lshl_add_u32 v122, v122, 2, v174
	v_lshl_add_u32 v123, v123, 2, v174
	v_lshl_add_u32 v118, v118, 2, v174
	v_lshl_add_u32 v119, v119, 2, v174
	v_lshl_add_u32 v136, v116, 2, v174
	v_med3_i32 v116, v134, 0, v172
	v_lshl_add_u32 v137, v116, 2, v174
	ds_read_b32 v114, v114
	ds_read_b32 v115, v115
	ds_read_b32 v116, v122
	ds_read_b32 v117, v123
	ds_read_b32 v118, v118
	ds_read_b32 v119, v119
	ds_read_b32 v122, v136
	ds_read_b32 v123, v137
	v_cndmask_b32_e32 v112, v173, v112, vcc
	s_waitcnt lgkmcnt(0)
	v_add_f32_e32 v108, v108, v116
	v_add_f32_e32 v109, v109, v117
	v_cmp_lt_i32_e32 vcc, -1, v126
	v_add_f32_e32 v100, v100, v118
	v_add_f32_e32 v101, v101, v119
	v_add_f32_e32 v98, v98, v120
	v_add_f32_e32 v99, v99, v121
	v_cndmask_b32_e32 v109, v173, v109, vcc
	v_cmp_lt_i32_e32 vcc, -1, v131
	v_add_f32_e32 v104, v104, v122
	v_add_f32_e32 v105, v105, v123
	v_add_f32_e32 v102, v102, v114
	v_add_f32_e32 v103, v103, v115
	v_cndmask_b32_e32 v108, v173, v108, vcc
	v_cmp_lt_i32_e32 vcc, -1, v127
	s_nop 1
	v_cndmask_b32_e32 v107, v173, v107, vcc
	v_cmp_lt_i32_e32 vcc, -1, v128
	s_nop 1
	v_cndmask_b32_e32 v106, v173, v106, vcc
	v_cmp_lt_i32_e32 vcc, -1, v132
	s_nop 1
	v_cndmask_b32_e32 v101, v173, v101, vcc
	v_cmp_lt_i32_e32 vcc, -1, v133
	s_nop 1
	v_cndmask_b32_e32 v100, v173, v100, vcc
	v_cmp_lt_i32_e32 vcc, -1, v129
	s_nop 1
	v_cndmask_b32_e32 v99, v173, v99, vcc
	v_cmp_lt_i32_e32 vcc, -1, v130
	s_nop 1
	v_cndmask_b32_e32 v98, v173, v98, vcc
	v_cmp_lt_i32_e32 vcc, -1, v134
	s_nop 1
	v_cndmask_b32_e32 v105, v173, v105, vcc
	v_cmp_lt_i32_e32 vcc, -1, v135
	s_nop 1
	v_cndmask_b32_e32 v104, v173, v104, vcc
	v_cmp_lt_i32_e32 vcc, -1, v124
	s_nop 1
	v_cndmask_b32_e32 v103, v173, v103, vcc
	v_cmp_lt_i32_e32 vcc, -1, v125
	s_nop 1
	v_cndmask_b32_e32 v102, v173, v102, vcc

; #define NEG_INF (-__builtin_inff())
; template <bool LUTB, bool WINLO>
; DEV void mask_bias(f32x4 (&s)[4], const AttnCtx& C, int t, int p0, int pstep, bool colok) {
; #pragma unroll
;     for (int kt = 0; kt < 4; ++kt)
; #pragma unroll
;         for (int i = 0; i < 4; ++i) { const int rel = t - (p0 + pstep * (16 * kt + 4 * C.q4 + i));
;             bool ok = colok && rel >= 0; if (WINLO) ok = ok && rel < 512;
;             float v = s[kt][i]; if (LUTB) v += C.lut[C.h * 129 + (rel < 0 ? 0 : (rel < 128 ? rel : 128))];
;             s[kt][i] = ok ? v : NEG_INF; }
; }
; DEV void attn_unit_mfma(Frame& F, int qg, int kv) {
;     ...
;         const int j = lst[1 + i]; const unsigned byte = (msk[2 * j + (w >> 2)] >> (8 * (w & 3))) & 0xffu;
;         const bool a0 = (byte & 0xfu) != 0u, a1 = (byte & 0xf0u) != 0u;
;         if (a0 || a1) {
;             const bool near = j >= cur - 2; const float bi = near ? 0.f : C.b31;
;             const bool c0 = ((byte >> (C.n >> 2)) & 1u) != 0u, c1 = ((byte >> (4 + (C.n >> 2))) & 1u) != 0u;
;     ...
;             if (a0 && a1) SEL_BODY(true, true); else if (a0) SEL_BODY(true, false); else SEL_BODY(false, true);
.LBB0_1231:
	v_mov_b64_e32 v[136:137], v[60:61]
	s_nop 1
	v_mov_b64_e32 v[112:113], v[64:65]
	v_mov_b64_e32 v[124:125], v[56:57]
	v_mov_b64_e32 v[128:129], v[52:53]
	v_mov_b64_e32 v[132:133], v[48:49]
	s_and_b64 vcc, exec, s[12:13]
	v_mov_b32_e32 v217, v213
	v_mov_b64_e32 v[134:135], v[58:59]
	v_mov_b64_e32 v[110:111], v[62:63]
	v_mov_b64_e32 v[122:123], v[54:55]
	v_mov_b64_e32 v[126:127], v[50:51]
	v_mov_b64_e32 v[130:131], v[46:47]
	s_cbranch_vccz .LBB0_1237
	v_cmp_eq_f32_e64 s[12:13], s3, v213
	s_nop 1
	v_cndmask_b32_e64 v98, v213, 0, s[12:13]
	v_sub_f32_e32 v98, v216, v98
	v_cndmask_b32_e64 v98, v173, v98, s[10:11]
	v_mov_b32_e32 v99, v98
	v_mov_b32_e32 v100, v98
	v_mov_b32_e32 v101, v98
	s_andn2_b64 vcc, exec, s[18:19]
	s_waitcnt lgkmcnt(0)
	v_mfma_f32_16x16x32_bf16 v[70:73], v[70:73], v[2:5], v[98:101]
	v_mfma_f32_16x16x32_bf16 v[90:93], v[90:93], v[6:9], v[70:73]
	v_mfma_f32_16x16x32_bf16 v[70:73], v[74:77], v[2:5], v[98:101]
	v_mfma_f32_16x16x32_bf16 v[74:77], v[78:81], v[6:9], v[70:73]
	v_mfma_f32_16x16x32_bf16 v[70:73], v[82:85], v[2:5], v[98:101]
	v_mfma_f32_16x16x32_bf16 v[78:81], v[86:89], v[2:5], v[98:101]
	v_mfma_f32_16x16x32_bf16 v[70:73], v[94:97], v[6:9], v[70:73]
	v_mfma_f32_16x16x32_bf16 v[66:69], v[66:69], v[6:9], v[78:81]
	s_cbranch_vccnz .LBB0_1234
	s_lshl_b32 s14, s28, 6
	v_subrev_u32_e32 v86, s14, v146
	v_sub_u32_e32 v87, v86, v20
	v_add_u32_e32 v88, v86, v208
	v_add_u32_e32 v89, -3, v87
	v_add_u32_e32 v94, -2, v87
	v_subrev_u32_e32 v95, 17, v87
	v_add_u32_e32 v96, -16, v87
	v_subrev_u32_e32 v97, 33, v87
	v_subrev_u32_e32 v98, 32, v87
	v_med3_i32 v78, v87, 0, v172
	v_med3_i32 v79, v88, 0, v172
	v_med3_i32 v80, v94, 0, v172
	v_med3_i32 v81, v89, 0, v172
	v_med3_i32 v82, v96, 0, v172
	v_med3_i32 v83, v95, 0, v172
	v_med3_i32 v84, v98, 0, v172
	v_med3_i32 v85, v97, 0, v172
	v_lshl_add_u32 v78, v78, 2, v174
	v_lshl_add_u32 v79, v79, 2, v174
	v_lshl_add_u32 v80, v80, 2, v174
	v_lshl_add_u32 v81, v81, 2, v174
	v_lshl_add_u32 v82, v82, 2, v174
	v_lshl_add_u32 v83, v83, 2, v174
	v_lshl_add_u32 v84, v84, 2, v174
	v_lshl_add_u32 v85, v85, 2, v174
	ds_read_b32 v78, v78
	ds_read_b32 v79, v79
	ds_read_b32 v80, v80
	ds_read_b32 v81, v81
	ds_read_b32 v82, v82
	ds_read_b32 v83, v83
	ds_read_b32 v84, v84
	ds_read_b32 v85, v85
	s_waitcnt lgkmcnt(0)
	v_add_f32_e32 v78, v90, v78
	v_add_f32_e32 v79, v91, v79
	v_cmp_lt_i32_e32 vcc, -1, v88
	v_add_f32_e32 v80, v92, v80
	v_add_f32_e32 v81, v93, v81
	v_subrev_u32_e32 v88, 49, v87
	v_cndmask_b32_e32 v91, v173, v79, vcc
	v_cmp_lt_i32_e32 vcc, -1, v87
	v_med3_i32 v79, v88, 0, v172
	v_add_f32_e32 v74, v74, v82
	v_add_f32_e32 v75, v75, v83
	v_cndmask_b32_e32 v90, v173, v78, vcc
	v_cmp_lt_i32_e32 vcc, -1, v89
	v_subrev_u32_e32 v89, 48, v87
	v_med3_i32 v78, v89, 0, v172
	v_cndmask_b32_e32 v93, v173, v81, vcc
	v_cmp_lt_i32_e32 vcc, -1, v94
	v_sub_u32_e32 v81, v86, v1
	v_add_u32_e32 v94, -16, v81
	v_cndmask_b32_e32 v92, v173, v80, vcc
	v_sub_u32_e32 v80, v86, v158
	v_add_u32_e32 v99, -16, v80
	v_subrev_u32_e32 v100, 32, v81
	v_subrev_u32_e32 v101, 32, v80
	v_subrev_u32_e32 v103, 48, v80
	v_med3_i32 v86, v99, 0, v172
	v_med3_i32 v87, v94, 0, v172
	v_med3_i32 v82, v101, 0, v172
	v_med3_i32 v83, v100, 0, v172
	v_subrev_u32_e32 v102, 48, v81
	v_med3_i32 v80, v103, 0, v172
	v_lshl_add_u32 v78, v78, 2, v174
	v_lshl_add_u32 v79, v79, 2, v174
	v_lshl_add_u32 v86, v86, 2, v174
	v_lshl_add_u32 v87, v87, 2, v174
	v_lshl_add_u32 v82, v82, 2, v174
	v_lshl_add_u32 v83, v83, 2, v174
	v_lshl_add_u32 v104, v80, 2, v174
	v_med3_i32 v80, v102, 0, v172
	v_lshl_add_u32 v105, v80, 2, v174
	ds_read_b32 v78, v78
	ds_read_b32 v79, v79
	ds_read_b32 v80, v86
	ds_read_b32 v81, v87
	ds_read_b32 v82, v82
	ds_read_b32 v83, v83
	ds_read_b32 v86, v104
	ds_read_b32 v87, v105
	s_waitcnt lgkmcnt(0)
	v_add_f32_e32 v76, v76, v80
	v_add_f32_e32 v77, v77, v81
	v_cmp_lt_i32_e32 vcc, -1, v94
	v_add_f32_e32 v72, v72, v82
	v_add_f32_e32 v73, v73, v83
	v_add_f32_e32 v70, v70, v84
	v_add_f32_e32 v71, v71, v85
	v_cndmask_b32_e32 v77, v173, v77, vcc
	v_cmp_lt_i32_e32 vcc, -1, v99
	v_add_f32_e32 v68, v68, v86
	v_add_f32_e32 v69, v69, v87
	v_add_f32_e32 v66, v66, v78
	v_add_f32_e32 v67, v67, v79
	v_cndmask_b32_e32 v76, v173, v76, vcc
	v_cmp_lt_i32_e32 vcc, -1, v95
	s_nop 1
	v_cndmask_b32_e32 v75, v173, v75, vcc
	v_cmp_lt_i32_e32 vcc, -1, v96
	s_nop 1
	v_cndmask_b32_e32 v74, v173, v74, vcc
	v_cmp_lt_i32_e32 vcc, -1, v100
	s_nop 1
	v_cndmask_b32_e32 v73, v173, v73, vcc
	v_cmp_lt_i32_e32 vcc, -1, v101
	s_nop 1
	v_cndmask_b32_e32 v72, v173, v72, vcc
	v_cmp_lt_i32_e32 vcc, -1, v97
	s_nop 1
	v_cndmask_b32_e32 v71, v173, v71, vcc
	v_cmp_lt_i32_e32 vcc, -1, v98
	s_nop 1
	v_cndmask_b32_e32 v70, v173, v70, vcc
	v_cmp_lt_i32_e32 vcc, -1, v102
	s_nop 1
	v_cndmask_b32_e32 v69, v173, v69, vcc
	v_cmp_lt_i32_e32 vcc, -1, v103
	s_nop 1
	v_cndmask_b32_e32 v68, v173, v68, vcc
	v_cmp_lt_i32_e32 vcc, -1, v88
	s_nop 1
	v_cndmask_b32_e32 v67, v173, v67, vcc
	v_cmp_lt_i32_e32 vcc, -1, v89
	s_nop 1
	v_cndmask_b32_e32 v66, v173, v66, vcc

; #define NEG_INF (-__builtin_inff())
; template <bool LUTB, bool WINLO>
; DEV void mask_bias(f32x4 (&s)[4], const AttnCtx& C, int t, int p0, int pstep, bool colok) {
; #pragma unroll
;     for (int kt = 0; kt < 4; ++kt)
; #pragma unroll
;         for (int i = 0; i < 4; ++i) { const int rel = t - (p0 + pstep * (16 * kt + 4 * C.q4 + i));
;             bool ok = colok && rel >= 0; if (WINLO) ok = ok && rel < 512;
;             float v = s[kt][i]; if (LUTB) v += C.lut[C.h * 129 + (rel < 0 ? 0 : (rel < 128 ? rel : 128))];
;             s[kt][i] = ok ? v : NEG_INF; }
; }
; DEV void attn_unit_mfma(Frame& F, int qg, int kv) {
;     ...
;         const int j = lst[1 + i]; const unsigned byte = (msk[2 * j + (w >> 2)] >> (8 * (w & 3))) & 0xffu;
;         const bool a0 = (byte & 0xfu) != 0u, a1 = (byte & 0xf0u) != 0u;
;         if (a0 || a1) {
;             const bool near = j >= cur - 2; const float bi = near ? 0.f : C.b31;
;             const bool c0 = ((byte >> (C.n >> 2)) & 1u) != 0u, c1 = ((byte >> (4 + (C.n >> 2))) & 1u) != 0u;
;     ...
;             if (a0 && a1) SEL_BODY(true, true); else if (a0) SEL_BODY(true, false); else SEL_BODY(false, true);
.LBB0_1238:
	s_andn2_b64 vcc, exec, s[12:13]
	s_cbranch_vccnz .LBB0_1247
	v_cmp_eq_f32_e64 s[14:15], s3, v213
	v_cmp_eq_f32_e64 s[12:13], s3, v212
	s_waitcnt lgkmcnt(0)
	v_cndmask_b32_e64 v66, v213, 0, s[14:15]
	v_sub_f32_e32 v66, v216, v66
	v_cndmask_b32_e64 v78, v173, v66, s[10:11]
	v_cndmask_b32_e64 v66, v212, 0, s[12:13]
	v_sub_f32_e32 v66, v216, v66
	v_cndmask_b32_e64 v98, v173, v66, s[8:9]
	ds_read_b128 v[66:69], v215 offset:32768
	ds_read_b128 v[70:73], v214 offset:32768
	ds_read_b128 v[74:77], v215 offset:34816
	ds_read_b128 v[90:93], v214 offset:34816
	ds_read_b128 v[94:97], v215 offset:36864
	ds_read_b128 v[102:105], v214 offset:36864
	ds_read_b128 v[106:109], v215 offset:38912
	ds_read_b128 v[110:113], v214 offset:38912
	v_mov_b32_e32 v79, v78
	v_mov_b32_e32 v80, v78
	v_mov_b32_e32 v81, v78
	v_mov_b32_e32 v99, v98
	v_mov_b32_e32 v100, v98
	v_mov_b32_e32 v101, v98
	s_waitcnt lgkmcnt(0)
	v_mfma_f32_16x16x32_bf16 v[82:85], v[66:69], v[2:5], v[78:81]
	s_andn2_b64 vcc, exec, s[18:19]
	v_mfma_f32_16x16x32_bf16 v[66:69], v[66:69], v[10:13], v[98:101]
	v_mfma_f32_16x16x32_bf16 v[82:85], v[70:73], v[6:9], v[82:85]
	v_mfma_f32_16x16x32_bf16 v[66:69], v[70:73], v[14:17], v[66:69]
	v_mfma_f32_16x16x32_bf16 v[70:73], v[74:77], v[2:5], v[78:81]
	v_mfma_f32_16x16x32_bf16 v[86:89], v[90:93], v[6:9], v[70:73]
	v_mfma_f32_16x16x32_bf16 v[70:73], v[74:77], v[10:13], v[98:101]
	v_mfma_f32_16x16x32_bf16 v[74:77], v[94:97], v[2:5], v[78:81]
	v_mfma_f32_16x16x32_bf16 v[78:81], v[106:109], v[2:5], v[78:81]
	v_mfma_f32_16x16x32_bf16 v[70:73], v[90:93], v[14:17], v[70:73]
	v_mfma_f32_16x16x32_bf16 v[90:93], v[102:105], v[6:9], v[74:77]
	v_mfma_f32_16x16x32_bf16 v[74:77], v[94:97], v[10:13], v[98:101]
	v_mfma_f32_16x16x32_bf16 v[94:97], v[110:113], v[6:9], v[78:81]
	v_mfma_f32_16x16x32_bf16 v[78:81], v[106:109], v[10:13], v[98:101]
	v_mfma_f32_16x16x32_bf16 v[74:77], v[102:105], v[14:17], v[74:77]
	s_nop 1
	v_cndmask_b32_e64 v98, 0, 1, s[18:19]
	v_cmp_ne_u32_e64 s[16:17], 1, v98
	v_mfma_f32_16x16x32_bf16 v[78:81], v[110:113], v[14:17], v[78:81]
	s_cbranch_vccnz .LBB0_1241
	s_lshl_b32 s18, s28, 6
	v_subrev_u32_e32 v106, s18, v146
	v_sub_u32_e32 v107, v106, v20
	v_add_u32_e32 v108, v106, v208
	v_add_u32_e32 v109, -3, v107
	v_add_u32_e32 v110, -2, v107
	v_subrev_u32_e32 v111, 17, v107
	v_add_u32_e32 v112, -16, v107
	v_subrev_u32_e32 v113, 33, v107
	v_subrev_u32_e32 v114, 32, v107
	v_med3_i32 v98, v107, 0, v172
	v_med3_i32 v99, v108, 0, v172
	v_med3_i32 v100, v110, 0, v172
	v_med3_i32 v101, v109, 0, v172
	v_med3_i32 v102, v112, 0, v172
	v_med3_i32 v103, v111, 0, v172
	v_med3_i32 v104, v114, 0, v172
	v_med3_i32 v105, v113, 0, v172
	v_lshl_add_u32 v98, v98, 2, v174
	v_lshl_add_u32 v99, v99, 2, v174
	v_lshl_add_u32 v100, v100, 2, v174
	v_lshl_add_u32 v101, v101, 2, v174
	v_lshl_add_u32 v102, v102, 2, v174
	v_lshl_add_u32 v103, v103, 2, v174
	v_lshl_add_u32 v104, v104, 2, v174
	v_lshl_add_u32 v105, v105, 2, v174
	ds_read_b32 v98, v98
	ds_read_b32 v99, v99
	ds_read_b32 v100, v100
	ds_read_b32 v101, v101
	ds_read_b32 v102, v102
	ds_read_b32 v103, v103
	ds_read_b32 v104, v104
	ds_read_b32 v105, v105
	s_waitcnt lgkmcnt(0)
	v_add_f32_e32 v82, v82, v98
	v_add_f32_e32 v83, v83, v99
	v_cmp_lt_i32_e32 vcc, -1, v108
	v_add_f32_e32 v84, v84, v100
	v_add_f32_e32 v85, v85, v101
	v_sub_u32_e32 v100, v106, v158
	v_cndmask_b32_e32 v83, v173, v83, vcc
	v_cmp_lt_i32_e32 vcc, -1, v107
	v_sub_u32_e32 v101, v106, v1
	v_subrev_u32_e32 v108, 49, v107
	v_cndmask_b32_e32 v82, v173, v82, vcc
	v_cmp_lt_i32_e32 vcc, -1, v109
	v_subrev_u32_e32 v109, 48, v107
	v_add_u32_e32 v115, -16, v100
	v_cndmask_b32_e32 v85, v173, v85, vcc
	v_cmp_lt_i32_e32 vcc, -1, v110
	v_add_u32_e32 v110, -16, v101
	v_subrev_u32_e32 v116, 32, v101
	v_subrev_u32_e32 v117, 32, v100
	v_subrev_u32_e32 v119, 48, v100
	v_med3_i32 v98, v109, 0, v172
	v_med3_i32 v99, v108, 0, v172
	v_med3_i32 v106, v115, 0, v172
	v_med3_i32 v107, v110, 0, v172
	v_add_f32_e32 v86, v86, v102
	v_add_f32_e32 v87, v87, v103
	v_med3_i32 v102, v117, 0, v172
	v_med3_i32 v103, v116, 0, v172
	v_subrev_u32_e32 v118, 48, v101
	v_med3_i32 v100, v119, 0, v172
	v_lshl_add_u32 v98, v98, 2, v174
	v_lshl_add_u32 v99, v99, 2, v174
	v_lshl_add_u32 v106, v106, 2, v174
	v_lshl_add_u32 v107, v107, 2, v174
	v_lshl_add_u32 v102, v102, 2, v174
	v_lshl_add_u32 v103, v103, 2, v174
	v_lshl_add_u32 v120, v100, 2, v174
	v_med3_i32 v100, v118, 0, v172
	v_lshl_add_u32 v121, v100, 2, v174
	ds_read_b32 v98, v98
	ds_read_b32 v99, v99
	ds_read_b32 v100, v106
	ds_read_b32 v101, v107
	ds_read_b32 v102, v102
	ds_read_b32 v103, v103
	ds_read_b32 v106, v120
	ds_read_b32 v107, v121
	v_cndmask_b32_e32 v84, v173, v84, vcc
	s_waitcnt lgkmcnt(0)
	v_add_f32_e32 v88, v88, v100
	v_add_f32_e32 v89, v89, v101
	v_cmp_lt_i32_e32 vcc, -1, v110
	v_add_f32_e32 v92, v92, v102
	v_add_f32_e32 v93, v93, v103
	v_add_f32_e32 v90, v90, v104
	v_add_f32_e32 v91, v91, v105
	v_cndmask_b32_e32 v89, v173, v89, vcc
	v_cmp_lt_i32_e32 vcc, -1, v115
	v_add_f32_e32 v96, v96, v106
	v_add_f32_e32 v97, v97, v107
	v_add_f32_e32 v94, v94, v98
	v_add_f32_e32 v95, v95, v99
	v_cndmask_b32_e32 v88, v173, v88, vcc
	v_cmp_lt_i32_e32 vcc, -1, v111
	s_nop 1
	v_cndmask_b32_e32 v87, v173, v87, vcc
	v_cmp_lt_i32_e32 vcc, -1, v112
	s_nop 1
	v_cndmask_b32_e32 v86, v173, v86, vcc
	v_cmp_lt_i32_e32 vcc, -1, v116
	s_nop 1
	v_cndmask_b32_e32 v93, v173, v93, vcc
	v_cmp_lt_i32_e32 vcc, -1, v117
	s_nop 1
	v_cndmask_b32_e32 v92, v173, v92, vcc
	v_cmp_lt_i32_e32 vcc, -1, v113
	s_nop 1
	v_cndmask_b32_e32 v91, v173, v91, vcc
	v_cmp_lt_i32_e32 vcc, -1, v114
	s_nop 1
	v_cndmask_b32_e32 v90, v173, v90, vcc
	v_cmp_lt_i32_e32 vcc, -1, v118
	s_nop 1
	v_cndmask_b32_e32 v97, v173, v97, vcc
	v_cmp_lt_i32_e32 vcc, -1, v119
	s_nop 1
	v_cndmask_b32_e32 v96, v173, v96, vcc
	v_cmp_lt_i32_e32 vcc, -1, v108
	s_nop 1
	v_cndmask_b32_e32 v95, v173, v95, vcc
	v_cmp_lt_i32_e32 vcc, -1, v109
	s_nop 1
	v_cndmask_b32_e32 v94, v173, v94, vcc

; #define NEG_INF (-__builtin_inff())
; template <bool LUTB, bool WINLO>
; DEV void mask_bias(f32x4 (&s)[4], const AttnCtx& C, int t, int p0, int pstep, bool colok) {
; #pragma unroll
;     for (int kt = 0; kt < 4; ++kt)
; #pragma unroll
;         for (int i = 0; i < 4; ++i) { const int rel = t - (p0 + pstep * (16 * kt + 4 * C.q4 + i));
;             bool ok = colok && rel >= 0; if (WINLO) ok = ok && rel < 512;
;             float v = s[kt][i]; if (LUTB) v += C.lut[C.h * 129 + (rel < 0 ? 0 : (rel < 128 ? rel : 128))];
;             s[kt][i] = ok ? v : NEG_INF; }
; }
; DEV void attn_unit_mfma(Frame& F, int qg, int kv) {
;     ...
;             if (a0 && a1) SEL_BODY(true, true); else if (a0) SEL_BODY(true, false); else SEL_BODY(false, true);
.LBB0_1243:
	s_lshl_b32 s10, s28, 6
	v_subrev_u32_e32 v106, s10, v144
	v_sub_u32_e32 v107, v106, v20
	v_add_u32_e32 v108, v106, v208
	v_add_u32_e32 v109, -3, v107
	v_add_u32_e32 v110, -2, v107
	v_subrev_u32_e32 v111, 17, v107
	v_add_u32_e32 v112, -16, v107
	v_subrev_u32_e32 v113, 33, v107
	v_subrev_u32_e32 v114, 32, v107
	v_med3_i32 v98, v107, 0, v172
	v_med3_i32 v99, v108, 0, v172
	v_med3_i32 v100, v110, 0, v172
	v_med3_i32 v101, v109, 0, v172
	v_med3_i32 v102, v112, 0, v172
	v_med3_i32 v103, v111, 0, v172
	v_med3_i32 v104, v114, 0, v172
	v_med3_i32 v105, v113, 0, v172
	v_lshl_add_u32 v98, v98, 2, v174
	v_lshl_add_u32 v99, v99, 2, v174
	v_lshl_add_u32 v100, v100, 2, v174
	v_lshl_add_u32 v101, v101, 2, v174
	v_lshl_add_u32 v102, v102, 2, v174
	v_lshl_add_u32 v103, v103, 2, v174
	v_lshl_add_u32 v104, v104, 2, v174
	v_lshl_add_u32 v105, v105, 2, v174
	ds_read_b32 v98, v98
	ds_read_b32 v99, v99
	ds_read_b32 v100, v100
	ds_read_b32 v101, v101
	ds_read_b32 v102, v102
	ds_read_b32 v103, v103
	ds_read_b32 v104, v104
	ds_read_b32 v105, v105
	s_waitcnt lgkmcnt(0)
	v_add_f32_e32 v66, v66, v98
	v_add_f32_e32 v67, v67, v99
	v_cmp_lt_i32_e32 vcc, -1, v108
	v_add_f32_e32 v68, v68, v100
	v_add_f32_e32 v69, v69, v101
	v_sub_u32_e32 v100, v106, v158
	v_cndmask_b32_e32 v67, v173, v67, vcc
	v_cmp_lt_i32_e32 vcc, -1, v107
	v_sub_u32_e32 v101, v106, v1
	v_subrev_u32_e32 v108, 49, v107
	v_cndmask_b32_e32 v66, v173, v66, vcc
	v_cmp_lt_i32_e32 vcc, -1, v109
	v_subrev_u32_e32 v109, 48, v107
	v_add_u32_e32 v115, -16, v100
	v_cndmask_b32_e32 v69, v173, v69, vcc
	v_cmp_lt_i32_e32 vcc, -1, v110
	v_add_u32_e32 v110, -16, v101
	v_subrev_u32_e32 v116, 32, v101
	v_subrev_u32_e32 v117, 32, v100
	v_subrev_u32_e32 v119, 48, v100
	v_med3_i32 v98, v109, 0, v172
	v_med3_i32 v99, v108, 0, v172
	v_med3_i32 v106, v115, 0, v172
	v_med3_i32 v107, v110, 0, v172
	v_add_f32_e32 v70, v70, v102
	v_add_f32_e32 v71, v71, v103
	v_med3_i32 v102, v117, 0, v172
	v_med3_i32 v103, v116, 0, v172
	v_subrev_u32_e32 v118, 48, v101
	v_med3_i32 v100, v119, 0, v172
	v_lshl_add_u32 v98, v98, 2, v174
	v_lshl_add_u32 v99, v99, 2, v174
	v_lshl_add_u32 v106, v106, 2, v174
	v_lshl_add_u32 v107, v107, 2, v174
	v_lshl_add_u32 v102, v102, 2, v174
	v_lshl_add_u32 v103, v103, 2, v174
	v_lshl_add_u32 v120, v100, 2, v174
	v_med3_i32 v100, v118, 0, v172
	v_lshl_add_u32 v121, v100, 2, v174
	ds_read_b32 v98, v98
	ds_read_b32 v99, v99
	ds_read_b32 v100, v106
	ds_read_b32 v101, v107
	ds_read_b32 v102, v102
	ds_read_b32 v103, v103
	ds_read_b32 v106, v120
	ds_read_b32 v107, v121
	v_cndmask_b32_e32 v68, v173, v68, vcc
	s_waitcnt lgkmcnt(0)
	v_add_f32_e32 v72, v72, v100
	v_add_f32_e32 v73, v73, v101
	v_cmp_lt_i32_e32 vcc, -1, v110
	v_add_f32_e32 v76, v76, v102
	v_add_f32_e32 v77, v77, v103
	v_add_f32_e32 v74, v74, v104
	v_add_f32_e32 v75, v75, v105
	v_cndmask_b32_e32 v73, v173, v73, vcc
	v_cmp_lt_i32_e32 vcc, -1, v115
	v_add_f32_e32 v80, v80, v106
	v_add_f32_e32 v81, v81, v107
	v_add_f32_e32 v78, v78, v98
	v_add_f32_e32 v79, v79, v99
	v_cndmask_b32_e32 v72, v173, v72, vcc
	v_cmp_lt_i32_e32 vcc, -1, v111
	s_nop 1
	v_cndmask_b32_e32 v71, v173, v71, vcc
	v_cmp_lt_i32_e32 vcc, -1, v112
	s_nop 1
	v_cndmask_b32_e32 v70, v173, v70, vcc
	v_cmp_lt_i32_e32 vcc, -1, v116
	s_nop 1
	v_cndmask_b32_e32 v77, v173, v77, vcc
	v_cmp_lt_i32_e32 vcc, -1, v117
	s_nop 1
	v_cndmask_b32_e32 v76, v173, v76, vcc
	v_cmp_lt_i32_e32 vcc, -1, v113
	s_nop 1
	v_cndmask_b32_e32 v75, v173, v75, vcc
	v_cmp_lt_i32_e32 vcc, -1, v114
	s_nop 1
	v_cndmask_b32_e32 v74, v173, v74, vcc
	v_cmp_lt_i32_e32 vcc, -1, v118
	s_nop 1
	v_cndmask_b32_e32 v81, v173, v81, vcc
	v_cmp_lt_i32_e32 vcc, -1, v119
	s_nop 1
	v_cndmask_b32_e32 v80, v173, v80, vcc
	v_cmp_lt_i32_e32 vcc, -1, v108
	s_nop 1
	v_cndmask_b32_e32 v79, v173, v79, vcc
	v_cmp_lt_i32_e32 vcc, -1, v109
	s_nop 1
	v_cndmask_b32_e32 v78, v173, v78, vcc

; #define NEG_INF (-__builtin_inff())
; template <bool LUTB, bool WINLO>
; DEV void mask_bias(f32x4 (&s)[4], const AttnCtx& C, int t, int p0, int pstep, bool colok) {
; #pragma unroll
;     for (int kt = 0; kt < 4; ++kt)
; #pragma unroll
;         for (int i = 0; i < 4; ++i) { const int rel = t - (p0 + pstep * (16 * kt + 4 * C.q4 + i));
;             bool ok = colok && rel >= 0; if (WINLO) ok = ok && rel < 512;
;             float v = s[kt][i]; if (LUTB) v += C.lut[C.h * 129 + (rel < 0 ? 0 : (rel < 128 ? rel : 128))];
;             s[kt][i] = ok ? v : NEG_INF; }
; }
; DEV void attn_unit_mfma(Frame& F, int qg, int kv) {
;     ...
;         const int it = i + iw0, p0 = t0 - 512 + 64 * it; const bool near = it >= 6; const float bi = near ? 0.f : C.b31;
;         f32x4 s[2][4]; qk64(Kb, C, qf, s, cinit(bi, m[0], true), cinit(bi, m[1], true), true, true);
;         ab8 pf[2][2], vf[4][2]; pv_load(Vb, C, vf); __builtin_amdgcn_sched_barrier(0);
; #pragma unroll
;         for (int g = 0; g < 2; ++g) { if (near) mask_bias<true, false>(s[g], C, C.tq[g], p0, 1, true); else if (it == 0) mask_bias<false, true>(s[g], C, C.tq[g], p0, 1, true);
;             ref_step(s[g], m[g], O[g], L[g], pf[g], true); }
.LBB0_1287:
	s_andn2_b64 vcc, exec, s[36:37]
	s_cbranch_vccnz .LBB0_1289
	v_add_u32_e32 v158, -4, v133
	v_add_u32_e32 v196, -5, v133
	v_add_u32_e32 v197, -7, v133
	v_add_u32_e32 v198, -6, v133
	v_subrev_u32_e32 v199, 21, v133
	v_subrev_u32_e32 v200, 20, v133
	v_subrev_u32_e32 v201, 23, v133
	v_subrev_u32_e32 v202, 22, v133
	v_med3_i32 v136, v158, 0, v172
	v_med3_i32 v137, v196, 0, v172
	v_med3_i32 v144, v198, 0, v172
	v_med3_i32 v145, v197, 0, v172
	v_med3_i32 v146, v200, 0, v172
	v_med3_i32 v147, v199, 0, v172
	v_med3_i32 v156, v202, 0, v172
	v_med3_i32 v157, v201, 0, v172
	v_lshl_add_u32 v136, v136, 2, v174
	v_lshl_add_u32 v137, v137, 2, v174
	v_lshl_add_u32 v144, v144, 2, v174
	v_lshl_add_u32 v145, v145, 2, v174
	v_lshl_add_u32 v146, v146, 2, v174
	v_lshl_add_u32 v147, v147, 2, v174
	v_lshl_add_u32 v156, v156, 2, v174
	v_lshl_add_u32 v157, v157, 2, v174
	ds_read_b32 v136, v136
	ds_read_b32 v137, v137
	ds_read_b32 v144, v144
	ds_read_b32 v145, v145
	ds_read_b32 v146, v146
	ds_read_b32 v147, v147
	ds_read_b32 v156, v156
	ds_read_b32 v157, v157
	s_waitcnt lgkmcnt(6)
	v_add_f32_e32 v126, v126, v136
	v_add_f32_e32 v127, v127, v137
	v_cmp_lt_i32_e32 vcc, -1, v158
	s_waitcnt lgkmcnt(4)
	v_add_f32_e32 v128, v128, v144
	v_add_f32_e32 v129, v129, v145
	s_waitcnt lgkmcnt(2)
	v_add_f32_e32 v122, v122, v146
	v_add_f32_e32 v123, v123, v147
	v_cndmask_b32_e32 v136, v173, v126, vcc
	v_cmp_lt_i32_e32 vcc, -1, v196
	s_waitcnt lgkmcnt(0)
	v_add_f32_e32 v124, v124, v156
	v_add_f32_e32 v125, v125, v157
	v_subrev_u32_e32 v196, 37, v133
	v_cndmask_b32_e32 v137, v173, v127, vcc
	v_cmp_lt_i32_e32 vcc, -1, v198
	v_subrev_u32_e32 v158, 36, v133
	v_subrev_u32_e32 v198, 39, v133
	v_cndmask_b32_e32 v144, v173, v128, vcc
	v_cmp_lt_i32_e32 vcc, -1, v197
	v_subrev_u32_e32 v197, 38, v133
	s_nop 0
	v_cndmask_b32_e32 v145, v173, v129, vcc
	v_cmp_lt_i32_e32 vcc, -1, v200
	v_subrev_u32_e32 v200, 53, v133
	v_med3_i32 v127, v200, 0, v172
	v_cndmask_b32_e32 v146, v173, v122, vcc
	v_cmp_lt_i32_e32 vcc, -1, v199
	v_subrev_u32_e32 v199, 52, v133
	v_med3_i32 v122, v158, 0, v172
	v_cndmask_b32_e32 v147, v173, v123, vcc
	v_cmp_lt_i32_e32 vcc, -1, v202
	v_subrev_u32_e32 v202, 55, v133
	v_med3_i32 v123, v196, 0, v172
	v_cndmask_b32_e32 v156, v173, v124, vcc
	v_cmp_lt_i32_e32 vcc, -1, v201
	v_subrev_u32_e32 v201, 54, v133
	v_med3_i32 v124, v197, 0, v172
	v_cndmask_b32_e32 v157, v173, v125, vcc
	v_med3_i32 v125, v198, 0, v172
	v_med3_i32 v126, v199, 0, v172
	v_med3_i32 v128, v201, 0, v172
	v_med3_i32 v129, v202, 0, v172
	v_lshl_add_u32 v122, v122, 2, v174
	v_lshl_add_u32 v123, v123, 2, v174
	v_lshl_add_u32 v124, v124, 2, v174
	v_lshl_add_u32 v125, v125, 2, v174
	v_lshl_add_u32 v126, v126, 2, v174
	v_lshl_add_u32 v127, v127, 2, v174
	v_lshl_add_u32 v128, v128, 2, v174
	v_lshl_add_u32 v129, v129, 2, v174
	ds_read_b32 v122, v122
	ds_read_b32 v123, v123
	ds_read_b32 v124, v124
	ds_read_b32 v125, v125
	ds_read_b32 v126, v126
	ds_read_b32 v127, v127
	ds_read_b32 v128, v128
	ds_read_b32 v129, v129
	s_waitcnt lgkmcnt(6)
	v_add_f32_e32 v118, v118, v122
	v_add_f32_e32 v119, v119, v123
	v_cmp_lt_i32_e32 vcc, -1, v158
	s_waitcnt lgkmcnt(4)
	v_add_f32_e32 v120, v120, v124
	v_add_f32_e32 v121, v121, v125
	s_waitcnt lgkmcnt(2)
	v_add_f32_e32 v114, v114, v126
	v_add_f32_e32 v115, v115, v127
	v_cndmask_b32_e32 v158, v173, v118, vcc
	v_cmp_lt_i32_e32 vcc, -1, v196
	s_waitcnt lgkmcnt(0)
	v_add_f32_e32 v116, v116, v128
	v_add_f32_e32 v117, v117, v129
	v_cndmask_b32_e32 v196, v173, v119, vcc
	v_cmp_lt_i32_e32 vcc, -1, v197
	s_nop 1
	v_cndmask_b32_e32 v197, v173, v120, vcc
	v_cmp_lt_i32_e32 vcc, -1, v198
	s_nop 1
	v_cndmask_b32_e32 v198, v173, v121, vcc
	v_cmp_lt_i32_e32 vcc, -1, v199
	s_nop 1
	v_cndmask_b32_e32 v199, v173, v114, vcc
	v_cmp_lt_i32_e32 vcc, -1, v200
	s_nop 1
	v_cndmask_b32_e32 v200, v173, v115, vcc
	v_cmp_lt_i32_e32 vcc, -1, v201
	s_nop 1
	v_cndmask_b32_e32 v201, v173, v116, vcc
	v_cmp_lt_i32_e32 vcc, -1, v202
	s_nop 1
	v_cndmask_b32_e32 v202, v173, v117, vcc

; #define NEG_INF (-__builtin_inff())
; template <bool LUTB, bool WINLO>
; DEV void mask_bias(f32x4 (&s)[4], const AttnCtx& C, int t, int p0, int pstep, bool colok) {
; #pragma unroll
;     for (int kt = 0; kt < 4; ++kt)
; #pragma unroll
;         for (int i = 0; i < 4; ++i) { const int rel = t - (p0 + pstep * (16 * kt + 4 * C.q4 + i));
;             bool ok = colok && rel >= 0; if (WINLO) ok = ok && rel < 512;
;             float v = s[kt][i]; if (LUTB) v += C.lut[C.h * 129 + (rel < 0 ? 0 : (rel < 128 ? rel : 128))];
;             s[kt][i] = ok ? v : NEG_INF; }
; }
; DEV void attn_unit_mfma(Frame& F, int qg, int kv) {
;     ...
;         const int it = i + iw0, p0 = t0 - 512 + 64 * it; const bool near = it >= 6; const float bi = near ? 0.f : C.b31;
;         f32x4 s[2][4]; qk64(Kb, C, qf, s, cinit(bi, m[0], true), cinit(bi, m[1], true), true, true);
;         ab8 pf[2][2], vf[4][2]; pv_load(Vb, C, vf); __builtin_amdgcn_sched_barrier(0);
; #pragma unroll
;         for (int g = 0; g < 2; ++g) { if (near) mask_bias<true, false>(s[g], C, C.tq[g], p0, 1, true); else if (it == 0) mask_bias<false, true>(s[g], C, C.tq[g], p0, 1, true);
;             ref_step(s[g], m[g], O[g], L[g], pf[g], true); }
.LBB0_1295:
	s_andn2_b64 vcc, exec, s[26:27]
	s_cbranch_vccnz .LBB0_1297
	v_add_u32_e32 v122, -1, v133
	v_add_u32_e32 v123, -3, v133
	v_add_u32_e32 v124, -2, v133
	v_add_u32_e32 v125, -16, v133
	v_subrev_u32_e32 v126, 17, v133
	v_subrev_u32_e32 v127, 19, v133
	v_subrev_u32_e32 v128, 18, v133
	v_med3_i32 v114, v133, 0, v172
	v_med3_i32 v115, v122, 0, v172
	v_med3_i32 v116, v124, 0, v172
	v_med3_i32 v117, v123, 0, v172
	v_med3_i32 v118, v125, 0, v172
	v_med3_i32 v119, v126, 0, v172
	v_med3_i32 v120, v128, 0, v172
	v_med3_i32 v121, v127, 0, v172
	v_lshl_add_u32 v114, v114, 2, v174
	v_lshl_add_u32 v115, v115, 2, v174
	v_lshl_add_u32 v116, v116, 2, v174
	v_lshl_add_u32 v117, v117, 2, v174
	v_lshl_add_u32 v118, v118, 2, v174
	v_lshl_add_u32 v119, v119, 2, v174
	v_lshl_add_u32 v120, v120, 2, v174
	v_lshl_add_u32 v121, v121, 2, v174
	ds_read_b32 v114, v114
	ds_read_b32 v115, v115
	ds_read_b32 v116, v116
	ds_read_b32 v117, v117
	ds_read_b32 v118, v118
	ds_read_b32 v119, v119
	ds_read_b32 v120, v120
	ds_read_b32 v121, v121
	s_waitcnt lgkmcnt(6)
	v_add_f32_e32 v110, v110, v114
	v_add_f32_e32 v111, v111, v115
	v_cmp_lt_i32_e32 vcc, -1, v133
	s_waitcnt lgkmcnt(4)
	v_add_f32_e32 v112, v112, v116
	v_add_f32_e32 v113, v113, v117
	s_waitcnt lgkmcnt(2)
	v_add_f32_e32 v106, v106, v118
	v_add_f32_e32 v107, v107, v119
	v_cndmask_b32_e32 v114, v173, v110, vcc
	v_cmp_lt_i32_e32 vcc, -1, v122
	s_waitcnt lgkmcnt(0)
	v_add_f32_e32 v108, v108, v120
	v_add_f32_e32 v109, v109, v121
	v_subrev_u32_e32 v122, 33, v133
	v_cndmask_b32_e32 v115, v173, v111, vcc
	v_cmp_lt_i32_e32 vcc, -1, v124
	v_subrev_u32_e32 v129, 49, v133
	v_subrev_u32_e32 v203, 51, v133
	v_cndmask_b32_e32 v116, v173, v112, vcc
	v_cmp_lt_i32_e32 vcc, -1, v123
	v_subrev_u32_e32 v123, 32, v133
	v_subrev_u32_e32 v204, 50, v133
	v_cndmask_b32_e32 v117, v173, v113, vcc
	v_cmp_lt_i32_e32 vcc, -1, v128
	v_subrev_u32_e32 v128, 48, v133
	v_med3_i32 v110, v128, 0, v172
	v_cndmask_b32_e32 v118, v173, v108, vcc
	v_cmp_lt_i32_e32 vcc, -1, v127
	v_subrev_u32_e32 v127, 35, v133
	v_med3_i32 v111, v129, 0, v172
	v_cndmask_b32_e32 v119, v173, v109, vcc
	v_cmp_lt_i32_e32 vcc, -1, v125
	v_med3_i32 v109, v127, 0, v172
	v_med3_i32 v112, v204, 0, v172
	v_cndmask_b32_e32 v120, v173, v106, vcc
	v_cmp_lt_i32_e32 vcc, -1, v126
	v_subrev_u32_e32 v126, 34, v133
	v_med3_i32 v106, v123, 0, v172
	v_cndmask_b32_e32 v121, v173, v107, vcc
	v_med3_i32 v107, v122, 0, v172
	v_med3_i32 v108, v126, 0, v172
	v_med3_i32 v113, v203, 0, v172
	v_lshl_add_u32 v106, v106, 2, v174
	v_lshl_add_u32 v107, v107, 2, v174
	v_lshl_add_u32 v108, v108, 2, v174
	v_lshl_add_u32 v109, v109, 2, v174
	v_lshl_add_u32 v110, v110, 2, v174
	v_lshl_add_u32 v111, v111, 2, v174
	v_lshl_add_u32 v112, v112, 2, v174
	v_lshl_add_u32 v113, v113, 2, v174
	ds_read_b32 v106, v106
	ds_read_b32 v107, v107
	ds_read_b32 v108, v108
	ds_read_b32 v109, v109
	ds_read_b32 v110, v110
	ds_read_b32 v111, v111
	ds_read_b32 v112, v112
	ds_read_b32 v113, v113
	s_waitcnt lgkmcnt(6)
	v_add_f32_e32 v102, v102, v106
	v_add_f32_e32 v103, v103, v107
	v_cmp_lt_i32_e32 vcc, -1, v123
	s_waitcnt lgkmcnt(4)
	v_add_f32_e32 v104, v104, v108
	v_add_f32_e32 v105, v105, v109
	s_waitcnt lgkmcnt(2)
	v_add_f32_e32 v98, v98, v110
	v_add_f32_e32 v99, v99, v111
	v_cndmask_b32_e32 v124, v173, v102, vcc
	v_cmp_lt_i32_e32 vcc, -1, v122
	s_waitcnt lgkmcnt(0)
	v_add_f32_e32 v100, v100, v112
	v_add_f32_e32 v101, v101, v113
	v_cndmask_b32_e32 v125, v173, v103, vcc
	v_cmp_lt_i32_e32 vcc, -1, v126
	s_nop 1
	v_cndmask_b32_e32 v126, v173, v104, vcc
	v_cmp_lt_i32_e32 vcc, -1, v127
	s_nop 1
	v_cndmask_b32_e32 v127, v173, v105, vcc
	v_cmp_lt_i32_e32 vcc, -1, v128
	s_nop 1
	v_cndmask_b32_e32 v128, v173, v98, vcc
	v_cmp_lt_i32_e32 vcc, -1, v129
	s_nop 1
	v_cndmask_b32_e32 v129, v173, v99, vcc
	v_cmp_lt_i32_e32 vcc, -1, v204
	s_nop 1
	v_cndmask_b32_e32 v122, v173, v100, vcc
	v_cmp_lt_i32_e32 vcc, -1, v203
	s_nop 1
	v_cndmask_b32_e32 v123, v173, v101, vcc

; #define LAS __attribute__((address_space(3)))
; template <class Tp> DEV Tp* wsp(const Frame& F, size_t off) { return (Tp*)(F.ws + off); }
; DEV void hgrn_c_unit(Frame& F, int c, int hp) {
;     ...
;     { const bf16* HL = wsp<bf16>(F, WS_HL) + (size_t)(c * 4 + 2 * hp) * 16384;
; #pragma unroll
;       for (int j = 0; j < 8; ++j) { const int e8 = tid + 512 * j; const v4u v = *(const v4u*)(HL + 8 * e8); const int hh = e8 >> 11, rem = e8 & 2047, kr = rem >> 4, vc = (rem & 15) * 8;
;           *(LAS v4u*)(L + hh * 128 * HC_SROW + kr * HC_SROW + 2 * vc) = v; } }
;     __syncthreads();
;     const int h = 2 * hp + (w >> 2), ti = w & 3; const size_t row = (size_t)c * 64 + 16 * ti + n;
;     const LAS unsigned char* Sb = L + (w >> 2) * 128 * HC_SROW;
;     const bf16* qp = wsp<bf16>(F, WS_HQT) + row * 512 + h * 128 + 8 * q4;
;     f32x4 acc[8];
; #pragma unroll
;     for (int vt = 0; vt < 8; ++vt) acc[vt] = *(const f32x4*)(wsp<float>(F, WS_HIN) + row * 512 + h * 128 + 16 * vt + 4 * q4);
; #pragma unroll
;     for (int ks = 0; ks < 4; ++ks) { const ab8 qf = *(const ab8*)(qp + 32 * ks);
; #pragma unroll
;         for (int vt = 0; vt < 8; ++vt) { const ab8 sf = tr_frag(Sb, 32 * ks, 32 * vt, n, q4, HC_SROW); acc[vt] = __builtin_amdgcn_mfma_f32_16x16x32_bf16(sf, qf, acc[vt], 0, 0, 0); } }
.LBB0_1686:
	s_ashr_i32 s4, s18, 1
	s_lshl_b32 s16, s18, 1
	s_lshl_b32 s5, s4, 2
	s_and_b32 s18, s16, 2
	s_or_b32 s16, s18, s5
	s_ashr_i32 s17, s16, 31
	s_lshl_b64 s[16:17], s[16:17], 15
	s_add_u32 s16, s20, s16
	s_addc_u32 s17, s21, s17
	v_lshl_add_u64 v[2:3], v[34:35], 1, s[16:17]
	v_lshl_add_u64 v[6:7], v[36:37], 1, s[16:17]
	v_lshl_add_u64 v[10:11], v[38:39], 1, s[16:17]
	v_lshl_add_u64 v[14:15], v[40:41], 1, s[16:17]
	v_lshl_add_u64 v[18:19], v[42:43], 1, s[16:17]
	v_lshl_add_u64 v[22:23], v[44:45], 1, s[16:17]
	v_lshl_add_u64 v[26:27], v[46:47], 1, s[16:17]
	v_lshl_add_u64 v[30:31], v[48:49], 1, s[16:17]
	global_load_dwordx4 v[2:5], v[2:3], off
	s_nop 0
	global_load_dwordx4 v[6:9], v[6:7], off
	s_nop 0
	global_load_dwordx4 v[10:13], v[10:11], off
	s_nop 0
	global_load_dwordx4 v[14:17], v[14:15], off
	s_nop 0
	global_load_dwordx4 v[18:21], v[18:19], off
	s_nop 0
	global_load_dwordx4 v[22:25], v[22:23], off
	s_nop 0
	global_load_dwordx4 v[26:29], v[26:27], off
	s_nop 0
	global_load_dwordx4 v[30:33], v[30:31], off
	v_readlane_b32 s5, v249, 35
	s_add_i32 s18, s18, s5
	s_ashr_i32 s5, s4, 31
	s_lshl_b64 s[4:5], s[4:5], 15
	s_lshl_b32 s18, s18, 7
	v_mov_b32_e32 v61, s5
	v_or_b32_e32 v60, s4, v56
	s_ashr_i32 s19, s18, 31
	v_lshl_add_u64 v[64:65], v[60:61], 2, s[12:13]
	v_lshlrev_b64 v[60:61], 1, v[60:61]
	s_lshl_b64 s[16:17], s[18:19], 1
	v_lshl_add_u64 v[74:75], s[14:15], 0, v[60:61]
	v_mov_b32_e32 v59, v51
	v_lshl_add_u64 v[74:75], v[74:75], 0, s[16:17]
	v_lshlrev_b32_e32 v50, 2, v52
	v_lshl_add_u64 v[64:65], s[18:19], 2, v[64:65]
	v_lshl_add_u64 v[98:99], v[74:75], 0, v[58:59]
	v_lshl_add_u64 v[64:65], v[64:65], 0, v[50:51]
	v_lshl_add_u64 v[132:133], s[6:7], 0, v[60:61]
	v_lshl_add_u64 v[132:133], v[132:133], 0, s[16:17]
	v_lshlrev_b32_e32 v134, 1, v52
	v_mov_b32_e32 v135, 0
	v_lshl_add_u64 v[132:133], v[132:133], 0, v[134:135]
	global_load_dwordx4 v[100:103], v[98:99], off
	global_load_dwordx4 v[104:107], v[98:99], off offset:64
	global_load_dwordx4 v[108:111], v[98:99], off offset:128
	global_load_dwordx4 v[112:115], v[98:99], off offset:192
	global_load_dwordx4 v[192:195], v[64:65], off
	global_load_dwordx4 v[196:199], v[64:65], off offset:64
	global_load_dwordx4 v[200:203], v[64:65], off offset:128
	global_load_dwordx4 v[204:207], v[64:65], off offset:192
	global_load_dwordx4 v[208:211], v[64:65], off offset:256
	global_load_dwordx4 v[212:215], v[64:65], off offset:320
	global_load_dwordx4 v[216:219], v[64:65], off offset:384
	global_load_dwordx4 v[220:223], v[64:65], off offset:448
	global_load_dwordx2 v[116:117], v[132:133], off
	global_load_dwordx2 v[118:119], v[132:133], off offset:32
	global_load_dwordx2 v[120:121], v[132:133], off offset:64
	global_load_dwordx2 v[122:123], v[132:133], off offset:96
	global_load_dwordx2 v[124:125], v[132:133], off offset:128
	global_load_dwordx2 v[126:127], v[132:133], off offset:160
	global_load_dwordx2 v[128:129], v[132:133], off offset:192
	global_load_dwordx2 v[130:131], v[132:133], off offset:224
	s_waitcnt vmcnt(27)
	ds_write_b128 v53, v[2:5]
	s_waitcnt vmcnt(26)
	ds_write_b128 v57, v[6:9]
	s_waitcnt vmcnt(25)
	ds_write_b128 v63, v[10:13]
	s_waitcnt vmcnt(24)
	ds_write_b128 v66, v[14:17]
	s_waitcnt vmcnt(23)
	ds_write_b128 v67, v[18:21]
	s_waitcnt vmcnt(22)
	ds_write_b128 v68, v[22:25]
	s_waitcnt vmcnt(21)
	ds_write_b128 v69, v[26:29]
	s_waitcnt vmcnt(20)
	ds_write_b128 v70, v[30:33]
	s_waitcnt lgkmcnt(0)
	s_barrier
	s_waitcnt vmcnt(8)
	ds_read_b64_tr_b16 v[16:17], v1 offset:1152
	ds_read_b64_tr_b16 v[14:15], v1
	ds_read_b64_tr_b16 v[28:29], v1 offset:1184
	ds_read_b64_tr_b16 v[26:27], v1 offset:32
	ds_read_b64_tr_b16 v[30:31], v1 offset:64
	ds_read_b64_tr_b16 v[74:75], v1 offset:96
	ds_read_b64_tr_b16 v[32:33], v1 offset:1216
	ds_read_b64_tr_b16 v[76:77], v1 offset:1248
	ds_read_b64_tr_b16 v[82:83], v1 offset:128
	s_waitcnt lgkmcnt(7)
	v_mfma_f32_16x16x32_bf16 v[6:9], v[14:17], v[100:103], v[192:195]
	s_waitcnt lgkmcnt(5)
	v_mfma_f32_16x16x32_bf16 v[10:13], v[26:29], v[100:103], v[196:199]
	s_waitcnt lgkmcnt(2)
	v_mfma_f32_16x16x32_bf16 v[18:21], v[30:33], v[100:103], v[200:203]
	ds_read_b64_tr_b16 v[84:85], v1 offset:1280
	ds_read_b64_tr_b16 v[32:33], v1 offset:1312
	s_waitcnt lgkmcnt(3)
	v_mfma_f32_16x16x32_bf16 v[22:25], v[74:77], v[100:103], v[204:207]
	ds_read_b64_tr_b16 v[30:31], v1 offset:160
	ds_read_b64_tr_b16 v[74:75], v1 offset:192
	ds_read_b64_tr_b16 v[86:87], v1 offset:224
	ds_read_b64_tr_b16 v[76:77], v1 offset:1344
	ds_read_b64_tr_b16 v[88:89], v1 offset:1376
	ds_read_b64_tr_b16 v[90:91], v1 offset:9216
	s_waitcnt lgkmcnt(7)
	v_mfma_f32_16x16x32_bf16 v[14:17], v[82:85], v[100:103], v[208:211]
	s_waitcnt lgkmcnt(5)
	v_mfma_f32_16x16x32_bf16 v[26:29], v[30:33], v[100:103], v[212:215]
	s_waitcnt lgkmcnt(2)
	v_mfma_f32_16x16x32_bf16 v[74:77], v[74:77], v[100:103], v[216:219]
	ds_read_b64_tr_b16 v[92:93], v1 offset:10368
	s_nop 1
	ds_read_b64_tr_b16 v[84:85], v1 offset:10400
	s_waitcnt lgkmcnt(3)
	v_mfma_f32_16x16x32_bf16 v[2:5], v[86:89], v[100:103], v[220:223]
	ds_read_b64_tr_b16 v[82:83], v1 offset:9248
	s_nop 1
	ds_read_b64_tr_b16 v[30:31], v1 offset:9280
	ds_read_b64_tr_b16 v[86:87], v1 offset:9312
	ds_read_b64_tr_b16 v[32:33], v1 offset:10432
	ds_read_b64_tr_b16 v[88:89], v1 offset:10464
	s_waitcnt lgkmcnt(4)
	v_mfma_f32_16x16x32_bf16 v[10:13], v[82:85], v[104:107], v[10:13]
	ds_read_b64_tr_b16 v[82:83], v1 offset:9344
	ds_read_b64_tr_b16 v[84:85], v1 offset:10496
	v_mfma_f32_16x16x32_bf16 v[6:9], v[90:93], v[104:107], v[6:9]
	s_waitcnt lgkmcnt(3)
; DEV void hgrn_c_unit(Frame& F, int c, int hp) {
;     ...
;     for (int ks = 0; ks < 4; ++ks) { const ab8 qf = *(const ab8*)(qp + 32 * ks);
; #pragma unroll
;         for (int vt = 0; vt < 8; ++vt) { const ab8 sf = tr_frag(Sb, 32 * ks, 32 * vt, n, q4, HC_SROW); acc[vt] = __builtin_amdgcn_mfma_f32_16x16x32_bf16(sf, qf, acc[vt], 0, 0, 0); } }
;     float ss = 0.f;
; #pragma unroll
;     for (int vt = 0; vt < 8; ++vt) ss += (acc[vt][0] * acc[vt][0] + acc[vt][1] * acc[vt][1]) + (acc[vt][2] * acc[vt][2] + acc[vt][3] * acc[vt][3]);
;     ss += __shfl_xor(ss, 16); ss += __shfl_xor(ss, 32);
	v_mfma_f32_16x16x32_bf16 v[18:21], v[30:33], v[104:107], v[18:21]
	ds_read_b64_tr_b16 v[30:31], v1 offset:9376
	ds_read_b64_tr_b16 v[90:91], v1 offset:9408
	ds_read_b64_tr_b16 v[94:95], v1 offset:9440
	ds_read_b64_tr_b16 v[32:33], v1 offset:10528
	ds_read_b64_tr_b16 v[92:93], v1 offset:10560
	ds_read_b64_tr_b16 v[96:97], v1 offset:10592
	s_waitcnt lgkmcnt(6)
	v_mfma_f32_16x16x32_bf16 v[14:17], v[82:85], v[104:107], v[14:17]
	v_mfma_f32_16x16x32_bf16 v[22:25], v[86:89], v[104:107], v[22:25]
	s_waitcnt lgkmcnt(2)
	v_mfma_f32_16x16x32_bf16 v[26:29], v[30:33], v[104:107], v[26:29]
	ds_read_b64_tr_b16 v[30:31], v1 offset:18432
	s_waitcnt lgkmcnt(2)
	v_mfma_f32_16x16x32_bf16 v[74:77], v[90:93], v[104:107], v[74:77]
	ds_read_b64_tr_b16 v[32:33], v1 offset:19584
	ds_read_b64_tr_b16 v[92:93], v1 offset:19616
	s_waitcnt lgkmcnt(3)
	v_mfma_f32_16x16x32_bf16 v[2:5], v[94:97], v[104:107], v[2:5]
	ds_read_b64_tr_b16 v[90:91], v1 offset:18464
	ds_read_b64_tr_b16 v[78:79], v1 offset:18496
	ds_read_b64_tr_b16 v[94:95], v1 offset:18528
	ds_read_b64_tr_b16 v[80:81], v1 offset:19648
	ds_read_b64_tr_b16 v[96:97], v1 offset:19680
	s_waitcnt lgkmcnt(6)
	v_mfma_f32_16x16x32_bf16 v[6:9], v[30:33], v[108:111], v[6:9]
	ds_read_b64_tr_b16 v[30:31], v1 offset:18560
	s_waitcnt lgkmcnt(2)
	v_mfma_f32_16x16x32_bf16 v[18:21], v[78:81], v[108:111], v[18:21]
	ds_read_b64_tr_b16 v[32:33], v1 offset:19712
	ds_read_b64_tr_b16 v[80:81], v1 offset:19744
	v_mfma_f32_16x16x32_bf16 v[10:13], v[90:93], v[108:111], v[10:13]
	s_waitcnt lgkmcnt(3)
	v_mfma_f32_16x16x32_bf16 v[90:93], v[94:97], v[108:111], v[22:25]
	ds_read_b64_tr_b16 v[78:79], v1 offset:18592
	s_nop 1
	ds_read_b64_tr_b16 v[22:23], v1 offset:18624
	ds_read_b64_tr_b16 v[94:95], v1 offset:18656
	ds_read_b64_tr_b16 v[24:25], v1 offset:19776
	ds_read_b64_tr_b16 v[96:97], v1 offset:19808
	s_waitcnt lgkmcnt(4)
	v_mfma_f32_16x16x32_bf16 v[78:81], v[78:81], v[108:111], v[26:29]
	s_nop 2
	ds_read_b64_tr_b16 v[26:27], v1 offset:27648
	s_waitcnt lgkmcnt(2)
	v_mfma_f32_16x16x32_bf16 v[74:77], v[22:25], v[108:111], v[74:77]
	ds_read_b64_tr_b16 v[28:29], v1 offset:28800
	ds_read_b64_tr_b16 v[24:25], v1 offset:28832
	v_mfma_f32_16x16x32_bf16 v[14:17], v[30:33], v[108:111], v[14:17]
	s_waitcnt lgkmcnt(3)
	v_mfma_f32_16x16x32_bf16 v[2:5], v[94:97], v[108:111], v[2:5]
	ds_read_b64_tr_b16 v[22:23], v1 offset:27680
	ds_read_b64_tr_b16 v[82:83], v1 offset:27712
	ds_read_b64_tr_b16 v[94:95], v1 offset:27744
	ds_read_b64_tr_b16 v[84:85], v1 offset:28864
	ds_read_b64_tr_b16 v[96:97], v1 offset:28896
	s_waitcnt lgkmcnt(6)
	v_mfma_f32_16x16x32_bf16 v[30:33], v[26:29], v[112:115], v[6:9]
	s_nop 2
	ds_read_b64_tr_b16 v[6:7], v1 offset:27776
	s_waitcnt lgkmcnt(5)
	v_mfma_f32_16x16x32_bf16 v[26:29], v[22:25], v[112:115], v[10:13]
	ds_read_b64_tr_b16 v[8:9], v1 offset:28928
	s_nop 1
	ds_read_b64_tr_b16 v[12:13], v1 offset:28960
	v_mov_b32_e32 v64, v30
	s_nop 2
	v_mov_b32_e32 v65, v26
	s_waitcnt lgkmcnt(4)
	v_mfma_f32_16x16x32_bf16 v[22:25], v[82:85], v[112:115], v[18:21]
	s_waitcnt lgkmcnt(3)
	v_mfma_f32_16x16x32_bf16 v[18:21], v[94:97], v[112:115], v[90:93]
	ds_read_b64_tr_b16 v[10:11], v1 offset:27808
	ds_read_b64_tr_b16 v[82:83], v1 offset:27840
	s_nop 0
	ds_read_b64_tr_b16 v[90:91], v1 offset:27872
	ds_read_b64_tr_b16 v[84:85], v1 offset:28992
	ds_read_b64_tr_b16 v[92:93], v1 offset:29024
	s_nop 1
	v_mul_f32_e32 v50, v19, v19
	s_waitcnt lgkmcnt(6)
	v_mfma_f32_16x16x32_bf16 v[14:17], v[6:9], v[112:115], v[14:17]
	s_waitcnt lgkmcnt(4)
	v_mfma_f32_16x16x32_bf16 v[10:13], v[10:13], v[112:115], v[78:81]
	s_waitcnt lgkmcnt(1)
	v_mfma_f32_16x16x32_bf16 v[6:9], v[82:85], v[112:115], v[74:77]
	s_nop 0
	v_mov_b32_e32 v78, v33
	v_mov_b32_e32 v79, v29
	v_mul_f32_e32 v80, v24, v24
	v_mul_f32_e32 v81, v25, v25
	v_mov_b32_e32 v74, v31
	v_mov_b32_e32 v75, v27
	v_mov_b32_e32 v76, v32
	v_mov_b32_e32 v77, v28
	v_mul_f32_e32 v82, v22, v22
	v_mul_f32_e32 v83, v23, v23
	v_mul_f32_e32 v74, v74, v74
	v_mul_f32_e32 v75, v75, v75
	v_mul_f32_e32 v78, v78, v78
	v_mul_f32_e32 v79, v79, v79
	v_pk_mov_b32 v[84:85], v[82:83], v[80:81] op_sel:[1,0]
	v_mov_b32_e32 v83, v81
	v_pk_fma_f32 v[64:65], v[64:65], v[64:65], v[74:75]
	v_pk_fma_f32 v[74:75], v[76:77], v[76:77], v[78:79]
	v_add_f32_e32 v76, v84, v82
	v_add_f32_e32 v77, v85, v83
	v_add_f32_e32 v64, v64, v74
	v_add_f32_e32 v65, v65, v75
	v_mul_f32_e32 v59, v14, v14
	v_mul_f32_e32 v62, v15, v15
	v_pk_add_f32 v[74:75], v[76:77], v[76:77] op_sel:[0,1] op_sel_hi:[1,0]
	v_pk_add_f32 v[64:65], v[64:65], v[64:65] op_sel:[0,1] op_sel_hi:[1,0]
	v_pk_fma_f32 v[80:81], v[18:19], v[18:19], v[50:51] op_sel_hi:[1,1,0]
	v_mov_b32_e32 v75, v62
	v_mov_b32_e32 v65, v59
	v_mul_f32_e32 v50, v21, v21
	s_waitcnt lgkmcnt(0)
	v_mfma_f32_16x16x32_bf16 v[2:5], v[90:93], v[112:115], v[2:5]
	v_mul_f32_e32 v73, v16, v16
	v_mul_f32_e32 v86, v17, v17
	v_add_f32_e32 v64, v64, v74
	v_add_f32_e32 v65, v65, v75
	v_pk_fma_f32 v[74:75], v[20:21], v[20:21], v[50:51] op_sel_hi:[1,1,0]
	v_mov_b32_e32 v81, v73
	v_mov_b32_e32 v75, v86
	v_add_f32_e32 v74, v80, v74
	v_add_f32_e32 v75, v81, v75
	s_nop 0
	v_mul_f32_e32 v50, v2, v2
	v_add_f32_e32 v64, v64, v74
	v_add_f32_e32 v65, v65, v75
	v_mul_f32_e32 v74, v12, v12
	v_mul_f32_e32 v75, v13, v13
	v_pk_add_f32 v[80:81], v[64:65], v[64:65] op_sel:[0,1] op_sel_hi:[1,0]
	v_mul_f32_e32 v76, v10, v10
	v_mul_f32_e32 v77, v11, v11
	v_mov_b32_e32 v81, v50
	v_lshlrev_b32_e32 v50, 1, v52
	v_pk_mov_b32 v[78:79], v[76:77], v[74:75] op_sel:[1,0]
	v_mov_b32_e32 v77, v75
	v_add_f32_e32 v78, v78, v76
	v_add_f32_e32 v79, v79, v77
	v_mul_f32_e32 v59, v3, v3
	v_pk_add_f32 v[78:79], v[78:79], v[78:79] op_sel:[0,1] op_sel_hi:[1,0]
	v_mul_f32_e32 v62, v7, v7
	v_mov_b32_e32 v79, v59
	v_mul_f32_e32 v73, v4, v4
	v_add_f32_e32 v78, v80, v78
	v_add_f32_e32 v79, v81, v79
	v_pk_fma_f32 v[80:81], v[6:7], v[6:7], v[62:63] op_sel_hi:[1,1,0]
	v_mul_f32_e32 v62, v9, v9
	v_mul_f32_e32 v86, v5, v5
	v_mov_b32_e32 v81, v73
	v_pk_fma_f32 v[84:85], v[8:9], v[8:9], v[62:63] op_sel_hi:[1,1,0]
	v_and_b32_e32 v73, 64, v139
	v_mov_b32_e32 v85, v86
	v_xor_b32_e32 v62, 16, v139
	v_add_u32_e32 v73, 64, v73
	v_add_f32_e32 v80, v80, v84
	v_add_f32_e32 v81, v81, v85
	v_cmp_lt_i32_e32 vcc, v62, v73
	v_add_f32_e32 v78, v78, v80
	v_add_f32_e32 v79, v79, v81
	v_lshl_add_u64 v[60:61], s[8:9], 0, v[60:61]
	v_cndmask_b32_e32 v62, v139, v62, vcc
	v_add_f32_e32 v59, v78, v79
	v_lshlrev_b32_e32 v62, 2, v62
	ds_bpermute_b32 v62, v62, v59
	v_lshl_add_u64 v[60:61], v[60:61], 0, s[16:17]
	v_lshl_add_u64 v[60:61], v[60:61], 0, v[50:51]
	s_waitcnt lgkmcnt(0)
; DEV unsigned cvtpk(float lo, float hi) { typedef float f2 __attribute__((ext_vector_type(2))); typedef __bf16 b2 __attribute__((ext_vector_type(2))); f2 v = {lo, hi}; b2 b = __builtin_convertvector(v, b2); return __builtin_bit_cast(unsigned, b); }
; template <class Tp> DEV Tp* wsp(const Frame& F, size_t off) { return (Tp*)(F.ws + off); }
; DEV void hgrn_c_unit(Frame& F, int c, int hp) {
;     ...
;     ss += __shfl_xor(ss, 16); ss += __shfl_xor(ss, 32);
;     const float rr = 1.0f / sqrtf(ss * (1.f / 128.f) + EPS);
;     const bf16* HG = wsp<bf16>(F, WS_HG) + row * 512 + h * 128 + 4 * q4; bf16* OB = wsp<bf16>(F, WS_OB) + row * 512 + h * 128 + 4 * q4; const float* gn = ((const float*)F.A.in[20]) + 4 * q4;
; #pragma unroll
;     for (int vt = 0; vt < 8; ++vt) { const v2u gw_ = *(const v2u*)(HG + 16 * vt); const f32x4 g4 = *(const f32x4*)(gn + 16 * vt);
;         v2u wv; wv.x = cvtpk(acc[vt][0] * rr * g4[0] * bflo(gw_.x), acc[vt][1] * rr * g4[1] * bfhi(gw_.x)); wv.y = cvtpk(acc[vt][2] * rr * g4[2] * bflo(gw_.y), acc[vt][3] * rr * g4[3] * bfhi(gw_.y));
;         *(v2u*)(OB + 16 * vt) = wv; }
	v_add_f32_e32 v59, v59, v62
	v_xor_b32_e32 v62, 32, v139
	v_cmp_lt_i32_e32 vcc, v62, v73
	s_waitcnt vmcnt(0)
	v_cndmask_b32_e32 v62, v139, v62, vcc
	v_lshlrev_b32_e32 v62, 2, v62
	ds_bpermute_b32 v62, v62, v59
	s_waitcnt lgkmcnt(0)
	v_add_f32_e32 v59, v59, v62
	v_fmamk_f32 v59, v59, 0x3c000000, v71
	v_mul_f32_e32 v62, 0x4f800000, v59
	v_cmp_gt_f32_e32 vcc, s24, v59
	s_nop 1
	v_cndmask_b32_e32 v59, v59, v62, vcc
	v_sqrt_f32_e32 v62, v59
	s_nop 0
	v_add_u32_e32 v73, -1, v62
	v_fma_f32 v78, -v73, v62, v59
	v_cmp_ge_f32_e64 s[4:5], 0, v78
	v_add_u32_e32 v78, 1, v62
	s_nop 0
	v_cndmask_b32_e64 v73, v62, v73, s[4:5]
	v_fma_f32 v62, -v78, v62, v59
	v_cmp_lt_f32_e64 s[4:5], 0, v62
	s_nop 1
	v_cndmask_b32_e64 v62, v73, v78, s[4:5]
	v_mul_f32_e32 v73, 0x37800000, v62
	v_cndmask_b32_e32 v62, v62, v73, vcc
	v_cmp_class_f32_e32 vcc, v59, v72
	s_nop 1
	v_cndmask_b32_e32 v59, v62, v59, vcc
	v_div_scale_f32 v62, s[4:5], v59, v59, 1.0
	v_rcp_f32_e32 v73, v62
	s_mov_b64 s[4:5], -1
	v_fma_f32 v78, -v62, v73, 1.0
	v_fmac_f32_e32 v73, v78, v73
	v_div_scale_f32 v78, vcc, 1.0, v59, 1.0
	v_mul_f32_e32 v79, v78, v73
	v_fma_f32 v80, -v62, v79, v78
	v_fmac_f32_e32 v79, v80, v73
	v_fma_f32 v62, -v62, v79, v78
	v_div_fmas_f32 v62, v62, v73, v79
	v_div_fixup_f32 v62, v62, v59, 1.0
	v_mul_f32_e32 v30, v30, v62
	v_mul_f32_e32 v31, v31, v62
	v_mul_f32_e32 v32, v32, v62
	v_mul_f32_e32 v33, v33, v62
	v_lshlrev_b32_e32 v140, 16, v116
	v_and_b32_e32 v141, 0xffff0000, v116
	v_lshlrev_b32_e32 v142, 16, v117
	v_and_b32_e32 v143, 0xffff0000, v117
	v_mul_f32_e32 v30, v160, v30
	v_mul_f32_e32 v31, v161, v31
	v_mul_f32_e32 v32, v162, v32
	v_mul_f32_e32 v33, v163, v33
	v_mul_f32_e32 v30, v30, v140
	v_mul_f32_e32 v31, v31, v141
	v_mul_f32_e32 v32, v32, v142
	v_mul_f32_e32 v33, v33, v143
	v_cvt_pk_bf16_f32 v30, v30, v31
	v_cvt_pk_bf16_f32 v31, v32, v33
	global_store_dwordx2 v[60:61], v[30:31], off
	v_mul_f32_e32 v26, v26, v62
	v_mul_f32_e32 v27, v27, v62
	v_mul_f32_e32 v28, v28, v62
	v_mul_f32_e32 v29, v29, v62
	v_lshlrev_b32_e32 v144, 16, v118
	v_and_b32_e32 v145, 0xffff0000, v118
	v_lshlrev_b32_e32 v146, 16, v119
	v_and_b32_e32 v147, 0xffff0000, v119
	v_mul_f32_e32 v26, v164, v26
	v_mul_f32_e32 v27, v165, v27
	v_mul_f32_e32 v28, v166, v28
	v_mul_f32_e32 v29, v167, v29
	v_mul_f32_e32 v26, v26, v144
	v_mul_f32_e32 v27, v27, v145
	v_mul_f32_e32 v28, v28, v146
	v_mul_f32_e32 v29, v29, v147
	v_cvt_pk_bf16_f32 v26, v26, v27
	v_cvt_pk_bf16_f32 v27, v28, v29
	global_store_dwordx2 v[60:61], v[26:27], off offset:32
	v_mul_f32_e32 v22, v22, v62
	v_mul_f32_e32 v23, v23, v62
	v_mul_f32_e32 v24, v24, v62
	v_mul_f32_e32 v25, v25, v62
	v_lshlrev_b32_e32 v140, 16, v120
	v_and_b32_e32 v141, 0xffff0000, v120
	v_lshlrev_b32_e32 v142, 16, v121
	v_and_b32_e32 v143, 0xffff0000, v121
	v_mul_f32_e32 v22, v168, v22
	v_mul_f32_e32 v23, v169, v23
	v_mul_f32_e32 v24, v170, v24
	v_mul_f32_e32 v25, v171, v25
	v_mul_f32_e32 v22, v22, v140
	v_mul_f32_e32 v23, v23, v141
	v_mul_f32_e32 v24, v24, v142
	v_mul_f32_e32 v25, v25, v143
	v_cvt_pk_bf16_f32 v22, v22, v23
	v_cvt_pk_bf16_f32 v23, v24, v25
	global_store_dwordx2 v[60:61], v[22:23], off offset:64
	v_mul_f32_e32 v18, v18, v62
	v_mul_f32_e32 v19, v19, v62
	v_mul_f32_e32 v20, v20, v62
	v_mul_f32_e32 v21, v21, v62
	v_lshlrev_b32_e32 v144, 16, v122
	v_and_b32_e32 v145, 0xffff0000, v122
	v_lshlrev_b32_e32 v146, 16, v123
	v_and_b32_e32 v147, 0xffff0000, v123
	v_mul_f32_e32 v18, v172, v18
	v_mul_f32_e32 v19, v173, v19
	v_mul_f32_e32 v20, v174, v20
	v_mul_f32_e32 v21, v175, v21
	v_mul_f32_e32 v18, v18, v144
	v_mul_f32_e32 v19, v19, v145
	v_mul_f32_e32 v20, v20, v146
	v_mul_f32_e32 v21, v21, v147
	v_cvt_pk_bf16_f32 v18, v18, v19
	v_cvt_pk_bf16_f32 v19, v20, v21
	global_store_dwordx2 v[60:61], v[18:19], off offset:96
	v_mul_f32_e32 v14, v14, v62
	v_mul_f32_e32 v15, v15, v62
	v_mul_f32_e32 v16, v16, v62
	v_mul_f32_e32 v17, v17, v62
	v_lshlrev_b32_e32 v140, 16, v124
	v_and_b32_e32 v141, 0xffff0000, v124
	v_lshlrev_b32_e32 v142, 16, v125
	v_and_b32_e32 v143, 0xffff0000, v125
	v_mul_f32_e32 v14, v176, v14
	v_mul_f32_e32 v15, v177, v15
	v_mul_f32_e32 v16, v178, v16
	v_mul_f32_e32 v17, v179, v17
	v_mul_f32_e32 v14, v14, v140
	v_mul_f32_e32 v15, v15, v141
	v_mul_f32_e32 v16, v16, v142
	v_mul_f32_e32 v17, v17, v143
	v_cvt_pk_bf16_f32 v14, v14, v15
	v_cvt_pk_bf16_f32 v15, v16, v17
	global_store_dwordx2 v[60:61], v[14:15], off offset:128
	v_mul_f32_e32 v10, v10, v62
	v_mul_f32_e32 v11, v11, v62
	v_mul_f32_e32 v12, v12, v62
	v_mul_f32_e32 v13, v13, v62
	v_lshlrev_b32_e32 v144, 16, v126
	v_and_b32_e32 v145, 0xffff0000, v126
	v_lshlrev_b32_e32 v146, 16, v127
	v_and_b32_e32 v147, 0xffff0000, v127
	v_mul_f32_e32 v10, v180, v10
	v_mul_f32_e32 v11, v181, v11
	v_mul_f32_e32 v12, v182, v12
	v_mul_f32_e32 v13, v183, v13
	v_mul_f32_e32 v10, v10, v144
	v_mul_f32_e32 v11, v11, v145
	v_mul_f32_e32 v12, v12, v146
	v_mul_f32_e32 v13, v13, v147
	v_cvt_pk_bf16_f32 v10, v10, v11
	v_cvt_pk_bf16_f32 v11, v12, v13
	global_store_dwordx2 v[60:61], v[10:11], off offset:160
	v_mul_f32_e32 v6, v6, v62
	v_mul_f32_e32 v7, v7, v62
	v_mul_f32_e32 v8, v8, v62
	v_mul_f32_e32 v9, v9, v62
	v_lshlrev_b32_e32 v140, 16, v128
	v_and_b32_e32 v141, 0xffff0000, v128
	v_lshlrev_b32_e32 v142, 16, v129
	v_and_b32_e32 v143, 0xffff0000, v129
	v_mul_f32_e32 v6, v184, v6
	v_mul_f32_e32 v7, v185, v7
	v_mul_f32_e32 v8, v186, v8
	v_mul_f32_e32 v9, v187, v9
	v_mul_f32_e32 v6, v6, v140
	v_mul_f32_e32 v7, v7, v141
	v_mul_f32_e32 v8, v8, v142
	v_mul_f32_e32 v9, v9, v143
	v_cvt_pk_bf16_f32 v6, v6, v7
	v_cvt_pk_bf16_f32 v7, v8, v9
	global_store_dwordx2 v[60:61], v[6:7], off offset:192
	v_mul_f32_e32 v2, v2, v62
	v_mul_f32_e32 v3, v3, v62
	v_mul_f32_e32 v4, v4, v62
	v_mul_f32_e32 v5, v5, v62
	v_lshlrev_b32_e32 v144, 16, v130
	v_and_b32_e32 v145, 0xffff0000, v130
	v_lshlrev_b32_e32 v146, 16, v131
	v_and_b32_e32 v147, 0xffff0000, v131
	v_mul_f32_e32 v2, v188, v2
	v_mul_f32_e32 v3, v189, v3
	v_mul_f32_e32 v4, v190, v4
	v_mul_f32_e32 v5, v191, v5
	v_mul_f32_e32 v2, v2, v144
	v_mul_f32_e32 v3, v3, v145
	v_mul_f32_e32 v4, v4, v146
	v_mul_f32_e32 v5, v5, v147
	v_cvt_pk_bf16_f32 v2, v2, v3
	v_cvt_pk_bf16_f32 v3, v4, v5
	global_store_dwordx2 v[60:61], v[2:3], off offset:224
	s_barrier
